# all four big K-loops as two per-wave-group copies: one barrier per load+MFMA pair, stagger barriers removed
# baseline (speedup 1.0000x reference)
.LBB0_200:
	s_ashr_i32 s47, s31, 8
	s_cmp_eq_u32 s47, 1
	s_cselect_b64 s[40:41], -1, 0
	s_cmp_lg_u32 s47, 1
	s_cbranch_scc1 .LBB0_202
	s_nop 0

.LBB0_209:
	s_and_b32 s46, s46, 7
	s_or_b32 s66, s46, s4
	s_and_b64 s[46:47], s[48:49], exec
	s_cselect_b32 s46, s66, s51
	s_ashr_i32 s47, s46, 31
	s_lshl_b64 s[46:47], s[46:47], 19
	s_add_u32 s46, s22, s46
	v_mov_b32_e32 v125, 0
	s_addc_u32 s47, s23, s47
	s_andn2_b64 vcc, exec, s[42:43]
	v_mov_b32_e32 v124, v125
	v_mov_b32_e32 v123, v125
	v_mov_b32_e32 v122, v125
	v_mov_b32_e32 v129, v125
	v_mov_b32_e32 v128, v125
	v_mov_b32_e32 v127, v125
	v_mov_b32_e32 v126, v125
	v_mov_b32_e32 v113, v125
	v_mov_b32_e32 v112, v125
	v_mov_b32_e32 v111, v125
	v_mov_b32_e32 v110, v125
	v_mov_b32_e32 v109, v125
	v_mov_b32_e32 v108, v125
	v_mov_b32_e32 v107, v125
	v_mov_b32_e32 v106, v125
	v_mov_b32_e32 v97, v125
	v_mov_b32_e32 v96, v125
	v_mov_b32_e32 v95, v125
	v_mov_b32_e32 v94, v125
	v_mov_b32_e32 v93, v125
	v_mov_b32_e32 v92, v125
	v_mov_b32_e32 v91, v125
	v_mov_b32_e32 v90, v125
	v_mov_b32_e32 v81, v125
	v_mov_b32_e32 v80, v125
	v_mov_b32_e32 v79, v125
	v_mov_b32_e32 v78, v125
	v_mov_b32_e32 v77, v125
	v_mov_b32_e32 v76, v125
	v_mov_b32_e32 v75, v125
	v_mov_b32_e32 v74, v125
	v_mov_b32_e32 v121, v125
	v_mov_b32_e32 v120, v125
	v_mov_b32_e32 v119, v125
	v_mov_b32_e32 v118, v125
	v_mov_b32_e32 v117, v125
	v_mov_b32_e32 v116, v125
	v_mov_b32_e32 v115, v125
	v_mov_b32_e32 v114, v125
	v_mov_b32_e32 v105, v125
	v_mov_b32_e32 v104, v125
	v_mov_b32_e32 v103, v125
	v_mov_b32_e32 v102, v125
	v_mov_b32_e32 v101, v125
	v_mov_b32_e32 v100, v125
	v_mov_b32_e32 v99, v125
	v_mov_b32_e32 v98, v125
	v_mov_b32_e32 v89, v125
	v_mov_b32_e32 v88, v125
	v_mov_b32_e32 v87, v125
	v_mov_b32_e32 v86, v125
	v_mov_b32_e32 v85, v125
	v_mov_b32_e32 v84, v125
	v_mov_b32_e32 v83, v125
	v_mov_b32_e32 v82, v125
	v_mov_b32_e32 v73, v125
	v_mov_b32_e32 v72, v125
	v_mov_b32_e32 v71, v125
	v_mov_b32_e32 v70, v125
	v_mov_b32_e32 v69, v125
	v_mov_b32_e32 v68, v125
	v_mov_b32_e32 v67, v125
	v_mov_b32_e32 v66, v125
	v_mov_b32_e32 v65, v125
	v_mov_b32_e32 v64, v125
	v_mov_b32_e32 v63, v125
	v_mov_b32_e32 v62, v125
	v_mov_b32_e32 v61, v125
	v_mov_b32_e32 v60, v125
	v_mov_b32_e32 v59, v125
	v_mov_b32_e32 v58, v125
	v_mov_b32_e32 v49, v125
	v_mov_b32_e32 v48, v125
	v_mov_b32_e32 v47, v125
	v_mov_b32_e32 v46, v125
	v_mov_b32_e32 v45, v125
	v_mov_b32_e32 v44, v125
	v_mov_b32_e32 v43, v125
	v_mov_b32_e32 v42, v125
	v_mov_b32_e32 v33, v125
	v_mov_b32_e32 v32, v125
	v_mov_b32_e32 v31, v125
	v_mov_b32_e32 v30, v125
	v_mov_b32_e32 v29, v125
	v_mov_b32_e32 v28, v125
	v_mov_b32_e32 v27, v125
	v_mov_b32_e32 v26, v125
	v_mov_b32_e32 v17, v125
	v_mov_b32_e32 v16, v125
	v_mov_b32_e32 v15, v125
	v_mov_b32_e32 v14, v125
	v_mov_b32_e32 v13, v125
	v_mov_b32_e32 v12, v125
	v_mov_b32_e32 v11, v125
	v_mov_b32_e32 v10, v125
	v_mov_b32_e32 v57, v125
	v_mov_b32_e32 v56, v125
	v_mov_b32_e32 v55, v125
	v_mov_b32_e32 v54, v125
	v_mov_b32_e32 v53, v125
	v_mov_b32_e32 v52, v125
	v_mov_b32_e32 v51, v125
	v_mov_b32_e32 v50, v125
	v_mov_b32_e32 v41, v125
	v_mov_b32_e32 v40, v125
	v_mov_b32_e32 v39, v125
	v_mov_b32_e32 v38, v125
	v_mov_b32_e32 v37, v125
	v_mov_b32_e32 v36, v125
	v_mov_b32_e32 v35, v125
	v_mov_b32_e32 v34, v125
	v_mov_b32_e32 v25, v125
	v_mov_b32_e32 v24, v125
	v_mov_b32_e32 v23, v125
	v_mov_b32_e32 v22, v125
	v_mov_b32_e32 v21, v125
	v_mov_b32_e32 v20, v125
	v_mov_b32_e32 v19, v125
	v_mov_b32_e32 v18, v125
	v_mov_b32_e32 v9, v125
	v_mov_b32_e32 v8, v125
	v_mov_b32_e32 v7, v125
	v_mov_b32_e32 v6, v125
	v_mov_b32_e32 v5, v125
	v_mov_b32_e32 v4, v125
	v_mov_b32_e32 v3, v125
	v_mov_b32_e32 v2, v125
	s_cbranch_vccnz .LBB0_213
	s_and_b64 s[72:73], s[48:49], exec
	s_cselect_b32 s51, s47, s57
	s_cselect_b32 s55, s46, s56
	s_add_u32 s56, s56, 0x80
	s_addc_u32 s57, s57, 0
	s_add_u32 s67, s58, 0x100
	v_mov_b32_e32 v2, 0
	s_addc_u32 s72, s59, 0
	s_mov_b32 s58, 0
	v_mov_b32_e32 v3, v2
	v_mov_b32_e32 v4, v2
	v_mov_b32_e32 v5, v2
	v_mov_b32_e32 v6, v2
	v_mov_b32_e32 v7, v2
	v_mov_b32_e32 v8, v2
	v_mov_b32_e32 v9, v2
	v_mov_b32_e32 v18, v2
	v_mov_b32_e32 v19, v2
	v_mov_b32_e32 v20, v2
	v_mov_b32_e32 v21, v2
	v_mov_b32_e32 v22, v2
	v_mov_b32_e32 v23, v2
	v_mov_b32_e32 v24, v2
	v_mov_b32_e32 v25, v2
	v_mov_b32_e32 v34, v2
	v_mov_b32_e32 v35, v2
	v_mov_b32_e32 v36, v2
	v_mov_b32_e32 v37, v2
	v_mov_b32_e32 v38, v2
	v_mov_b32_e32 v39, v2
	v_mov_b32_e32 v40, v2
	v_mov_b32_e32 v41, v2
	v_mov_b32_e32 v50, v2
	v_mov_b32_e32 v51, v2
	v_mov_b32_e32 v52, v2
	v_mov_b32_e32 v53, v2
	v_mov_b32_e32 v54, v2
	v_mov_b32_e32 v55, v2
	v_mov_b32_e32 v56, v2
	v_mov_b32_e32 v57, v2
	v_mov_b32_e32 v10, v2
	v_mov_b32_e32 v11, v2
	v_mov_b32_e32 v12, v2
	v_mov_b32_e32 v13, v2
	v_mov_b32_e32 v14, v2
	v_mov_b32_e32 v15, v2
	v_mov_b32_e32 v16, v2
	v_mov_b32_e32 v17, v2
	v_mov_b32_e32 v26, v2
	v_mov_b32_e32 v27, v2
	v_mov_b32_e32 v28, v2
	v_mov_b32_e32 v29, v2
	v_mov_b32_e32 v30, v2
	v_mov_b32_e32 v31, v2
	v_mov_b32_e32 v32, v2
	v_mov_b32_e32 v33, v2
	v_mov_b32_e32 v42, v2
	v_mov_b32_e32 v43, v2
	v_mov_b32_e32 v44, v2
	v_mov_b32_e32 v45, v2
	v_mov_b32_e32 v46, v2
	v_mov_b32_e32 v47, v2
	v_mov_b32_e32 v48, v2
	v_mov_b32_e32 v49, v2
	v_mov_b32_e32 v58, v2
	v_mov_b32_e32 v59, v2
	v_mov_b32_e32 v60, v2
	v_mov_b32_e32 v61, v2
	v_mov_b32_e32 v62, v2
	v_mov_b32_e32 v63, v2
	v_mov_b32_e32 v64, v2
	v_mov_b32_e32 v65, v2
	v_mov_b32_e32 v66, v2
	v_mov_b32_e32 v67, v2
	v_mov_b32_e32 v68, v2
	v_mov_b32_e32 v69, v2
	v_mov_b32_e32 v70, v2
	v_mov_b32_e32 v71, v2
	v_mov_b32_e32 v72, v2
	v_mov_b32_e32 v73, v2
	v_mov_b32_e32 v82, v2
	v_mov_b32_e32 v83, v2
	v_mov_b32_e32 v84, v2
	v_mov_b32_e32 v85, v2
	v_mov_b32_e32 v86, v2
	v_mov_b32_e32 v87, v2
	v_mov_b32_e32 v88, v2
	v_mov_b32_e32 v89, v2
	v_mov_b32_e32 v98, v2
	v_mov_b32_e32 v99, v2
	v_mov_b32_e32 v100, v2
	v_mov_b32_e32 v101, v2
	v_mov_b32_e32 v102, v2
	v_mov_b32_e32 v103, v2
	v_mov_b32_e32 v104, v2
	v_mov_b32_e32 v105, v2
	v_mov_b32_e32 v114, v2
	v_mov_b32_e32 v115, v2
	v_mov_b32_e32 v116, v2
	v_mov_b32_e32 v117, v2
	v_mov_b32_e32 v118, v2
	v_mov_b32_e32 v119, v2
	v_mov_b32_e32 v120, v2
	v_mov_b32_e32 v121, v2
	v_mov_b32_e32 v74, v2
	v_mov_b32_e32 v75, v2
	v_mov_b32_e32 v76, v2
	v_mov_b32_e32 v77, v2
	v_mov_b32_e32 v78, v2
	v_mov_b32_e32 v79, v2
	v_mov_b32_e32 v80, v2
	v_mov_b32_e32 v81, v2
	v_mov_b32_e32 v90, v2
	v_mov_b32_e32 v91, v2
	v_mov_b32_e32 v92, v2
	v_mov_b32_e32 v93, v2
	v_mov_b32_e32 v94, v2
	v_mov_b32_e32 v95, v2
	v_mov_b32_e32 v96, v2
	v_mov_b32_e32 v97, v2
	v_mov_b32_e32 v106, v2
	v_mov_b32_e32 v107, v2
	v_mov_b32_e32 v108, v2
	v_mov_b32_e32 v109, v2
	v_mov_b32_e32 v110, v2
	v_mov_b32_e32 v111, v2
	v_mov_b32_e32 v112, v2
	v_mov_b32_e32 v113, v2
	v_mov_b32_e32 v126, v2
	v_mov_b32_e32 v127, v2
	v_mov_b32_e32 v128, v2
	v_mov_b32_e32 v129, v2
	v_mov_b32_e32 v122, v2
	v_mov_b32_e32 v123, v2
	v_mov_b32_e32 v124, v2
	v_mov_b32_e32 v125, v2
	s_bitcmp1_b32 s38, 0
	s_cbranch_scc0 .Lmy_q211
.LBB0_211:
	s_add_i32 s73, s58, 2
	s_add_u32 s74, s56, 0x80
	s_addc_u32 s59, s57, 0
	s_add_i32 s78, 0, 0x10000
	s_cmp_eq_u32 s63, s58
	s_cselect_b32 s59, s51, s59
	s_cselect_b32 s58, s55, s74
	v_add_u32_e32 v0, s78, v146
	s_cselect_b32 s75, s45, s72
	s_cselect_b32 s74, s44, s67
	s_add_i32 s80, 0, 0x14000
	ds_read_b128 v[148:151], v0
	ds_read_b128 v[152:155], v0 offset:1024
	ds_read_b128 v[156:159], v0 offset:2048
	ds_read_b128 v[160:163], v0 offset:3072
	v_add_u32_e32 v0, s80, v146
	ds_read_b128 v[164:167], v0
	ds_read_b128 v[168:171], v0 offset:1024
	ds_read_b128 v[172:175], v0 offset:2048
	ds_read_b128 v[176:179], v0 offset:3072
	s_mov_b32 m0, s31
	v_lshl_add_u64 v[142:143], s[56:57], 0, v[136:137]
	global_load_lds_dwordx4 v[142:143], off
	v_lshl_add_u64 v[142:143], s[56:57], 0, v[132:133]
	s_mov_b32 m0, s53
	s_nop 0
	global_load_lds_dwordx4 v[142:143], off
	v_lshl_add_u64 v[142:143], s[56:57], 0, v[138:139]
	s_add_i32 m0, s27, 0xc000
	s_nop 0
	global_load_lds_dwordx4 v[142:143], off
	v_lshl_add_u64 v[142:143], s[56:57], 0, v[140:141]
	s_add_i32 m0, s27, 0xe000
	s_nop 0
	global_load_lds_dwordx4 v[142:143], off
	ds_read_b128 v[180:183], v147
	ds_read_b128 v[184:187], v147 offset:1024
	ds_read_b128 v[200:203], v147 offset:2048
	ds_read_b128 v[204:207], v147 offset:3072
	ds_read_b128 v[208:211], v147 offset:4096
	ds_read_b128 v[212:215], v147 offset:5120
	ds_read_b128 v[216:219], v147 offset:6144
	ds_read_b128 v[220:223], v147 offset:7168
	s_waitcnt vmcnt(8)
	s_waitcnt lgkmcnt(0)
	s_barrier
	s_setprio 1
	s_waitcnt lgkmcnt(0)
	v_mfma_f32_16x16x32_bf16 v[122:125], v[148:151], v[180:183], v[122:125]
	v_mfma_f32_16x16x32_bf16 v[126:129], v[156:159], v[180:183], v[126:129]
	v_mfma_f32_16x16x32_bf16 v[110:113], v[148:151], v[200:203], v[110:113]
	v_mfma_f32_16x16x32_bf16 v[106:109], v[156:159], v[200:203], v[106:109]
	v_mfma_f32_16x16x32_bf16 v[94:97], v[148:151], v[208:211], v[94:97]
	v_mfma_f32_16x16x32_bf16 v[90:93], v[156:159], v[208:211], v[90:93]
	v_mfma_f32_16x16x32_bf16 v[78:81], v[148:151], v[216:219], v[78:81]
	v_mfma_f32_16x16x32_bf16 v[74:77], v[156:159], v[216:219], v[74:77]
	v_mfma_f32_16x16x32_bf16 v[122:125], v[152:155], v[184:187], v[122:125]
	v_mfma_f32_16x16x32_bf16 v[126:129], v[160:163], v[184:187], v[126:129]
	v_mfma_f32_16x16x32_bf16 v[110:113], v[152:155], v[204:207], v[110:113]
	v_mfma_f32_16x16x32_bf16 v[106:109], v[160:163], v[204:207], v[106:109]
	v_mfma_f32_16x16x32_bf16 v[94:97], v[152:155], v[212:215], v[94:97]
	v_mfma_f32_16x16x32_bf16 v[90:93], v[160:163], v[212:215], v[90:93]
	v_mfma_f32_16x16x32_bf16 v[78:81], v[152:155], v[220:223], v[78:81]
	v_mfma_f32_16x16x32_bf16 v[74:77], v[160:163], v[220:223], v[74:77]
	s_setprio 0
	s_setprio 1
	v_mfma_f32_16x16x32_bf16 v[118:121], v[164:167], v[180:183], v[118:121]
	v_mfma_f32_16x16x32_bf16 v[114:117], v[172:175], v[180:183], v[114:117]
	v_mfma_f32_16x16x32_bf16 v[102:105], v[164:167], v[200:203], v[102:105]
	v_mfma_f32_16x16x32_bf16 v[98:101], v[172:175], v[200:203], v[98:101]
	v_mfma_f32_16x16x32_bf16 v[86:89], v[164:167], v[208:211], v[86:89]
	v_mfma_f32_16x16x32_bf16 v[82:85], v[172:175], v[208:211], v[82:85]
	v_mfma_f32_16x16x32_bf16 v[70:73], v[164:167], v[216:219], v[70:73]
	v_mfma_f32_16x16x32_bf16 v[66:69], v[172:175], v[216:219], v[66:69]
	v_mfma_f32_16x16x32_bf16 v[118:121], v[168:171], v[184:187], v[118:121]
	v_mfma_f32_16x16x32_bf16 v[114:117], v[176:179], v[184:187], v[114:117]
	v_mfma_f32_16x16x32_bf16 v[102:105], v[168:171], v[204:207], v[102:105]
	v_mfma_f32_16x16x32_bf16 v[98:101], v[176:179], v[204:207], v[98:101]
	v_mfma_f32_16x16x32_bf16 v[86:89], v[168:171], v[212:215], v[86:89]
	v_mfma_f32_16x16x32_bf16 v[82:85], v[176:179], v[212:215], v[82:85]
	v_mfma_f32_16x16x32_bf16 v[70:73], v[168:171], v[220:223], v[70:73]
	v_mfma_f32_16x16x32_bf16 v[66:69], v[176:179], v[220:223], v[66:69]
	s_setprio 0
	s_add_i32 s78, s78, s5
	v_lshl_add_u64 v[142:143], s[74:75], 0, v[134:135]
	s_mov_b32 m0, s78
	ds_read_b128 v[180:183], v147 offset:16384
	ds_read_b128 v[184:187], v147 offset:17408
	ds_read_b128 v[200:203], v147 offset:18432
	ds_read_b128 v[204:207], v147 offset:19456
	ds_read_b128 v[208:211], v147 offset:20480
	ds_read_b128 v[212:215], v147 offset:21504
	ds_read_b128 v[216:219], v147 offset:22528
	ds_read_b128 v[220:223], v147 offset:23552
	global_load_lds_dwordx4 v[142:143], off
	s_add_i32 m0, s78, 0x2000
	v_lshl_add_u64 v[188:189], s[74:75], 0, v[130:131]
	s_add_u32 s74, s74, s6
	s_addc_u32 s75, s75, s7
	s_add_i32 s78, s80, s5
	global_load_lds_dwordx4 v[188:189], off
	v_lshl_add_u64 v[224:225], s[74:75], 0, v[134:135]
	s_mov_b32 m0, s78
	v_lshl_add_u64 v[226:227], s[74:75], 0, v[130:131]
	global_load_lds_dwordx4 v[224:225], off
	s_add_i32 m0, s78, 0x2000
	v_lshl_add_u64 v[228:229], s[58:59], 0, v[136:137]
	global_load_lds_dwordx4 v[226:227], off
	v_lshl_add_u64 v[230:231], s[58:59], 0, v[132:133]
	s_waitcnt vmcnt(6)
	s_waitcnt lgkmcnt(0)
	s_barrier
	s_setprio 1
	s_waitcnt lgkmcnt(0)
	v_mfma_f32_16x16x32_bf16 v[62:65], v[148:151], v[180:183], v[62:65]
	v_mfma_f32_16x16x32_bf16 v[58:61], v[156:159], v[180:183], v[58:61]
	v_mfma_f32_16x16x32_bf16 v[46:49], v[148:151], v[200:203], v[46:49]
	v_mfma_f32_16x16x32_bf16 v[42:45], v[156:159], v[200:203], v[42:45]
	v_mfma_f32_16x16x32_bf16 v[30:33], v[148:151], v[208:211], v[30:33]
	v_mfma_f32_16x16x32_bf16 v[26:29], v[156:159], v[208:211], v[26:29]
	v_mfma_f32_16x16x32_bf16 v[14:17], v[148:151], v[216:219], v[14:17]
	v_mfma_f32_16x16x32_bf16 v[10:13], v[156:159], v[216:219], v[10:13]
	v_mfma_f32_16x16x32_bf16 v[62:65], v[152:155], v[184:187], v[62:65]
	v_mfma_f32_16x16x32_bf16 v[58:61], v[160:163], v[184:187], v[58:61]
	v_mfma_f32_16x16x32_bf16 v[46:49], v[152:155], v[204:207], v[46:49]
	v_mfma_f32_16x16x32_bf16 v[42:45], v[160:163], v[204:207], v[42:45]
	v_mfma_f32_16x16x32_bf16 v[30:33], v[152:155], v[212:215], v[30:33]
	v_mfma_f32_16x16x32_bf16 v[26:29], v[160:163], v[212:215], v[26:29]
	v_mfma_f32_16x16x32_bf16 v[14:17], v[152:155], v[220:223], v[14:17]
	v_mfma_f32_16x16x32_bf16 v[10:13], v[160:163], v[220:223], v[10:13]
	s_setprio 0
	s_setprio 1
	v_mfma_f32_16x16x32_bf16 v[54:57], v[164:167], v[180:183], v[54:57]
	v_mfma_f32_16x16x32_bf16 v[50:53], v[172:175], v[180:183], v[50:53]
	v_mfma_f32_16x16x32_bf16 v[38:41], v[164:167], v[200:203], v[38:41]
	v_mfma_f32_16x16x32_bf16 v[34:37], v[172:175], v[200:203], v[34:37]
	v_mfma_f32_16x16x32_bf16 v[22:25], v[164:167], v[208:211], v[22:25]
	v_mfma_f32_16x16x32_bf16 v[18:21], v[172:175], v[208:211], v[18:21]
	v_mfma_f32_16x16x32_bf16 v[6:9], v[164:167], v[216:219], v[6:9]
	v_mfma_f32_16x16x32_bf16 v[2:5], v[172:175], v[216:219], v[2:5]
	v_mfma_f32_16x16x32_bf16 v[54:57], v[168:171], v[184:187], v[54:57]
	v_mfma_f32_16x16x32_bf16 v[50:53], v[176:179], v[184:187], v[50:53]
	v_mfma_f32_16x16x32_bf16 v[38:41], v[168:171], v[204:207], v[38:41]
	v_mfma_f32_16x16x32_bf16 v[34:37], v[176:179], v[204:207], v[34:37]
	v_mfma_f32_16x16x32_bf16 v[22:25], v[168:171], v[212:215], v[22:25]
	v_mfma_f32_16x16x32_bf16 v[18:21], v[176:179], v[212:215], v[18:21]
	v_mfma_f32_16x16x32_bf16 v[6:9], v[168:171], v[220:223], v[6:9]
	v_mfma_f32_16x16x32_bf16 v[2:5], v[176:179], v[220:223], v[2:5]
	s_setprio 0
	s_add_i32 s74, 0, 0x18000
	v_add_u32_e32 v0, s74, v146
	s_add_i32 s75, 0, 0x1c000
	ds_read_b128 v[148:151], v0
	ds_read_b128 v[152:155], v0 offset:1024
	ds_read_b128 v[156:159], v0 offset:2048
	ds_read_b128 v[160:163], v0 offset:3072
	v_add_u32_e32 v0, s75, v146
	ds_read_b128 v[164:167], v0
	ds_read_b128 v[168:171], v0 offset:1024
	ds_read_b128 v[172:175], v0 offset:2048
	ds_read_b128 v[176:179], v0 offset:3072
	s_add_u32 s58, s58, s2
	s_addc_u32 s59, s59, s3
	s_mov_b32 m0, s27
	v_lshl_add_u64 v[232:233], s[58:59], 0, v[136:137]
	s_nop 0
	global_load_lds_dwordx4 v[228:229], off
	s_mov_b32 m0, s28
	s_nop 0
	global_load_lds_dwordx4 v[230:231], off
	s_mov_b32 m0, s29
	s_nop 0
	global_load_lds_dwordx4 v[232:233], off
	v_lshl_add_u64 v[232:233], s[58:59], 0, v[132:133]
	s_mov_b32 m0, s30
	s_nop 0
	global_load_lds_dwordx4 v[232:233], off
	ds_read_b128 v[180:183], v147 offset:32768
	ds_read_b128 v[184:187], v147 offset:33792
	ds_read_b128 v[200:203], v147 offset:34816
	ds_read_b128 v[204:207], v147 offset:35840
	ds_read_b128 v[208:211], v147 offset:36864
	ds_read_b128 v[212:215], v147 offset:37888
	ds_read_b128 v[216:219], v147 offset:38912
	ds_read_b128 v[220:223], v147 offset:39936
	s_waitcnt vmcnt(8)
	s_waitcnt lgkmcnt(0)
	s_barrier
	s_setprio 1
	s_waitcnt lgkmcnt(0)
	v_mfma_f32_16x16x32_bf16 v[122:125], v[148:151], v[180:183], v[122:125]
	v_mfma_f32_16x16x32_bf16 v[126:129], v[156:159], v[180:183], v[126:129]
	v_mfma_f32_16x16x32_bf16 v[110:113], v[148:151], v[200:203], v[110:113]
	v_mfma_f32_16x16x32_bf16 v[106:109], v[156:159], v[200:203], v[106:109]
	v_mfma_f32_16x16x32_bf16 v[94:97], v[148:151], v[208:211], v[94:97]
	v_mfma_f32_16x16x32_bf16 v[90:93], v[156:159], v[208:211], v[90:93]
	v_mfma_f32_16x16x32_bf16 v[78:81], v[148:151], v[216:219], v[78:81]
	v_mfma_f32_16x16x32_bf16 v[74:77], v[156:159], v[216:219], v[74:77]
	v_mfma_f32_16x16x32_bf16 v[122:125], v[152:155], v[184:187], v[122:125]
	v_mfma_f32_16x16x32_bf16 v[126:129], v[160:163], v[184:187], v[126:129]
	v_mfma_f32_16x16x32_bf16 v[110:113], v[152:155], v[204:207], v[110:113]
	v_mfma_f32_16x16x32_bf16 v[106:109], v[160:163], v[204:207], v[106:109]
	v_mfma_f32_16x16x32_bf16 v[94:97], v[152:155], v[212:215], v[94:97]
	v_mfma_f32_16x16x32_bf16 v[90:93], v[160:163], v[212:215], v[90:93]
	v_mfma_f32_16x16x32_bf16 v[78:81], v[152:155], v[220:223], v[78:81]
	v_mfma_f32_16x16x32_bf16 v[74:77], v[160:163], v[220:223], v[74:77]
	s_setprio 0
	s_setprio 1
	v_mfma_f32_16x16x32_bf16 v[118:121], v[164:167], v[180:183], v[118:121]
	v_mfma_f32_16x16x32_bf16 v[114:117], v[172:175], v[180:183], v[114:117]
	v_mfma_f32_16x16x32_bf16 v[102:105], v[164:167], v[200:203], v[102:105]
	v_mfma_f32_16x16x32_bf16 v[98:101], v[172:175], v[200:203], v[98:101]
	v_mfma_f32_16x16x32_bf16 v[86:89], v[164:167], v[208:211], v[86:89]
	v_mfma_f32_16x16x32_bf16 v[82:85], v[172:175], v[208:211], v[82:85]
	v_mfma_f32_16x16x32_bf16 v[70:73], v[164:167], v[216:219], v[70:73]
	v_mfma_f32_16x16x32_bf16 v[66:69], v[172:175], v[216:219], v[66:69]
	v_mfma_f32_16x16x32_bf16 v[118:121], v[168:171], v[184:187], v[118:121]
	v_mfma_f32_16x16x32_bf16 v[114:117], v[176:179], v[184:187], v[114:117]
	v_mfma_f32_16x16x32_bf16 v[102:105], v[168:171], v[204:207], v[102:105]
	v_mfma_f32_16x16x32_bf16 v[98:101], v[176:179], v[204:207], v[98:101]
	v_mfma_f32_16x16x32_bf16 v[86:89], v[168:171], v[212:215], v[86:89]
	v_mfma_f32_16x16x32_bf16 v[82:85], v[176:179], v[212:215], v[82:85]
	v_mfma_f32_16x16x32_bf16 v[70:73], v[168:171], v[220:223], v[70:73]
	v_mfma_f32_16x16x32_bf16 v[66:69], v[176:179], v[220:223], v[66:69]
	s_setprio 0
	s_add_i32 s58, s74, s5
	v_lshl_add_u64 v[142:143], v[142:143], 0, s[24:25]
	s_mov_b32 m0, s58
	ds_read_b128 v[180:183], v147 offset:49152
	ds_read_b128 v[184:187], v147 offset:50176
	ds_read_b128 v[200:203], v147 offset:51200
	ds_read_b128 v[204:207], v147 offset:52224
	ds_read_b128 v[208:211], v147 offset:53248
	ds_read_b128 v[212:215], v147 offset:54272
	ds_read_b128 v[216:219], v147 offset:55296
	ds_read_b128 v[220:223], v147 offset:56320
	global_load_lds_dwordx4 v[142:143], off
	v_lshl_add_u64 v[142:143], v[188:189], 0, s[24:25]
	s_add_i32 m0, s58, 0x2000
	s_add_i32 s58, s75, s5
	global_load_lds_dwordx4 v[142:143], off
	v_lshl_add_u64 v[142:143], v[224:225], 0, s[24:25]
	s_mov_b32 m0, s58
	s_nop 0
	global_load_lds_dwordx4 v[142:143], off
	v_lshl_add_u64 v[142:143], v[226:227], 0, s[24:25]
	s_add_i32 m0, s58, 0x2000
	s_nop 0
	global_load_lds_dwordx4 v[142:143], off
	s_waitcnt vmcnt(6)
	s_waitcnt lgkmcnt(0)
	s_barrier
	s_setprio 1
	s_waitcnt lgkmcnt(0)
	v_mfma_f32_16x16x32_bf16 v[62:65], v[148:151], v[180:183], v[62:65]
	v_mfma_f32_16x16x32_bf16 v[58:61], v[156:159], v[180:183], v[58:61]
	v_mfma_f32_16x16x32_bf16 v[46:49], v[148:151], v[200:203], v[46:49]
	v_mfma_f32_16x16x32_bf16 v[42:45], v[156:159], v[200:203], v[42:45]
	v_mfma_f32_16x16x32_bf16 v[30:33], v[148:151], v[208:211], v[30:33]
	v_mfma_f32_16x16x32_bf16 v[26:29], v[156:159], v[208:211], v[26:29]
	v_mfma_f32_16x16x32_bf16 v[14:17], v[148:151], v[216:219], v[14:17]
	v_mfma_f32_16x16x32_bf16 v[10:13], v[156:159], v[216:219], v[10:13]
	v_mfma_f32_16x16x32_bf16 v[62:65], v[152:155], v[184:187], v[62:65]
	v_mfma_f32_16x16x32_bf16 v[58:61], v[160:163], v[184:187], v[58:61]
	v_mfma_f32_16x16x32_bf16 v[46:49], v[152:155], v[204:207], v[46:49]
	v_mfma_f32_16x16x32_bf16 v[42:45], v[160:163], v[204:207], v[42:45]
	v_mfma_f32_16x16x32_bf16 v[30:33], v[152:155], v[212:215], v[30:33]
	v_mfma_f32_16x16x32_bf16 v[26:29], v[160:163], v[212:215], v[26:29]
	v_mfma_f32_16x16x32_bf16 v[14:17], v[152:155], v[220:223], v[14:17]
	v_mfma_f32_16x16x32_bf16 v[10:13], v[160:163], v[220:223], v[10:13]
	s_setprio 0
	s_setprio 1
	v_mfma_f32_16x16x32_bf16 v[54:57], v[164:167], v[180:183], v[54:57]
	v_mfma_f32_16x16x32_bf16 v[50:53], v[172:175], v[180:183], v[50:53]
	v_mfma_f32_16x16x32_bf16 v[38:41], v[164:167], v[200:203], v[38:41]
	v_mfma_f32_16x16x32_bf16 v[34:37], v[172:175], v[200:203], v[34:37]
	v_mfma_f32_16x16x32_bf16 v[22:25], v[164:167], v[208:211], v[22:25]
	v_mfma_f32_16x16x32_bf16 v[18:21], v[172:175], v[208:211], v[18:21]
	v_mfma_f32_16x16x32_bf16 v[6:9], v[164:167], v[216:219], v[6:9]
	v_mfma_f32_16x16x32_bf16 v[2:5], v[172:175], v[216:219], v[2:5]
	v_mfma_f32_16x16x32_bf16 v[54:57], v[168:171], v[184:187], v[54:57]
	v_mfma_f32_16x16x32_bf16 v[50:53], v[176:179], v[184:187], v[50:53]
	v_mfma_f32_16x16x32_bf16 v[38:41], v[168:171], v[204:207], v[38:41]
	v_mfma_f32_16x16x32_bf16 v[34:37], v[176:179], v[204:207], v[34:37]
	v_mfma_f32_16x16x32_bf16 v[22:25], v[168:171], v[212:215], v[22:25]
	v_mfma_f32_16x16x32_bf16 v[18:21], v[176:179], v[212:215], v[18:21]
	v_mfma_f32_16x16x32_bf16 v[6:9], v[168:171], v[220:223], v[6:9]
	v_mfma_f32_16x16x32_bf16 v[2:5], v[176:179], v[220:223], v[2:5]
	s_setprio 0
	s_add_u32 s56, s56, 0x100
	s_addc_u32 s57, s57, 0
	s_add_u32 s67, s67, 0x100
	s_addc_u32 s72, s72, 0
	s_cmp_ge_i32 s73, s60
	s_mov_b32 s58, s73
	s_cbranch_scc0 .LBB0_211
	s_branch .Lmy_post211
.Lmy_q211:
	s_add_i32 s73, s58, 2
	s_add_u32 s74, s56, 0x80
	s_addc_u32 s59, s57, 0
	s_add_i32 s78, 0, 0x10000
	s_cmp_eq_u32 s63, s58
	s_cselect_b32 s59, s51, s59
	s_cselect_b32 s58, s55, s74
	v_add_u32_e32 v0, s78, v146
	s_cselect_b32 s75, s45, s72
	s_cselect_b32 s74, s44, s67
	s_add_i32 s80, 0, 0x14000
	ds_read_b128 v[148:151], v0
	ds_read_b128 v[152:155], v0 offset:1024
	ds_read_b128 v[156:159], v0 offset:2048
	ds_read_b128 v[160:163], v0 offset:3072
	v_add_u32_e32 v0, s80, v146
	ds_read_b128 v[164:167], v0
	ds_read_b128 v[168:171], v0 offset:1024
	ds_read_b128 v[172:175], v0 offset:2048
	ds_read_b128 v[176:179], v0 offset:3072
	s_mov_b32 m0, s31
	v_lshl_add_u64 v[142:143], s[56:57], 0, v[136:137]
	global_load_lds_dwordx4 v[142:143], off
	v_lshl_add_u64 v[142:143], s[56:57], 0, v[132:133]
	s_mov_b32 m0, s53
	s_nop 0
	global_load_lds_dwordx4 v[142:143], off
	v_lshl_add_u64 v[142:143], s[56:57], 0, v[138:139]
	s_add_i32 m0, s27, 0xc000
	s_nop 0
	global_load_lds_dwordx4 v[142:143], off
	v_lshl_add_u64 v[142:143], s[56:57], 0, v[140:141]
	s_add_i32 m0, s27, 0xe000
	s_nop 0
	global_load_lds_dwordx4 v[142:143], off
	ds_read_b128 v[180:183], v147
	ds_read_b128 v[184:187], v147 offset:1024
	ds_read_b128 v[200:203], v147 offset:2048
	ds_read_b128 v[204:207], v147 offset:3072
	ds_read_b128 v[208:211], v147 offset:4096
	ds_read_b128 v[212:215], v147 offset:5120
	ds_read_b128 v[216:219], v147 offset:6144
	ds_read_b128 v[220:223], v147 offset:7168
	s_waitcnt vmcnt(8)
	s_waitcnt lgkmcnt(0)
	s_setprio 1
	s_waitcnt lgkmcnt(0)
	v_mfma_f32_16x16x32_bf16 v[122:125], v[148:151], v[180:183], v[122:125]
	v_mfma_f32_16x16x32_bf16 v[126:129], v[156:159], v[180:183], v[126:129]
	v_mfma_f32_16x16x32_bf16 v[110:113], v[148:151], v[200:203], v[110:113]
	v_mfma_f32_16x16x32_bf16 v[106:109], v[156:159], v[200:203], v[106:109]
	v_mfma_f32_16x16x32_bf16 v[94:97], v[148:151], v[208:211], v[94:97]
	v_mfma_f32_16x16x32_bf16 v[90:93], v[156:159], v[208:211], v[90:93]
	v_mfma_f32_16x16x32_bf16 v[78:81], v[148:151], v[216:219], v[78:81]
	v_mfma_f32_16x16x32_bf16 v[74:77], v[156:159], v[216:219], v[74:77]
	v_mfma_f32_16x16x32_bf16 v[122:125], v[152:155], v[184:187], v[122:125]
	v_mfma_f32_16x16x32_bf16 v[126:129], v[160:163], v[184:187], v[126:129]
	v_mfma_f32_16x16x32_bf16 v[110:113], v[152:155], v[204:207], v[110:113]
	v_mfma_f32_16x16x32_bf16 v[106:109], v[160:163], v[204:207], v[106:109]
	v_mfma_f32_16x16x32_bf16 v[94:97], v[152:155], v[212:215], v[94:97]
	v_mfma_f32_16x16x32_bf16 v[90:93], v[160:163], v[212:215], v[90:93]
	v_mfma_f32_16x16x32_bf16 v[78:81], v[152:155], v[220:223], v[78:81]
	v_mfma_f32_16x16x32_bf16 v[74:77], v[160:163], v[220:223], v[74:77]
	s_setprio 0
	s_setprio 1
	v_mfma_f32_16x16x32_bf16 v[118:121], v[164:167], v[180:183], v[118:121]
	v_mfma_f32_16x16x32_bf16 v[114:117], v[172:175], v[180:183], v[114:117]
	v_mfma_f32_16x16x32_bf16 v[102:105], v[164:167], v[200:203], v[102:105]
	v_mfma_f32_16x16x32_bf16 v[98:101], v[172:175], v[200:203], v[98:101]
	v_mfma_f32_16x16x32_bf16 v[86:89], v[164:167], v[208:211], v[86:89]
	v_mfma_f32_16x16x32_bf16 v[82:85], v[172:175], v[208:211], v[82:85]
	v_mfma_f32_16x16x32_bf16 v[70:73], v[164:167], v[216:219], v[70:73]
	v_mfma_f32_16x16x32_bf16 v[66:69], v[172:175], v[216:219], v[66:69]
	v_mfma_f32_16x16x32_bf16 v[118:121], v[168:171], v[184:187], v[118:121]
	v_mfma_f32_16x16x32_bf16 v[114:117], v[176:179], v[184:187], v[114:117]
	v_mfma_f32_16x16x32_bf16 v[102:105], v[168:171], v[204:207], v[102:105]
	v_mfma_f32_16x16x32_bf16 v[98:101], v[176:179], v[204:207], v[98:101]
	v_mfma_f32_16x16x32_bf16 v[86:89], v[168:171], v[212:215], v[86:89]
	v_mfma_f32_16x16x32_bf16 v[82:85], v[176:179], v[212:215], v[82:85]
	v_mfma_f32_16x16x32_bf16 v[70:73], v[168:171], v[220:223], v[70:73]
	v_mfma_f32_16x16x32_bf16 v[66:69], v[176:179], v[220:223], v[66:69]
	s_setprio 0
	s_barrier
	s_add_i32 s78, s78, s5
	v_lshl_add_u64 v[142:143], s[74:75], 0, v[134:135]
	s_mov_b32 m0, s78
	ds_read_b128 v[180:183], v147 offset:16384
	ds_read_b128 v[184:187], v147 offset:17408
	ds_read_b128 v[200:203], v147 offset:18432
	ds_read_b128 v[204:207], v147 offset:19456
	ds_read_b128 v[208:211], v147 offset:20480
	ds_read_b128 v[212:215], v147 offset:21504
	ds_read_b128 v[216:219], v147 offset:22528
	ds_read_b128 v[220:223], v147 offset:23552
	global_load_lds_dwordx4 v[142:143], off
	s_add_i32 m0, s78, 0x2000
	v_lshl_add_u64 v[188:189], s[74:75], 0, v[130:131]
	s_add_u32 s74, s74, s6
	s_addc_u32 s75, s75, s7
	s_add_i32 s78, s80, s5
	global_load_lds_dwordx4 v[188:189], off
	v_lshl_add_u64 v[224:225], s[74:75], 0, v[134:135]
	s_mov_b32 m0, s78
	v_lshl_add_u64 v[226:227], s[74:75], 0, v[130:131]
	global_load_lds_dwordx4 v[224:225], off
	s_add_i32 m0, s78, 0x2000
	v_lshl_add_u64 v[228:229], s[58:59], 0, v[136:137]
	global_load_lds_dwordx4 v[226:227], off
	v_lshl_add_u64 v[230:231], s[58:59], 0, v[132:133]
	s_waitcnt vmcnt(6)
	s_waitcnt lgkmcnt(0)
	s_setprio 1
	s_waitcnt lgkmcnt(0)
	v_mfma_f32_16x16x32_bf16 v[62:65], v[148:151], v[180:183], v[62:65]
	v_mfma_f32_16x16x32_bf16 v[58:61], v[156:159], v[180:183], v[58:61]
	v_mfma_f32_16x16x32_bf16 v[46:49], v[148:151], v[200:203], v[46:49]
	v_mfma_f32_16x16x32_bf16 v[42:45], v[156:159], v[200:203], v[42:45]
	v_mfma_f32_16x16x32_bf16 v[30:33], v[148:151], v[208:211], v[30:33]
	v_mfma_f32_16x16x32_bf16 v[26:29], v[156:159], v[208:211], v[26:29]
	v_mfma_f32_16x16x32_bf16 v[14:17], v[148:151], v[216:219], v[14:17]
	v_mfma_f32_16x16x32_bf16 v[10:13], v[156:159], v[216:219], v[10:13]
	v_mfma_f32_16x16x32_bf16 v[62:65], v[152:155], v[184:187], v[62:65]
	v_mfma_f32_16x16x32_bf16 v[58:61], v[160:163], v[184:187], v[58:61]
	v_mfma_f32_16x16x32_bf16 v[46:49], v[152:155], v[204:207], v[46:49]
	v_mfma_f32_16x16x32_bf16 v[42:45], v[160:163], v[204:207], v[42:45]
	v_mfma_f32_16x16x32_bf16 v[30:33], v[152:155], v[212:215], v[30:33]
	v_mfma_f32_16x16x32_bf16 v[26:29], v[160:163], v[212:215], v[26:29]
	v_mfma_f32_16x16x32_bf16 v[14:17], v[152:155], v[220:223], v[14:17]
	v_mfma_f32_16x16x32_bf16 v[10:13], v[160:163], v[220:223], v[10:13]
	s_setprio 0
	s_setprio 1
	v_mfma_f32_16x16x32_bf16 v[54:57], v[164:167], v[180:183], v[54:57]
	v_mfma_f32_16x16x32_bf16 v[50:53], v[172:175], v[180:183], v[50:53]
	v_mfma_f32_16x16x32_bf16 v[38:41], v[164:167], v[200:203], v[38:41]
	v_mfma_f32_16x16x32_bf16 v[34:37], v[172:175], v[200:203], v[34:37]
	v_mfma_f32_16x16x32_bf16 v[22:25], v[164:167], v[208:211], v[22:25]
	v_mfma_f32_16x16x32_bf16 v[18:21], v[172:175], v[208:211], v[18:21]
	v_mfma_f32_16x16x32_bf16 v[6:9], v[164:167], v[216:219], v[6:9]
	v_mfma_f32_16x16x32_bf16 v[2:5], v[172:175], v[216:219], v[2:5]
	v_mfma_f32_16x16x32_bf16 v[54:57], v[168:171], v[184:187], v[54:57]
	v_mfma_f32_16x16x32_bf16 v[50:53], v[176:179], v[184:187], v[50:53]
	v_mfma_f32_16x16x32_bf16 v[38:41], v[168:171], v[204:207], v[38:41]
	v_mfma_f32_16x16x32_bf16 v[34:37], v[176:179], v[204:207], v[34:37]
	v_mfma_f32_16x16x32_bf16 v[22:25], v[168:171], v[212:215], v[22:25]
	v_mfma_f32_16x16x32_bf16 v[18:21], v[176:179], v[212:215], v[18:21]
	v_mfma_f32_16x16x32_bf16 v[6:9], v[168:171], v[220:223], v[6:9]
	v_mfma_f32_16x16x32_bf16 v[2:5], v[176:179], v[220:223], v[2:5]
	s_setprio 0
	s_barrier
	s_add_i32 s74, 0, 0x18000
	v_add_u32_e32 v0, s74, v146
	s_add_i32 s75, 0, 0x1c000
	ds_read_b128 v[148:151], v0
	ds_read_b128 v[152:155], v0 offset:1024
	ds_read_b128 v[156:159], v0 offset:2048
	ds_read_b128 v[160:163], v0 offset:3072
	v_add_u32_e32 v0, s75, v146
	ds_read_b128 v[164:167], v0
	ds_read_b128 v[168:171], v0 offset:1024
	ds_read_b128 v[172:175], v0 offset:2048
	ds_read_b128 v[176:179], v0 offset:3072
	s_add_u32 s58, s58, s2
	s_addc_u32 s59, s59, s3
	s_mov_b32 m0, s27
	v_lshl_add_u64 v[232:233], s[58:59], 0, v[136:137]
	s_nop 0
	global_load_lds_dwordx4 v[228:229], off
	s_mov_b32 m0, s28
	s_nop 0
	global_load_lds_dwordx4 v[230:231], off
	s_mov_b32 m0, s29
	s_nop 0
	global_load_lds_dwordx4 v[232:233], off
	v_lshl_add_u64 v[232:233], s[58:59], 0, v[132:133]
	s_mov_b32 m0, s30
	s_nop 0
	global_load_lds_dwordx4 v[232:233], off
	ds_read_b128 v[180:183], v147 offset:32768
	ds_read_b128 v[184:187], v147 offset:33792
	ds_read_b128 v[200:203], v147 offset:34816
	ds_read_b128 v[204:207], v147 offset:35840
	ds_read_b128 v[208:211], v147 offset:36864
	ds_read_b128 v[212:215], v147 offset:37888
	ds_read_b128 v[216:219], v147 offset:38912
	ds_read_b128 v[220:223], v147 offset:39936
	s_waitcnt vmcnt(8)
	s_waitcnt lgkmcnt(0)
	s_setprio 1
	s_waitcnt lgkmcnt(0)
	v_mfma_f32_16x16x32_bf16 v[122:125], v[148:151], v[180:183], v[122:125]
	v_mfma_f32_16x16x32_bf16 v[126:129], v[156:159], v[180:183], v[126:129]
	v_mfma_f32_16x16x32_bf16 v[110:113], v[148:151], v[200:203], v[110:113]
	v_mfma_f32_16x16x32_bf16 v[106:109], v[156:159], v[200:203], v[106:109]
	v_mfma_f32_16x16x32_bf16 v[94:97], v[148:151], v[208:211], v[94:97]
	v_mfma_f32_16x16x32_bf16 v[90:93], v[156:159], v[208:211], v[90:93]
	v_mfma_f32_16x16x32_bf16 v[78:81], v[148:151], v[216:219], v[78:81]
	v_mfma_f32_16x16x32_bf16 v[74:77], v[156:159], v[216:219], v[74:77]
	v_mfma_f32_16x16x32_bf16 v[122:125], v[152:155], v[184:187], v[122:125]
	v_mfma_f32_16x16x32_bf16 v[126:129], v[160:163], v[184:187], v[126:129]
	v_mfma_f32_16x16x32_bf16 v[110:113], v[152:155], v[204:207], v[110:113]
	v_mfma_f32_16x16x32_bf16 v[106:109], v[160:163], v[204:207], v[106:109]
	v_mfma_f32_16x16x32_bf16 v[94:97], v[152:155], v[212:215], v[94:97]
	v_mfma_f32_16x16x32_bf16 v[90:93], v[160:163], v[212:215], v[90:93]
	v_mfma_f32_16x16x32_bf16 v[78:81], v[152:155], v[220:223], v[78:81]
	v_mfma_f32_16x16x32_bf16 v[74:77], v[160:163], v[220:223], v[74:77]
	s_setprio 0
	s_setprio 1
	v_mfma_f32_16x16x32_bf16 v[118:121], v[164:167], v[180:183], v[118:121]
	v_mfma_f32_16x16x32_bf16 v[114:117], v[172:175], v[180:183], v[114:117]
	v_mfma_f32_16x16x32_bf16 v[102:105], v[164:167], v[200:203], v[102:105]
	v_mfma_f32_16x16x32_bf16 v[98:101], v[172:175], v[200:203], v[98:101]
	v_mfma_f32_16x16x32_bf16 v[86:89], v[164:167], v[208:211], v[86:89]
	v_mfma_f32_16x16x32_bf16 v[82:85], v[172:175], v[208:211], v[82:85]
	v_mfma_f32_16x16x32_bf16 v[70:73], v[164:167], v[216:219], v[70:73]
	v_mfma_f32_16x16x32_bf16 v[66:69], v[172:175], v[216:219], v[66:69]
	v_mfma_f32_16x16x32_bf16 v[118:121], v[168:171], v[184:187], v[118:121]
	v_mfma_f32_16x16x32_bf16 v[114:117], v[176:179], v[184:187], v[114:117]
	v_mfma_f32_16x16x32_bf16 v[102:105], v[168:171], v[204:207], v[102:105]
	v_mfma_f32_16x16x32_bf16 v[98:101], v[176:179], v[204:207], v[98:101]
	v_mfma_f32_16x16x32_bf16 v[86:89], v[168:171], v[212:215], v[86:89]
	v_mfma_f32_16x16x32_bf16 v[82:85], v[176:179], v[212:215], v[82:85]
	v_mfma_f32_16x16x32_bf16 v[70:73], v[168:171], v[220:223], v[70:73]
	v_mfma_f32_16x16x32_bf16 v[66:69], v[176:179], v[220:223], v[66:69]
	s_setprio 0
	s_barrier
	s_add_i32 s58, s74, s5
	v_lshl_add_u64 v[142:143], v[142:143], 0, s[24:25]
	s_mov_b32 m0, s58
	ds_read_b128 v[180:183], v147 offset:49152
	ds_read_b128 v[184:187], v147 offset:50176
	ds_read_b128 v[200:203], v147 offset:51200
	ds_read_b128 v[204:207], v147 offset:52224
	ds_read_b128 v[208:211], v147 offset:53248
	ds_read_b128 v[212:215], v147 offset:54272
	ds_read_b128 v[216:219], v147 offset:55296
	ds_read_b128 v[220:223], v147 offset:56320
	global_load_lds_dwordx4 v[142:143], off
	v_lshl_add_u64 v[142:143], v[188:189], 0, s[24:25]
	s_add_i32 m0, s58, 0x2000
	s_add_i32 s58, s75, s5
	global_load_lds_dwordx4 v[142:143], off
	v_lshl_add_u64 v[142:143], v[224:225], 0, s[24:25]
	s_mov_b32 m0, s58
	s_nop 0
	global_load_lds_dwordx4 v[142:143], off
	v_lshl_add_u64 v[142:143], v[226:227], 0, s[24:25]
	s_add_i32 m0, s58, 0x2000
	s_nop 0
	global_load_lds_dwordx4 v[142:143], off
	s_waitcnt vmcnt(6)
	s_waitcnt lgkmcnt(0)
	s_setprio 1
	s_waitcnt lgkmcnt(0)
	v_mfma_f32_16x16x32_bf16 v[62:65], v[148:151], v[180:183], v[62:65]
	v_mfma_f32_16x16x32_bf16 v[58:61], v[156:159], v[180:183], v[58:61]
	v_mfma_f32_16x16x32_bf16 v[46:49], v[148:151], v[200:203], v[46:49]
	v_mfma_f32_16x16x32_bf16 v[42:45], v[156:159], v[200:203], v[42:45]
	v_mfma_f32_16x16x32_bf16 v[30:33], v[148:151], v[208:211], v[30:33]
	v_mfma_f32_16x16x32_bf16 v[26:29], v[156:159], v[208:211], v[26:29]
	v_mfma_f32_16x16x32_bf16 v[14:17], v[148:151], v[216:219], v[14:17]
	v_mfma_f32_16x16x32_bf16 v[10:13], v[156:159], v[216:219], v[10:13]
	v_mfma_f32_16x16x32_bf16 v[62:65], v[152:155], v[184:187], v[62:65]
	v_mfma_f32_16x16x32_bf16 v[58:61], v[160:163], v[184:187], v[58:61]
	v_mfma_f32_16x16x32_bf16 v[46:49], v[152:155], v[204:207], v[46:49]
	v_mfma_f32_16x16x32_bf16 v[42:45], v[160:163], v[204:207], v[42:45]
	v_mfma_f32_16x16x32_bf16 v[30:33], v[152:155], v[212:215], v[30:33]
	v_mfma_f32_16x16x32_bf16 v[26:29], v[160:163], v[212:215], v[26:29]
	v_mfma_f32_16x16x32_bf16 v[14:17], v[152:155], v[220:223], v[14:17]
	v_mfma_f32_16x16x32_bf16 v[10:13], v[160:163], v[220:223], v[10:13]
	s_setprio 0
	s_setprio 1
	v_mfma_f32_16x16x32_bf16 v[54:57], v[164:167], v[180:183], v[54:57]
	v_mfma_f32_16x16x32_bf16 v[50:53], v[172:175], v[180:183], v[50:53]
	v_mfma_f32_16x16x32_bf16 v[38:41], v[164:167], v[200:203], v[38:41]
	v_mfma_f32_16x16x32_bf16 v[34:37], v[172:175], v[200:203], v[34:37]
	v_mfma_f32_16x16x32_bf16 v[22:25], v[164:167], v[208:211], v[22:25]
	v_mfma_f32_16x16x32_bf16 v[18:21], v[172:175], v[208:211], v[18:21]
	v_mfma_f32_16x16x32_bf16 v[6:9], v[164:167], v[216:219], v[6:9]
	v_mfma_f32_16x16x32_bf16 v[2:5], v[172:175], v[216:219], v[2:5]
	v_mfma_f32_16x16x32_bf16 v[54:57], v[168:171], v[184:187], v[54:57]
	v_mfma_f32_16x16x32_bf16 v[50:53], v[176:179], v[184:187], v[50:53]
	v_mfma_f32_16x16x32_bf16 v[38:41], v[168:171], v[204:207], v[38:41]
	v_mfma_f32_16x16x32_bf16 v[34:37], v[176:179], v[204:207], v[34:37]
	v_mfma_f32_16x16x32_bf16 v[22:25], v[168:171], v[212:215], v[22:25]
	v_mfma_f32_16x16x32_bf16 v[18:21], v[176:179], v[212:215], v[18:21]
	v_mfma_f32_16x16x32_bf16 v[6:9], v[168:171], v[220:223], v[6:9]
	v_mfma_f32_16x16x32_bf16 v[2:5], v[176:179], v[220:223], v[2:5]
	s_setprio 0
	s_barrier
	s_add_u32 s56, s56, 0x100
	s_addc_u32 s57, s57, 0
	s_add_u32 s67, s67, 0x100
	s_addc_u32 s72, s72, 0
	s_cmp_ge_i32 s73, s60
	s_mov_b32 s58, s73
	s_cbranch_scc0 .Lmy_q211
.Lmy_post211:
	v_readlane_b32 s74, v236, 30
	v_readlane_b32 s75, v236, 31
	v_readlane_b32 s73, v236, 32
	s_mov_b32 s78, s76
.LBB0_213:
	s_and_b64 vcc, exec, s[38:39]
	s_cbranch_vccz .LBB0_215
	s_nop 0
.LBB0_215:
	v_mov_b32_e32 v0, v144
	v_mov_b32_e32 v142, v145
	s_lshl_b32 s50, s50, 8
	s_or_b32 s50, s50, s62
	s_ashr_i32 s55, s54, 31
	v_add_u32_e32 v148, s61, v0
	v_lshl_add_u32 v142, v142, 3, s50
	s_lshl_b64 s[50:51], s[54:55], 21
	v_readlane_b32 s54, v236, 59
	s_add_u32 s54, s54, s50
	v_readlane_b32 s50, v236, 56
	v_and_b32_e32 v149, 0xff, v148
	s_addc_u32 s55, s50, s51
	v_lshlrev_b32_e32 v0, 13, v149
	s_add_i32 s50, 0, 0x20400
	v_lshl_add_u64 v[150:151], s[54:55], 0, v[0:1]
	v_lshl_add_u32 v0, v149, 2, s50
	ds_read_b32 v0, v0
	v_ashrrev_i32_e32 v143, 31, v142
	v_lshlrev_b64 v[142:143], 1, v[142:143]
	v_lshl_add_u64 v[150:151], v[150:151], 0, v[142:143]
	s_movk_i32 s51, 0x80
	s_waitcnt lgkmcnt(0)
	v_pk_mul_f32 v[124:125], v[124:125], v[0:1] op_sel_hi:[1,0]
	v_pk_mul_f32 v[122:123], v[122:123], v[0:1] op_sel_hi:[1,0]
	v_pk_mul_f32 v[128:129], v[128:129], v[0:1] op_sel_hi:[1,0]
	v_pk_mul_f32 v[126:127], v[126:127], v[0:1] op_sel_hi:[1,0]
	v_max_f32_e32 v122, 0, v122
	v_max_f32_e32 v126, 0, v126
	v_max_f32_e32 v123, 0, v123
	v_max_f32_e32 v127, 0, v127
	v_max_f32_e32 v124, 0, v124
	v_max_f32_e32 v128, 0, v128
	v_max_f32_e32 v125, 0, v125
	v_max_f32_e32 v129, 0, v129
	v_pk_mul_f32 v[122:123], v[122:123], v[122:123]
	v_pk_mul_f32 v[126:127], v[126:127], v[126:127]
	v_pk_mul_f32 v[124:125], v[124:125], v[124:125]
	v_pk_mul_f32 v[128:129], v[128:129], v[128:129]
	v_pk_mul_f32 v[114:115], v[114:115], v[0:1] op_sel_hi:[1,0]
	v_cvt_pk_bf16_f32 v122, v122, v123
	v_cvt_pk_bf16_f32 v123, v124, v125
	v_cvt_pk_bf16_f32 v124, v126, v127
	v_cvt_pk_bf16_f32 v125, v128, v129
	v_pk_mul_f32 v[120:121], v[120:121], v[0:1] op_sel_hi:[1,0]
	v_pk_mul_f32 v[118:119], v[118:119], v[0:1] op_sel_hi:[1,0]
	v_pk_mul_f32 v[116:117], v[116:117], v[0:1] op_sel_hi:[1,0]
	v_max_f32_e32 v114, 0, v114
	v_max_f32_e32 v115, 0, v115
	global_store_dwordx4 v[150:151], v[122:125], off
	v_max_f32_e32 v118, 0, v118
	v_max_f32_e32 v119, 0, v119
	v_pk_mul_f32 v[122:123], v[114:115], v[114:115]
	v_max_f32_e32 v114, 0, v120
	v_max_f32_e32 v116, 0, v116
	v_max_f32_e32 v115, 0, v121
	v_max_f32_e32 v117, 0, v117
	v_pk_mul_f32 v[118:119], v[118:119], v[118:119]
	v_pk_mul_f32 v[120:121], v[114:115], v[114:115]
	v_pk_mul_f32 v[124:125], v[116:117], v[116:117]
	v_cvt_pk_bf16_f32 v114, v118, v119
	v_cvt_pk_bf16_f32 v115, v120, v121
	v_cvt_pk_bf16_f32 v116, v122, v123
	v_cvt_pk_bf16_f32 v117, v124, v125
	v_add_u32_e32 v0, 16, v148
	global_store_dwordx4 v[150:151], v[114:117], off offset:256
	s_andn2_b64 vcc, exec, s[48:49]
	s_nop 0
	v_and_b32_e32 v116, 0xff, v0
	v_lshlrev_b32_e32 v0, 13, v116
	v_lshl_add_u64 v[114:115], s[54:55], 0, v[0:1]
	v_lshl_add_u32 v0, v116, 2, s50
	ds_read_b32 v0, v0
	v_lshl_add_u64 v[114:115], v[114:115], 0, v[142:143]
	s_waitcnt lgkmcnt(0)
	v_pk_mul_f32 v[106:107], v[106:107], v[0:1] op_sel_hi:[1,0]
	v_pk_mul_f32 v[112:113], v[112:113], v[0:1] op_sel_hi:[1,0]
	v_pk_mul_f32 v[110:111], v[110:111], v[0:1] op_sel_hi:[1,0]
	v_pk_mul_f32 v[108:109], v[108:109], v[0:1] op_sel_hi:[1,0]
	v_max_f32_e32 v106, 0, v106
	v_max_f32_e32 v107, 0, v107
	v_max_f32_e32 v110, 0, v110
	v_max_f32_e32 v111, 0, v111
	v_pk_mul_f32 v[116:117], v[106:107], v[106:107]
	v_max_f32_e32 v106, 0, v112
	v_max_f32_e32 v108, 0, v108
	v_max_f32_e32 v107, 0, v113
	v_max_f32_e32 v109, 0, v109
	v_pk_mul_f32 v[110:111], v[110:111], v[110:111]
	v_pk_mul_f32 v[112:113], v[106:107], v[106:107]
	v_pk_mul_f32 v[118:119], v[108:109], v[108:109]
	v_pk_mul_f32 v[98:99], v[98:99], v[0:1] op_sel_hi:[1,0]
	v_cvt_pk_bf16_f32 v106, v110, v111
	v_cvt_pk_bf16_f32 v107, v112, v113
	v_cvt_pk_bf16_f32 v108, v116, v117
	v_cvt_pk_bf16_f32 v109, v118, v119
	v_pk_mul_f32 v[104:105], v[104:105], v[0:1] op_sel_hi:[1,0]
	v_pk_mul_f32 v[102:103], v[102:103], v[0:1] op_sel_hi:[1,0]
	v_pk_mul_f32 v[100:101], v[100:101], v[0:1] op_sel_hi:[1,0]
	v_max_f32_e32 v98, 0, v98
	v_max_f32_e32 v99, 0, v99
	global_store_dwordx4 v[114:115], v[106:109], off
	v_max_f32_e32 v102, 0, v102
	v_max_f32_e32 v103, 0, v103
	v_pk_mul_f32 v[106:107], v[98:99], v[98:99]
	v_max_f32_e32 v98, 0, v104
	v_max_f32_e32 v100, 0, v100
	v_max_f32_e32 v99, 0, v105
	v_max_f32_e32 v101, 0, v101
	v_pk_mul_f32 v[102:103], v[102:103], v[102:103]
	v_pk_mul_f32 v[104:105], v[98:99], v[98:99]
	v_pk_mul_f32 v[108:109], v[100:101], v[100:101]
	v_cvt_pk_bf16_f32 v98, v102, v103
	v_cvt_pk_bf16_f32 v99, v104, v105
	v_cvt_pk_bf16_f32 v100, v106, v107
	v_cvt_pk_bf16_f32 v101, v108, v109
	v_add_u32_e32 v0, 32, v148
	global_store_dwordx4 v[114:115], v[98:101], off offset:256
	s_nop 1
	v_and_b32_e32 v100, 0xff, v0
	v_lshlrev_b32_e32 v0, 13, v100
	v_lshl_add_u64 v[98:99], s[54:55], 0, v[0:1]
	v_lshl_add_u32 v0, v100, 2, s50
	ds_read_b32 v0, v0
	v_lshl_add_u64 v[98:99], v[98:99], 0, v[142:143]
	s_waitcnt lgkmcnt(0)
	v_pk_mul_f32 v[90:91], v[90:91], v[0:1] op_sel_hi:[1,0]
	v_pk_mul_f32 v[96:97], v[96:97], v[0:1] op_sel_hi:[1,0]
	v_pk_mul_f32 v[94:95], v[94:95], v[0:1] op_sel_hi:[1,0]
	v_pk_mul_f32 v[92:93], v[92:93], v[0:1] op_sel_hi:[1,0]
	v_max_f32_e32 v90, 0, v90
	v_max_f32_e32 v91, 0, v91
	v_max_f32_e32 v94, 0, v94
	v_max_f32_e32 v95, 0, v95
	v_pk_mul_f32 v[100:101], v[90:91], v[90:91]
	v_max_f32_e32 v90, 0, v96
	v_max_f32_e32 v92, 0, v92
	v_max_f32_e32 v91, 0, v97
	v_max_f32_e32 v93, 0, v93
	v_pk_mul_f32 v[94:95], v[94:95], v[94:95]
	v_pk_mul_f32 v[96:97], v[90:91], v[90:91]
	v_pk_mul_f32 v[102:103], v[92:93], v[92:93]
	v_pk_mul_f32 v[82:83], v[82:83], v[0:1] op_sel_hi:[1,0]
	v_cvt_pk_bf16_f32 v90, v94, v95
	v_cvt_pk_bf16_f32 v91, v96, v97
	v_cvt_pk_bf16_f32 v92, v100, v101
	v_cvt_pk_bf16_f32 v93, v102, v103
	v_pk_mul_f32 v[88:89], v[88:89], v[0:1] op_sel_hi:[1,0]
	v_pk_mul_f32 v[86:87], v[86:87], v[0:1] op_sel_hi:[1,0]
	v_pk_mul_f32 v[84:85], v[84:85], v[0:1] op_sel_hi:[1,0]
	v_max_f32_e32 v82, 0, v82
	v_max_f32_e32 v83, 0, v83
	global_store_dwordx4 v[98:99], v[90:93], off
	v_max_f32_e32 v86, 0, v86
	v_max_f32_e32 v87, 0, v87
	v_pk_mul_f32 v[90:91], v[82:83], v[82:83]
	v_max_f32_e32 v82, 0, v88
	v_max_f32_e32 v84, 0, v84
	v_max_f32_e32 v83, 0, v89
	v_max_f32_e32 v85, 0, v85
	v_pk_mul_f32 v[86:87], v[86:87], v[86:87]
	v_pk_mul_f32 v[88:89], v[82:83], v[82:83]
	v_pk_mul_f32 v[92:93], v[84:85], v[84:85]
	v_cvt_pk_bf16_f32 v82, v86, v87
	v_cvt_pk_bf16_f32 v83, v88, v89
	v_cvt_pk_bf16_f32 v84, v90, v91
	v_cvt_pk_bf16_f32 v85, v92, v93
	v_add_u32_e32 v0, 48, v148
	global_store_dwordx4 v[98:99], v[82:85], off offset:256
	s_nop 1
	v_and_b32_e32 v84, 0xff, v0
	v_lshlrev_b32_e32 v0, 13, v84
	v_lshl_add_u64 v[82:83], s[54:55], 0, v[0:1]
	v_lshl_add_u32 v0, v84, 2, s50
	ds_read_b32 v0, v0
	v_lshl_add_u64 v[82:83], v[82:83], 0, v[142:143]
	s_waitcnt lgkmcnt(0)
	v_pk_mul_f32 v[74:75], v[74:75], v[0:1] op_sel_hi:[1,0]
	v_pk_mul_f32 v[80:81], v[80:81], v[0:1] op_sel_hi:[1,0]
	v_pk_mul_f32 v[78:79], v[78:79], v[0:1] op_sel_hi:[1,0]
	v_pk_mul_f32 v[76:77], v[76:77], v[0:1] op_sel_hi:[1,0]
	v_max_f32_e32 v74, 0, v74
	v_max_f32_e32 v75, 0, v75
	v_max_f32_e32 v78, 0, v78
	v_max_f32_e32 v79, 0, v79
	v_pk_mul_f32 v[84:85], v[74:75], v[74:75]
	v_max_f32_e32 v74, 0, v80
	v_max_f32_e32 v76, 0, v76
	v_max_f32_e32 v75, 0, v81
	v_max_f32_e32 v77, 0, v77
	v_pk_mul_f32 v[78:79], v[78:79], v[78:79]
	v_pk_mul_f32 v[80:81], v[74:75], v[74:75]
	v_pk_mul_f32 v[86:87], v[76:77], v[76:77]
	v_pk_mul_f32 v[66:67], v[66:67], v[0:1] op_sel_hi:[1,0]
	v_cvt_pk_bf16_f32 v74, v78, v79
	v_cvt_pk_bf16_f32 v75, v80, v81
	v_cvt_pk_bf16_f32 v76, v84, v85
	v_cvt_pk_bf16_f32 v77, v86, v87
	v_pk_mul_f32 v[72:73], v[72:73], v[0:1] op_sel_hi:[1,0]
	v_pk_mul_f32 v[70:71], v[70:71], v[0:1] op_sel_hi:[1,0]
	v_pk_mul_f32 v[68:69], v[68:69], v[0:1] op_sel_hi:[1,0]
	v_max_f32_e32 v66, 0, v66
	v_max_f32_e32 v67, 0, v67
	global_store_dwordx4 v[82:83], v[74:77], off
	v_max_f32_e32 v70, 0, v70
	v_max_f32_e32 v71, 0, v71
	v_pk_mul_f32 v[74:75], v[66:67], v[66:67]
	v_max_f32_e32 v66, 0, v72
	v_max_f32_e32 v68, 0, v68
	v_max_f32_e32 v67, 0, v73
	v_max_f32_e32 v69, 0, v69
	v_pk_mul_f32 v[70:71], v[70:71], v[70:71]
	v_pk_mul_f32 v[72:73], v[66:67], v[66:67]
	v_pk_mul_f32 v[76:77], v[68:69], v[68:69]
	v_cvt_pk_bf16_f32 v66, v70, v71
	v_cvt_pk_bf16_f32 v67, v72, v73
	v_cvt_pk_bf16_f32 v68, v74, v75
	v_cvt_pk_bf16_f32 v69, v76, v77
	global_store_dwordx4 v[82:83], v[66:69], off offset:256
	s_nop 1
	v_bitop3_b32 v68, v148, s51, v195 bitop3:0x6c
	v_lshlrev_b32_e32 v0, 13, v68
	v_lshl_add_u64 v[66:67], s[54:55], 0, v[0:1]
	v_lshl_add_u32 v0, v68, 2, s50
	ds_read_b32 v0, v0
	v_lshl_add_u64 v[66:67], v[66:67], 0, v[142:143]
	s_waitcnt lgkmcnt(0)
	v_pk_mul_f32 v[58:59], v[58:59], v[0:1] op_sel_hi:[1,0]
	v_pk_mul_f32 v[64:65], v[64:65], v[0:1] op_sel_hi:[1,0]
	v_pk_mul_f32 v[62:63], v[62:63], v[0:1] op_sel_hi:[1,0]
	v_pk_mul_f32 v[60:61], v[60:61], v[0:1] op_sel_hi:[1,0]
	v_max_f32_e32 v58, 0, v58
	v_max_f32_e32 v59, 0, v59
	v_max_f32_e32 v62, 0, v62
	v_max_f32_e32 v63, 0, v63
	v_pk_mul_f32 v[68:69], v[58:59], v[58:59]
	v_max_f32_e32 v58, 0, v64
	v_max_f32_e32 v60, 0, v60
	v_max_f32_e32 v59, 0, v65
	v_max_f32_e32 v61, 0, v61
	v_pk_mul_f32 v[62:63], v[62:63], v[62:63]
	v_pk_mul_f32 v[64:65], v[58:59], v[58:59]
	v_pk_mul_f32 v[70:71], v[60:61], v[60:61]
	v_pk_mul_f32 v[50:51], v[50:51], v[0:1] op_sel_hi:[1,0]
	v_cvt_pk_bf16_f32 v58, v62, v63
	v_cvt_pk_bf16_f32 v59, v64, v65
	v_cvt_pk_bf16_f32 v60, v68, v69
	v_cvt_pk_bf16_f32 v61, v70, v71
	v_pk_mul_f32 v[56:57], v[56:57], v[0:1] op_sel_hi:[1,0]
	v_pk_mul_f32 v[54:55], v[54:55], v[0:1] op_sel_hi:[1,0]
	v_pk_mul_f32 v[52:53], v[52:53], v[0:1] op_sel_hi:[1,0]
	v_max_f32_e32 v50, 0, v50
	v_max_f32_e32 v51, 0, v51
	global_store_dwordx4 v[66:67], v[58:61], off
	v_max_f32_e32 v54, 0, v54
	v_max_f32_e32 v55, 0, v55
	v_pk_mul_f32 v[58:59], v[50:51], v[50:51]
	v_max_f32_e32 v50, 0, v56
	v_max_f32_e32 v52, 0, v52
	v_max_f32_e32 v51, 0, v57
	v_max_f32_e32 v53, 0, v53
	v_pk_mul_f32 v[54:55], v[54:55], v[54:55]
	v_pk_mul_f32 v[56:57], v[50:51], v[50:51]
	v_pk_mul_f32 v[60:61], v[52:53], v[52:53]
	v_cvt_pk_bf16_f32 v50, v54, v55
	v_cvt_pk_bf16_f32 v51, v56, v57
	v_cvt_pk_bf16_f32 v52, v58, v59
	v_cvt_pk_bf16_f32 v53, v60, v61
	v_add_u32_e32 v0, 0x90, v148
	global_store_dwordx4 v[66:67], v[50:53], off offset:256
	s_nop 1
	v_and_b32_e32 v52, 0xff, v0
	v_lshlrev_b32_e32 v0, 13, v52
	v_lshl_add_u64 v[50:51], s[54:55], 0, v[0:1]
	v_lshl_add_u32 v0, v52, 2, s50
	ds_read_b32 v0, v0
	v_lshl_add_u64 v[50:51], v[50:51], 0, v[142:143]
	s_waitcnt lgkmcnt(0)
	v_pk_mul_f32 v[42:43], v[42:43], v[0:1] op_sel_hi:[1,0]
	v_pk_mul_f32 v[48:49], v[48:49], v[0:1] op_sel_hi:[1,0]
	v_pk_mul_f32 v[46:47], v[46:47], v[0:1] op_sel_hi:[1,0]
	v_pk_mul_f32 v[44:45], v[44:45], v[0:1] op_sel_hi:[1,0]
	v_max_f32_e32 v42, 0, v42
	v_max_f32_e32 v43, 0, v43
	v_max_f32_e32 v46, 0, v46
	v_max_f32_e32 v47, 0, v47
	v_pk_mul_f32 v[52:53], v[42:43], v[42:43]
	v_max_f32_e32 v42, 0, v48
	v_max_f32_e32 v44, 0, v44
	v_max_f32_e32 v43, 0, v49
	v_max_f32_e32 v45, 0, v45
	v_pk_mul_f32 v[46:47], v[46:47], v[46:47]
	v_pk_mul_f32 v[48:49], v[42:43], v[42:43]
	v_pk_mul_f32 v[54:55], v[44:45], v[44:45]
	v_pk_mul_f32 v[34:35], v[34:35], v[0:1] op_sel_hi:[1,0]
	v_cvt_pk_bf16_f32 v42, v46, v47
	v_cvt_pk_bf16_f32 v43, v48, v49
	v_cvt_pk_bf16_f32 v44, v52, v53
	v_cvt_pk_bf16_f32 v45, v54, v55
	v_pk_mul_f32 v[40:41], v[40:41], v[0:1] op_sel_hi:[1,0]
	v_pk_mul_f32 v[38:39], v[38:39], v[0:1] op_sel_hi:[1,0]
	v_pk_mul_f32 v[36:37], v[36:37], v[0:1] op_sel_hi:[1,0]
	v_max_f32_e32 v34, 0, v34
	v_max_f32_e32 v35, 0, v35
	global_store_dwordx4 v[50:51], v[42:45], off
	v_max_f32_e32 v38, 0, v38
	v_max_f32_e32 v39, 0, v39
	v_pk_mul_f32 v[42:43], v[34:35], v[34:35]
	v_max_f32_e32 v34, 0, v40
	v_max_f32_e32 v36, 0, v36
	v_max_f32_e32 v35, 0, v41
	v_max_f32_e32 v37, 0, v37
	v_pk_mul_f32 v[38:39], v[38:39], v[38:39]
	v_pk_mul_f32 v[40:41], v[34:35], v[34:35]
	v_pk_mul_f32 v[44:45], v[36:37], v[36:37]
	v_cvt_pk_bf16_f32 v34, v38, v39
	v_cvt_pk_bf16_f32 v35, v40, v41
	v_cvt_pk_bf16_f32 v36, v42, v43
	v_cvt_pk_bf16_f32 v37, v44, v45
	v_add_u32_e32 v0, 0xa0, v148
	global_store_dwordx4 v[50:51], v[34:37], off offset:256
	s_nop 1
	v_and_b32_e32 v36, 0xff, v0
	v_lshlrev_b32_e32 v0, 13, v36
	v_lshl_add_u64 v[34:35], s[54:55], 0, v[0:1]
	v_lshl_add_u32 v0, v36, 2, s50
	ds_read_b32 v0, v0
	v_lshl_add_u64 v[34:35], v[34:35], 0, v[142:143]
	s_waitcnt lgkmcnt(0)
	v_pk_mul_f32 v[26:27], v[26:27], v[0:1] op_sel_hi:[1,0]
	v_pk_mul_f32 v[32:33], v[32:33], v[0:1] op_sel_hi:[1,0]
	v_pk_mul_f32 v[30:31], v[30:31], v[0:1] op_sel_hi:[1,0]
	v_pk_mul_f32 v[28:29], v[28:29], v[0:1] op_sel_hi:[1,0]
	v_max_f32_e32 v26, 0, v26
	v_max_f32_e32 v27, 0, v27
	v_max_f32_e32 v30, 0, v30
	v_max_f32_e32 v31, 0, v31
	v_pk_mul_f32 v[36:37], v[26:27], v[26:27]
	v_max_f32_e32 v26, 0, v32
	v_max_f32_e32 v28, 0, v28
	v_max_f32_e32 v27, 0, v33
	v_max_f32_e32 v29, 0, v29
	v_pk_mul_f32 v[30:31], v[30:31], v[30:31]
	v_pk_mul_f32 v[32:33], v[26:27], v[26:27]
	v_pk_mul_f32 v[38:39], v[28:29], v[28:29]
	v_pk_mul_f32 v[18:19], v[18:19], v[0:1] op_sel_hi:[1,0]
	v_cvt_pk_bf16_f32 v26, v30, v31
	v_cvt_pk_bf16_f32 v27, v32, v33
	v_cvt_pk_bf16_f32 v28, v36, v37
	v_cvt_pk_bf16_f32 v29, v38, v39
	v_pk_mul_f32 v[24:25], v[24:25], v[0:1] op_sel_hi:[1,0]
	v_pk_mul_f32 v[22:23], v[22:23], v[0:1] op_sel_hi:[1,0]
	v_pk_mul_f32 v[20:21], v[20:21], v[0:1] op_sel_hi:[1,0]
	v_max_f32_e32 v18, 0, v18
	v_max_f32_e32 v19, 0, v19
	global_store_dwordx4 v[34:35], v[26:29], off
	v_max_f32_e32 v22, 0, v22
	v_max_f32_e32 v23, 0, v23
	v_pk_mul_f32 v[26:27], v[18:19], v[18:19]
	v_max_f32_e32 v18, 0, v24
	v_max_f32_e32 v20, 0, v20
	v_max_f32_e32 v19, 0, v25
	v_max_f32_e32 v21, 0, v21
	v_pk_mul_f32 v[22:23], v[22:23], v[22:23]
	v_pk_mul_f32 v[24:25], v[18:19], v[18:19]
	v_pk_mul_f32 v[28:29], v[20:21], v[20:21]
	v_cvt_pk_bf16_f32 v18, v22, v23
	v_cvt_pk_bf16_f32 v19, v24, v25
	v_cvt_pk_bf16_f32 v20, v26, v27
	v_cvt_pk_bf16_f32 v21, v28, v29
	v_add_u32_e32 v0, 0xb0, v148
	global_store_dwordx4 v[34:35], v[18:21], off offset:256
	s_nop 1
	v_and_b32_e32 v20, 0xff, v0
	v_lshlrev_b32_e32 v0, 13, v20
	v_lshl_add_u64 v[18:19], s[54:55], 0, v[0:1]
	v_lshl_add_u32 v0, v20, 2, s50
	ds_read_b32 v0, v0
	v_lshl_add_u64 v[18:19], v[18:19], 0, v[142:143]
	s_mov_b64 s[50:51], -1
	s_waitcnt lgkmcnt(0)
	v_pk_mul_f32 v[10:11], v[10:11], v[0:1] op_sel_hi:[1,0]
	v_pk_mul_f32 v[16:17], v[16:17], v[0:1] op_sel_hi:[1,0]
	v_pk_mul_f32 v[14:15], v[14:15], v[0:1] op_sel_hi:[1,0]
	v_pk_mul_f32 v[12:13], v[12:13], v[0:1] op_sel_hi:[1,0]
	v_max_f32_e32 v10, 0, v10
	v_max_f32_e32 v11, 0, v11
	v_max_f32_e32 v14, 0, v14
	v_max_f32_e32 v15, 0, v15
	v_pk_mul_f32 v[20:21], v[10:11], v[10:11]
	v_max_f32_e32 v10, 0, v16
	v_max_f32_e32 v12, 0, v12
	v_max_f32_e32 v11, 0, v17
	v_max_f32_e32 v13, 0, v13
	v_pk_mul_f32 v[14:15], v[14:15], v[14:15]
	v_pk_mul_f32 v[16:17], v[10:11], v[10:11]
	v_pk_mul_f32 v[22:23], v[12:13], v[12:13]
	v_pk_mul_f32 v[2:3], v[2:3], v[0:1] op_sel_hi:[1,0]
	v_cvt_pk_bf16_f32 v10, v14, v15
	v_cvt_pk_bf16_f32 v11, v16, v17
	v_cvt_pk_bf16_f32 v12, v20, v21
	v_cvt_pk_bf16_f32 v13, v22, v23
	v_pk_mul_f32 v[8:9], v[8:9], v[0:1] op_sel_hi:[1,0]
	v_pk_mul_f32 v[6:7], v[6:7], v[0:1] op_sel_hi:[1,0]
	v_pk_mul_f32 v[4:5], v[4:5], v[0:1] op_sel_hi:[1,0]
	v_max_f32_e32 v2, 0, v2
	v_max_f32_e32 v3, 0, v3
	global_store_dwordx4 v[18:19], v[10:13], off
	v_max_f32_e32 v6, 0, v6
	v_max_f32_e32 v7, 0, v7
	v_pk_mul_f32 v[10:11], v[2:3], v[2:3]
	v_max_f32_e32 v2, 0, v8
	v_max_f32_e32 v4, 0, v4
	v_max_f32_e32 v3, 0, v9
	v_max_f32_e32 v5, 0, v5
	v_pk_mul_f32 v[6:7], v[6:7], v[6:7]
	v_pk_mul_f32 v[8:9], v[2:3], v[2:3]
	v_pk_mul_f32 v[12:13], v[4:5], v[4:5]
	v_cvt_pk_bf16_f32 v2, v6, v7
	v_cvt_pk_bf16_f32 v3, v8, v9
	v_cvt_pk_bf16_f32 v4, v10, v11
	v_cvt_pk_bf16_f32 v5, v12, v13
	global_store_dwordx4 v[18:19], v[2:5], off offset:256
	s_cbranch_vccnz .LBB0_206
	s_andn2_b64 vcc, exec, s[40:41]
	s_cbranch_vccnz .LBB0_205
	s_nop 0
	s_branch .LBB0_205

.LBB0_228:
	s_and_b32 s48, s48, 7
	s_or_b32 s73, s48, s4
	s_and_b64 s[48:49], s[46:47], exec
	s_cselect_b32 s48, s73, s29
	s_ashr_i32 s49, s48, 31
	s_lshl_b64 s[48:49], s[48:49], 21
	v_readlane_b32 s29, v236, 61
	s_add_u32 s48, s29, s48
	v_readlane_b32 s29, v236, 58
	v_mov_b32_e32 v125, 0
	s_addc_u32 s49, s29, s49
	s_andn2_b64 vcc, exec, s[42:43]
	v_mov_b32_e32 v124, v125
	v_mov_b32_e32 v123, v125
	v_mov_b32_e32 v122, v125
	v_mov_b32_e32 v129, v125
	v_mov_b32_e32 v128, v125
	v_mov_b32_e32 v127, v125
	v_mov_b32_e32 v126, v125
	v_mov_b32_e32 v113, v125
	v_mov_b32_e32 v112, v125
	v_mov_b32_e32 v111, v125
	v_mov_b32_e32 v110, v125
	v_mov_b32_e32 v109, v125
	v_mov_b32_e32 v108, v125
	v_mov_b32_e32 v107, v125
	v_mov_b32_e32 v106, v125
	v_mov_b32_e32 v97, v125
	v_mov_b32_e32 v96, v125
	v_mov_b32_e32 v95, v125
	v_mov_b32_e32 v94, v125
	v_mov_b32_e32 v93, v125
	v_mov_b32_e32 v92, v125
	v_mov_b32_e32 v91, v125
	v_mov_b32_e32 v90, v125
	v_mov_b32_e32 v81, v125
	v_mov_b32_e32 v80, v125
	v_mov_b32_e32 v79, v125
	v_mov_b32_e32 v78, v125
	v_mov_b32_e32 v77, v125
	v_mov_b32_e32 v76, v125
	v_mov_b32_e32 v75, v125
	v_mov_b32_e32 v74, v125
	v_mov_b32_e32 v121, v125
	v_mov_b32_e32 v120, v125
	v_mov_b32_e32 v119, v125
	v_mov_b32_e32 v118, v125
	v_mov_b32_e32 v117, v125
	v_mov_b32_e32 v116, v125
	v_mov_b32_e32 v115, v125
	v_mov_b32_e32 v114, v125
	v_mov_b32_e32 v105, v125
	v_mov_b32_e32 v104, v125
	v_mov_b32_e32 v103, v125
	v_mov_b32_e32 v102, v125
	v_mov_b32_e32 v101, v125
	v_mov_b32_e32 v100, v125
	v_mov_b32_e32 v99, v125
	v_mov_b32_e32 v98, v125
	v_mov_b32_e32 v89, v125
	v_mov_b32_e32 v88, v125
	v_mov_b32_e32 v87, v125
	v_mov_b32_e32 v86, v125
	v_mov_b32_e32 v85, v125
	v_mov_b32_e32 v84, v125
	v_mov_b32_e32 v83, v125
	v_mov_b32_e32 v82, v125
	v_mov_b32_e32 v73, v125
	v_mov_b32_e32 v72, v125
	v_mov_b32_e32 v71, v125
	v_mov_b32_e32 v70, v125
	v_mov_b32_e32 v69, v125
	v_mov_b32_e32 v68, v125
	v_mov_b32_e32 v67, v125
	v_mov_b32_e32 v66, v125
	v_mov_b32_e32 v65, v125
	v_mov_b32_e32 v64, v125
	v_mov_b32_e32 v63, v125
	v_mov_b32_e32 v62, v125
	v_mov_b32_e32 v61, v125
	v_mov_b32_e32 v60, v125
	v_mov_b32_e32 v59, v125
	v_mov_b32_e32 v58, v125
	v_mov_b32_e32 v49, v125
	v_mov_b32_e32 v48, v125
	v_mov_b32_e32 v47, v125
	v_mov_b32_e32 v46, v125
	v_mov_b32_e32 v45, v125
	v_mov_b32_e32 v44, v125
	v_mov_b32_e32 v43, v125
	v_mov_b32_e32 v42, v125
	v_mov_b32_e32 v33, v125
	v_mov_b32_e32 v32, v125
	v_mov_b32_e32 v31, v125
	v_mov_b32_e32 v30, v125
	v_mov_b32_e32 v29, v125
	v_mov_b32_e32 v28, v125
	v_mov_b32_e32 v27, v125
	v_mov_b32_e32 v26, v125
	v_mov_b32_e32 v17, v125
	v_mov_b32_e32 v16, v125
	v_mov_b32_e32 v15, v125
	v_mov_b32_e32 v14, v125
	v_mov_b32_e32 v13, v125
	v_mov_b32_e32 v12, v125
	v_mov_b32_e32 v11, v125
	v_mov_b32_e32 v10, v125
	v_mov_b32_e32 v57, v125
	v_mov_b32_e32 v56, v125
	v_mov_b32_e32 v55, v125
	v_mov_b32_e32 v54, v125
	v_mov_b32_e32 v53, v125
	v_mov_b32_e32 v52, v125
	v_mov_b32_e32 v51, v125
	v_mov_b32_e32 v50, v125
	v_mov_b32_e32 v41, v125
	v_mov_b32_e32 v40, v125
	v_mov_b32_e32 v39, v125
	v_mov_b32_e32 v38, v125
	v_mov_b32_e32 v37, v125
	v_mov_b32_e32 v36, v125
	v_mov_b32_e32 v35, v125
	v_mov_b32_e32 v34, v125
	v_mov_b32_e32 v25, v125
	v_mov_b32_e32 v24, v125
	v_mov_b32_e32 v23, v125
	v_mov_b32_e32 v22, v125
	v_mov_b32_e32 v21, v125
	v_mov_b32_e32 v20, v125
	v_mov_b32_e32 v19, v125
	v_mov_b32_e32 v18, v125
	v_mov_b32_e32 v9, v125
	v_mov_b32_e32 v8, v125
	v_mov_b32_e32 v7, v125
	v_mov_b32_e32 v6, v125
	v_mov_b32_e32 v5, v125
	v_mov_b32_e32 v4, v125
	s_waitcnt lgkmcnt(0)
	v_mov_b32_e32 v3, v125
	v_mov_b32_e32 v2, v125
	s_cbranch_vccnz .LBB0_232
	s_and_b64 s[50:51], s[46:47], exec
	s_cselect_b32 s29, s49, s57
	s_cselect_b32 s50, s48, s56
	s_add_u32 s56, s56, 0x80
	s_addc_u32 s57, s57, 0
	s_add_u32 s51, s58, 0x100
	v_mov_b32_e32 v2, 0
	s_addc_u32 s55, s59, 0
	s_mov_b32 s58, 0
	v_mov_b32_e32 v3, v2
	v_mov_b32_e32 v4, v2
	v_mov_b32_e32 v5, v2
	v_mov_b32_e32 v6, v2
	v_mov_b32_e32 v7, v2
	v_mov_b32_e32 v8, v2
	v_mov_b32_e32 v9, v2
	v_mov_b32_e32 v18, v2
	v_mov_b32_e32 v19, v2
	v_mov_b32_e32 v20, v2
	v_mov_b32_e32 v21, v2
	v_mov_b32_e32 v22, v2
	v_mov_b32_e32 v23, v2
	v_mov_b32_e32 v24, v2
	v_mov_b32_e32 v25, v2
	v_mov_b32_e32 v34, v2
	v_mov_b32_e32 v35, v2
	v_mov_b32_e32 v36, v2
	v_mov_b32_e32 v37, v2
	v_mov_b32_e32 v38, v2
	v_mov_b32_e32 v39, v2
	v_mov_b32_e32 v40, v2
	v_mov_b32_e32 v41, v2
	v_mov_b32_e32 v50, v2
	v_mov_b32_e32 v51, v2
	v_mov_b32_e32 v52, v2
	v_mov_b32_e32 v53, v2
	v_mov_b32_e32 v54, v2
	v_mov_b32_e32 v55, v2
	v_mov_b32_e32 v56, v2
	v_mov_b32_e32 v57, v2
	v_mov_b32_e32 v10, v2
	v_mov_b32_e32 v11, v2
	v_mov_b32_e32 v12, v2
	v_mov_b32_e32 v13, v2
	v_mov_b32_e32 v14, v2
	v_mov_b32_e32 v15, v2
	v_mov_b32_e32 v16, v2
	v_mov_b32_e32 v17, v2
	v_mov_b32_e32 v26, v2
	v_mov_b32_e32 v27, v2
	v_mov_b32_e32 v28, v2
	v_mov_b32_e32 v29, v2
	v_mov_b32_e32 v30, v2
	v_mov_b32_e32 v31, v2
	v_mov_b32_e32 v32, v2
	v_mov_b32_e32 v33, v2
	v_mov_b32_e32 v42, v2
	v_mov_b32_e32 v43, v2
	v_mov_b32_e32 v44, v2
	v_mov_b32_e32 v45, v2
	v_mov_b32_e32 v46, v2
	v_mov_b32_e32 v47, v2
	v_mov_b32_e32 v48, v2
	v_mov_b32_e32 v49, v2
	v_mov_b32_e32 v58, v2
	v_mov_b32_e32 v59, v2
	v_mov_b32_e32 v60, v2
	v_mov_b32_e32 v61, v2
	v_mov_b32_e32 v62, v2
	v_mov_b32_e32 v63, v2
	v_mov_b32_e32 v64, v2
	v_mov_b32_e32 v65, v2
	v_mov_b32_e32 v66, v2
	v_mov_b32_e32 v67, v2
	v_mov_b32_e32 v68, v2
	v_mov_b32_e32 v69, v2
	v_mov_b32_e32 v70, v2
	v_mov_b32_e32 v71, v2
	v_mov_b32_e32 v72, v2
	v_mov_b32_e32 v73, v2
	v_mov_b32_e32 v82, v2
	v_mov_b32_e32 v83, v2
	v_mov_b32_e32 v84, v2
	v_mov_b32_e32 v85, v2
	v_mov_b32_e32 v86, v2
	v_mov_b32_e32 v87, v2
	v_mov_b32_e32 v88, v2
	v_mov_b32_e32 v89, v2
	v_mov_b32_e32 v98, v2
	v_mov_b32_e32 v99, v2
	v_mov_b32_e32 v100, v2
	v_mov_b32_e32 v101, v2
	v_mov_b32_e32 v102, v2
	v_mov_b32_e32 v103, v2
	v_mov_b32_e32 v104, v2
	v_mov_b32_e32 v105, v2
	v_mov_b32_e32 v114, v2
	v_mov_b32_e32 v115, v2
	v_mov_b32_e32 v116, v2
	v_mov_b32_e32 v117, v2
	v_mov_b32_e32 v118, v2
	v_mov_b32_e32 v119, v2
	v_mov_b32_e32 v120, v2
	v_mov_b32_e32 v121, v2
	v_mov_b32_e32 v74, v2
	v_mov_b32_e32 v75, v2
	v_mov_b32_e32 v76, v2
	v_mov_b32_e32 v77, v2
	v_mov_b32_e32 v78, v2
	v_mov_b32_e32 v79, v2
	v_mov_b32_e32 v80, v2
	v_mov_b32_e32 v81, v2
	v_mov_b32_e32 v90, v2
	v_mov_b32_e32 v91, v2
	v_mov_b32_e32 v92, v2
	v_mov_b32_e32 v93, v2
	v_mov_b32_e32 v94, v2
	v_mov_b32_e32 v95, v2
	v_mov_b32_e32 v96, v2
	v_mov_b32_e32 v97, v2
	v_mov_b32_e32 v106, v2
	v_mov_b32_e32 v107, v2
	v_mov_b32_e32 v108, v2
	v_mov_b32_e32 v109, v2
	v_mov_b32_e32 v110, v2
	v_mov_b32_e32 v111, v2
	v_mov_b32_e32 v112, v2
	v_mov_b32_e32 v113, v2
	v_mov_b32_e32 v126, v2
	v_mov_b32_e32 v127, v2
	v_mov_b32_e32 v128, v2
	v_mov_b32_e32 v129, v2
	v_mov_b32_e32 v122, v2
	v_mov_b32_e32 v123, v2
	v_mov_b32_e32 v124, v2
	v_mov_b32_e32 v125, v2
	s_bitcmp1_b32 s40, 0
	s_cbranch_scc0 .Lmy_q230
.LBB0_230:
	s_add_i32 s74, s58, 2
	s_add_u32 s75, s56, 0x80
	s_addc_u32 s59, s57, 0
	s_add_i32 s78, 0, 0x10000
	s_cmp_eq_u32 s66, s58
	s_cselect_b32 s59, s29, s59
	s_cselect_b32 s58, s50, s75
	s_cselect_b32 s81, s45, s55
	s_cselect_b32 s80, s44, s51
	s_add_i32 s75, 0, 0x14000
	v_add_u32_e32 v156, s78, v146
	v_add_u32_e32 v172, s75, v146
	ds_read_b128 v[140:143], v156
	ds_read_b128 v[148:151], v156 offset:1024
	ds_read_b128 v[152:155], v156 offset:2048
	ds_read_b128 v[156:159], v156 offset:3072
	ds_read_b128 v[160:163], v172
	ds_read_b128 v[164:167], v172 offset:1024
	ds_read_b128 v[168:171], v172 offset:2048
	ds_read_b128 v[172:175], v172 offset:3072
	v_lshl_add_u64 v[188:189], s[56:57], 0, v[134:135]
	s_mov_b32 m0, s64
	s_nop 0
	global_load_lds_dwordx4 v[188:189], off
	v_lshl_add_u64 v[188:189], s[56:57], 0, v[132:133]
	s_mov_b32 m0, s65
	s_nop 0
	global_load_lds_dwordx4 v[188:189], off
	v_lshl_add_u64 v[188:189], s[56:57], 0, v[136:137]
	s_add_i32 m0, s27, 0xc000
	s_nop 0
	global_load_lds_dwordx4 v[188:189], off
	v_lshl_add_u64 v[188:189], s[56:57], 0, v[138:139]
	s_add_i32 m0, s27, 0xe000
	s_nop 0
	global_load_lds_dwordx4 v[188:189], off
	ds_read_b128 v[176:179], v147
	ds_read_b128 v[180:183], v147 offset:1024
	ds_read_b128 v[184:187], v147 offset:2048
	ds_read_b128 v[200:203], v147 offset:3072
	ds_read_b128 v[204:207], v147 offset:4096
	ds_read_b128 v[208:211], v147 offset:5120
	ds_read_b128 v[212:215], v147 offset:6144
	ds_read_b128 v[216:219], v147 offset:7168
	s_waitcnt vmcnt(8)
	s_waitcnt lgkmcnt(0)
	s_barrier
	s_setprio 1
	s_waitcnt lgkmcnt(0)
	v_mfma_f32_16x16x32_bf16 v[122:125], v[140:143], v[176:179], v[122:125]
	v_mfma_f32_16x16x32_bf16 v[126:129], v[152:155], v[176:179], v[126:129]
	v_mfma_f32_16x16x32_bf16 v[110:113], v[140:143], v[184:187], v[110:113]
	v_mfma_f32_16x16x32_bf16 v[106:109], v[152:155], v[184:187], v[106:109]
	v_mfma_f32_16x16x32_bf16 v[94:97], v[140:143], v[204:207], v[94:97]
	v_mfma_f32_16x16x32_bf16 v[90:93], v[152:155], v[204:207], v[90:93]
	v_mfma_f32_16x16x32_bf16 v[78:81], v[140:143], v[212:215], v[78:81]
	v_mfma_f32_16x16x32_bf16 v[74:77], v[152:155], v[212:215], v[74:77]
	v_mfma_f32_16x16x32_bf16 v[122:125], v[148:151], v[180:183], v[122:125]
	v_mfma_f32_16x16x32_bf16 v[126:129], v[156:159], v[180:183], v[126:129]
	v_mfma_f32_16x16x32_bf16 v[110:113], v[148:151], v[200:203], v[110:113]
	v_mfma_f32_16x16x32_bf16 v[106:109], v[156:159], v[200:203], v[106:109]
	v_mfma_f32_16x16x32_bf16 v[94:97], v[148:151], v[208:211], v[94:97]
	v_mfma_f32_16x16x32_bf16 v[90:93], v[156:159], v[208:211], v[90:93]
	v_mfma_f32_16x16x32_bf16 v[78:81], v[148:151], v[216:219], v[78:81]
	v_mfma_f32_16x16x32_bf16 v[74:77], v[156:159], v[216:219], v[74:77]
	s_setprio 0
	s_setprio 1
	v_mfma_f32_16x16x32_bf16 v[118:121], v[160:163], v[176:179], v[118:121]
	v_mfma_f32_16x16x32_bf16 v[114:117], v[168:171], v[176:179], v[114:117]
	v_mfma_f32_16x16x32_bf16 v[102:105], v[160:163], v[184:187], v[102:105]
	v_mfma_f32_16x16x32_bf16 v[98:101], v[168:171], v[184:187], v[98:101]
	v_mfma_f32_16x16x32_bf16 v[86:89], v[160:163], v[204:207], v[86:89]
	v_mfma_f32_16x16x32_bf16 v[82:85], v[168:171], v[204:207], v[82:85]
	v_mfma_f32_16x16x32_bf16 v[70:73], v[160:163], v[212:215], v[70:73]
	v_mfma_f32_16x16x32_bf16 v[66:69], v[168:171], v[212:215], v[66:69]
	v_mfma_f32_16x16x32_bf16 v[118:121], v[164:167], v[180:183], v[118:121]
	v_mfma_f32_16x16x32_bf16 v[114:117], v[172:175], v[180:183], v[114:117]
	v_mfma_f32_16x16x32_bf16 v[102:105], v[164:167], v[200:203], v[102:105]
	v_mfma_f32_16x16x32_bf16 v[98:101], v[172:175], v[200:203], v[98:101]
	v_mfma_f32_16x16x32_bf16 v[86:89], v[164:167], v[208:211], v[86:89]
	v_mfma_f32_16x16x32_bf16 v[82:85], v[172:175], v[208:211], v[82:85]
	v_mfma_f32_16x16x32_bf16 v[70:73], v[164:167], v[216:219], v[70:73]
	v_mfma_f32_16x16x32_bf16 v[66:69], v[172:175], v[216:219], v[66:69]
	s_setprio 0
	s_add_i32 s78, s78, s5
	v_lshl_add_u64 v[188:189], s[80:81], 0, v[0:1]
	s_mov_b32 m0, s78
	ds_read_b128 v[176:179], v147 offset:16384
	ds_read_b128 v[180:183], v147 offset:17408
	ds_read_b128 v[184:187], v147 offset:18432
	ds_read_b128 v[200:203], v147 offset:19456
	ds_read_b128 v[204:207], v147 offset:20480
	ds_read_b128 v[208:211], v147 offset:21504
	ds_read_b128 v[212:215], v147 offset:22528
	ds_read_b128 v[216:219], v147 offset:23552
	global_load_lds_dwordx4 v[188:189], off
	s_add_i32 m0, s78, 0x2000
	v_lshl_add_u64 v[220:221], s[80:81], 0, v[130:131]
	s_add_u32 s80, s80, s6
	s_addc_u32 s81, s81, s7
	s_add_i32 s75, s75, s5
	global_load_lds_dwordx4 v[220:221], off
	v_lshl_add_u64 v[222:223], s[80:81], 0, v[0:1]
	s_mov_b32 m0, s75
	v_lshl_add_u64 v[224:225], s[80:81], 0, v[130:131]
	global_load_lds_dwordx4 v[222:223], off
	s_add_i32 m0, s75, 0x2000
	v_lshl_add_u64 v[226:227], s[58:59], 0, v[134:135]
	global_load_lds_dwordx4 v[224:225], off
	v_lshl_add_u64 v[228:229], s[58:59], 0, v[132:133]
	s_waitcnt vmcnt(6)
	s_waitcnt lgkmcnt(0)
	s_barrier
	s_setprio 1
	s_waitcnt lgkmcnt(0)
	v_mfma_f32_16x16x32_bf16 v[62:65], v[140:143], v[176:179], v[62:65]
	v_mfma_f32_16x16x32_bf16 v[58:61], v[152:155], v[176:179], v[58:61]
	v_mfma_f32_16x16x32_bf16 v[46:49], v[140:143], v[184:187], v[46:49]
	v_mfma_f32_16x16x32_bf16 v[42:45], v[152:155], v[184:187], v[42:45]
	v_mfma_f32_16x16x32_bf16 v[30:33], v[140:143], v[204:207], v[30:33]
	v_mfma_f32_16x16x32_bf16 v[26:29], v[152:155], v[204:207], v[26:29]
	v_mfma_f32_16x16x32_bf16 v[14:17], v[140:143], v[212:215], v[14:17]
	v_mfma_f32_16x16x32_bf16 v[10:13], v[152:155], v[212:215], v[10:13]
	v_mfma_f32_16x16x32_bf16 v[62:65], v[148:151], v[180:183], v[62:65]
	v_mfma_f32_16x16x32_bf16 v[58:61], v[156:159], v[180:183], v[58:61]
	v_mfma_f32_16x16x32_bf16 v[46:49], v[148:151], v[200:203], v[46:49]
	v_mfma_f32_16x16x32_bf16 v[42:45], v[156:159], v[200:203], v[42:45]
	v_mfma_f32_16x16x32_bf16 v[30:33], v[148:151], v[208:211], v[30:33]
	v_mfma_f32_16x16x32_bf16 v[26:29], v[156:159], v[208:211], v[26:29]
	v_mfma_f32_16x16x32_bf16 v[14:17], v[148:151], v[216:219], v[14:17]
	v_mfma_f32_16x16x32_bf16 v[10:13], v[156:159], v[216:219], v[10:13]
	s_setprio 0
	s_setprio 1
	v_mfma_f32_16x16x32_bf16 v[54:57], v[160:163], v[176:179], v[54:57]
	v_mfma_f32_16x16x32_bf16 v[50:53], v[168:171], v[176:179], v[50:53]
	v_mfma_f32_16x16x32_bf16 v[38:41], v[160:163], v[184:187], v[38:41]
	v_mfma_f32_16x16x32_bf16 v[34:37], v[168:171], v[184:187], v[34:37]
	v_mfma_f32_16x16x32_bf16 v[22:25], v[160:163], v[204:207], v[22:25]
	v_mfma_f32_16x16x32_bf16 v[18:21], v[168:171], v[204:207], v[18:21]
	v_mfma_f32_16x16x32_bf16 v[6:9], v[160:163], v[212:215], v[6:9]
	v_mfma_f32_16x16x32_bf16 v[2:5], v[168:171], v[212:215], v[2:5]
	v_mfma_f32_16x16x32_bf16 v[54:57], v[164:167], v[180:183], v[54:57]
	v_mfma_f32_16x16x32_bf16 v[50:53], v[172:175], v[180:183], v[50:53]
	v_mfma_f32_16x16x32_bf16 v[38:41], v[164:167], v[200:203], v[38:41]
	v_mfma_f32_16x16x32_bf16 v[34:37], v[172:175], v[200:203], v[34:37]
	v_mfma_f32_16x16x32_bf16 v[22:25], v[164:167], v[208:211], v[22:25]
	v_mfma_f32_16x16x32_bf16 v[18:21], v[172:175], v[208:211], v[18:21]
	v_mfma_f32_16x16x32_bf16 v[6:9], v[164:167], v[216:219], v[6:9]
	v_mfma_f32_16x16x32_bf16 v[2:5], v[172:175], v[216:219], v[2:5]
	s_setprio 0
	s_add_i32 s75, 0, 0x18000
	s_add_i32 s78, 0, 0x1c000
	v_add_u32_e32 v156, s75, v146
	v_add_u32_e32 v172, s78, v146
	ds_read_b128 v[140:143], v156
	ds_read_b128 v[148:151], v156 offset:1024
	ds_read_b128 v[152:155], v156 offset:2048
	ds_read_b128 v[156:159], v156 offset:3072
	ds_read_b128 v[160:163], v172
	ds_read_b128 v[164:167], v172 offset:1024
	ds_read_b128 v[168:171], v172 offset:2048
	ds_read_b128 v[172:175], v172 offset:3072
	s_add_u32 s58, s58, s2
	s_addc_u32 s59, s59, s3
	s_mov_b32 m0, s27
	v_lshl_add_u64 v[230:231], s[58:59], 0, v[134:135]
	s_nop 0
	global_load_lds_dwordx4 v[226:227], off
	s_mov_b32 m0, s30
	s_nop 0
	global_load_lds_dwordx4 v[228:229], off
	s_mov_b32 m0, s31
	s_nop 0
	global_load_lds_dwordx4 v[230:231], off
	v_lshl_add_u64 v[230:231], s[58:59], 0, v[132:133]
	s_mov_b32 m0, s53
	s_nop 0
	global_load_lds_dwordx4 v[230:231], off
	ds_read_b128 v[176:179], v147 offset:32768
	ds_read_b128 v[180:183], v147 offset:33792
	ds_read_b128 v[184:187], v147 offset:34816
	ds_read_b128 v[200:203], v147 offset:35840
	ds_read_b128 v[204:207], v147 offset:36864
	ds_read_b128 v[208:211], v147 offset:37888
	ds_read_b128 v[212:215], v147 offset:38912
	ds_read_b128 v[216:219], v147 offset:39936
	s_waitcnt vmcnt(8)
	s_waitcnt lgkmcnt(0)
	s_barrier
	s_setprio 1
	s_waitcnt lgkmcnt(0)
	v_mfma_f32_16x16x32_bf16 v[122:125], v[140:143], v[176:179], v[122:125]
	v_mfma_f32_16x16x32_bf16 v[126:129], v[152:155], v[176:179], v[126:129]
	v_mfma_f32_16x16x32_bf16 v[110:113], v[140:143], v[184:187], v[110:113]
	v_mfma_f32_16x16x32_bf16 v[106:109], v[152:155], v[184:187], v[106:109]
	v_mfma_f32_16x16x32_bf16 v[94:97], v[140:143], v[204:207], v[94:97]
	v_mfma_f32_16x16x32_bf16 v[90:93], v[152:155], v[204:207], v[90:93]
	v_mfma_f32_16x16x32_bf16 v[78:81], v[140:143], v[212:215], v[78:81]
	v_mfma_f32_16x16x32_bf16 v[74:77], v[152:155], v[212:215], v[74:77]
	v_mfma_f32_16x16x32_bf16 v[122:125], v[148:151], v[180:183], v[122:125]
	v_mfma_f32_16x16x32_bf16 v[126:129], v[156:159], v[180:183], v[126:129]
	v_mfma_f32_16x16x32_bf16 v[110:113], v[148:151], v[200:203], v[110:113]
	v_mfma_f32_16x16x32_bf16 v[106:109], v[156:159], v[200:203], v[106:109]
	v_mfma_f32_16x16x32_bf16 v[94:97], v[148:151], v[208:211], v[94:97]
	v_mfma_f32_16x16x32_bf16 v[90:93], v[156:159], v[208:211], v[90:93]
	v_mfma_f32_16x16x32_bf16 v[78:81], v[148:151], v[216:219], v[78:81]
	v_mfma_f32_16x16x32_bf16 v[74:77], v[156:159], v[216:219], v[74:77]
	s_setprio 0
	s_setprio 1
	v_mfma_f32_16x16x32_bf16 v[118:121], v[160:163], v[176:179], v[118:121]
	v_mfma_f32_16x16x32_bf16 v[114:117], v[168:171], v[176:179], v[114:117]
	v_mfma_f32_16x16x32_bf16 v[102:105], v[160:163], v[184:187], v[102:105]
	v_mfma_f32_16x16x32_bf16 v[98:101], v[168:171], v[184:187], v[98:101]
	v_mfma_f32_16x16x32_bf16 v[86:89], v[160:163], v[204:207], v[86:89]
	v_mfma_f32_16x16x32_bf16 v[82:85], v[168:171], v[204:207], v[82:85]
	v_mfma_f32_16x16x32_bf16 v[70:73], v[160:163], v[212:215], v[70:73]
	v_mfma_f32_16x16x32_bf16 v[66:69], v[168:171], v[212:215], v[66:69]
	v_mfma_f32_16x16x32_bf16 v[118:121], v[164:167], v[180:183], v[118:121]
	v_mfma_f32_16x16x32_bf16 v[114:117], v[172:175], v[180:183], v[114:117]
	v_mfma_f32_16x16x32_bf16 v[102:105], v[164:167], v[200:203], v[102:105]
	v_mfma_f32_16x16x32_bf16 v[98:101], v[172:175], v[200:203], v[98:101]
	v_mfma_f32_16x16x32_bf16 v[86:89], v[164:167], v[208:211], v[86:89]
	v_mfma_f32_16x16x32_bf16 v[82:85], v[172:175], v[208:211], v[82:85]
	v_mfma_f32_16x16x32_bf16 v[70:73], v[164:167], v[216:219], v[70:73]
	v_mfma_f32_16x16x32_bf16 v[66:69], v[172:175], v[216:219], v[66:69]
	s_setprio 0
	s_add_i32 s58, s75, s5
	v_lshl_add_u64 v[188:189], v[188:189], 0, s[24:25]
	s_mov_b32 m0, s58
	ds_read_b128 v[176:179], v147 offset:49152
	ds_read_b128 v[180:183], v147 offset:50176
	ds_read_b128 v[184:187], v147 offset:51200
	ds_read_b128 v[200:203], v147 offset:52224
	ds_read_b128 v[204:207], v147 offset:53248
	ds_read_b128 v[208:211], v147 offset:54272
	ds_read_b128 v[212:215], v147 offset:55296
	ds_read_b128 v[216:219], v147 offset:56320
	global_load_lds_dwordx4 v[188:189], off
	v_lshl_add_u64 v[188:189], v[220:221], 0, s[24:25]
	s_add_i32 m0, s58, 0x2000
	s_add_i32 s58, s78, s5
	global_load_lds_dwordx4 v[188:189], off
	v_lshl_add_u64 v[188:189], v[222:223], 0, s[24:25]
	s_mov_b32 m0, s58
	s_nop 0
	global_load_lds_dwordx4 v[188:189], off
	v_lshl_add_u64 v[188:189], v[224:225], 0, s[24:25]
	s_add_i32 m0, s58, 0x2000
	s_nop 0
	global_load_lds_dwordx4 v[188:189], off
	s_waitcnt vmcnt(6)
	s_waitcnt lgkmcnt(0)
	s_barrier
	s_setprio 1
	s_waitcnt lgkmcnt(0)
	v_mfma_f32_16x16x32_bf16 v[62:65], v[140:143], v[176:179], v[62:65]
	v_mfma_f32_16x16x32_bf16 v[58:61], v[152:155], v[176:179], v[58:61]
	v_mfma_f32_16x16x32_bf16 v[46:49], v[140:143], v[184:187], v[46:49]
	v_mfma_f32_16x16x32_bf16 v[42:45], v[152:155], v[184:187], v[42:45]
	v_mfma_f32_16x16x32_bf16 v[30:33], v[140:143], v[204:207], v[30:33]
	v_mfma_f32_16x16x32_bf16 v[26:29], v[152:155], v[204:207], v[26:29]
	v_mfma_f32_16x16x32_bf16 v[14:17], v[140:143], v[212:215], v[14:17]
	v_mfma_f32_16x16x32_bf16 v[10:13], v[152:155], v[212:215], v[10:13]
	v_mfma_f32_16x16x32_bf16 v[62:65], v[148:151], v[180:183], v[62:65]
	v_mfma_f32_16x16x32_bf16 v[58:61], v[156:159], v[180:183], v[58:61]
	v_mfma_f32_16x16x32_bf16 v[46:49], v[148:151], v[200:203], v[46:49]
	v_mfma_f32_16x16x32_bf16 v[42:45], v[156:159], v[200:203], v[42:45]
	v_mfma_f32_16x16x32_bf16 v[30:33], v[148:151], v[208:211], v[30:33]
	v_mfma_f32_16x16x32_bf16 v[26:29], v[156:159], v[208:211], v[26:29]
	v_mfma_f32_16x16x32_bf16 v[14:17], v[148:151], v[216:219], v[14:17]
	v_mfma_f32_16x16x32_bf16 v[10:13], v[156:159], v[216:219], v[10:13]
	s_setprio 0
	s_setprio 1
	v_mfma_f32_16x16x32_bf16 v[54:57], v[160:163], v[176:179], v[54:57]
	v_mfma_f32_16x16x32_bf16 v[50:53], v[168:171], v[176:179], v[50:53]
	v_mfma_f32_16x16x32_bf16 v[38:41], v[160:163], v[184:187], v[38:41]
	v_mfma_f32_16x16x32_bf16 v[34:37], v[168:171], v[184:187], v[34:37]
	v_mfma_f32_16x16x32_bf16 v[22:25], v[160:163], v[204:207], v[22:25]
	v_mfma_f32_16x16x32_bf16 v[18:21], v[168:171], v[204:207], v[18:21]
	v_mfma_f32_16x16x32_bf16 v[6:9], v[160:163], v[212:215], v[6:9]
	v_mfma_f32_16x16x32_bf16 v[2:5], v[168:171], v[212:215], v[2:5]
	v_mfma_f32_16x16x32_bf16 v[54:57], v[164:167], v[180:183], v[54:57]
	v_mfma_f32_16x16x32_bf16 v[50:53], v[172:175], v[180:183], v[50:53]
	v_mfma_f32_16x16x32_bf16 v[38:41], v[164:167], v[200:203], v[38:41]
	v_mfma_f32_16x16x32_bf16 v[34:37], v[172:175], v[200:203], v[34:37]
	v_mfma_f32_16x16x32_bf16 v[22:25], v[164:167], v[208:211], v[22:25]
	v_mfma_f32_16x16x32_bf16 v[18:21], v[172:175], v[208:211], v[18:21]
	v_mfma_f32_16x16x32_bf16 v[6:9], v[164:167], v[216:219], v[6:9]
	v_mfma_f32_16x16x32_bf16 v[2:5], v[172:175], v[216:219], v[2:5]
	s_setprio 0
	s_add_u32 s56, s56, 0x100
	s_addc_u32 s57, s57, 0
	s_add_u32 s51, s51, 0x100
	s_addc_u32 s55, s55, 0
	s_cmp_ge_i32 s74, s61
	s_mov_b32 s58, s74
	s_cbranch_scc0 .LBB0_230
	s_branch .Lmy_post230
.Lmy_q230:
	s_add_i32 s74, s58, 2
	s_add_u32 s75, s56, 0x80
	s_addc_u32 s59, s57, 0
	s_add_i32 s78, 0, 0x10000
	s_cmp_eq_u32 s66, s58
	s_cselect_b32 s59, s29, s59
	s_cselect_b32 s58, s50, s75
	s_cselect_b32 s81, s45, s55
	s_cselect_b32 s80, s44, s51
	s_add_i32 s75, 0, 0x14000
	v_add_u32_e32 v156, s78, v146
	v_add_u32_e32 v172, s75, v146
	ds_read_b128 v[140:143], v156
	ds_read_b128 v[148:151], v156 offset:1024
	ds_read_b128 v[152:155], v156 offset:2048
	ds_read_b128 v[156:159], v156 offset:3072
	ds_read_b128 v[160:163], v172
	ds_read_b128 v[164:167], v172 offset:1024
	ds_read_b128 v[168:171], v172 offset:2048
	ds_read_b128 v[172:175], v172 offset:3072
	v_lshl_add_u64 v[188:189], s[56:57], 0, v[134:135]
	s_mov_b32 m0, s64
	s_nop 0
	global_load_lds_dwordx4 v[188:189], off
	v_lshl_add_u64 v[188:189], s[56:57], 0, v[132:133]
	s_mov_b32 m0, s65
	s_nop 0
	global_load_lds_dwordx4 v[188:189], off
	v_lshl_add_u64 v[188:189], s[56:57], 0, v[136:137]
	s_add_i32 m0, s27, 0xc000
	s_nop 0
	global_load_lds_dwordx4 v[188:189], off
	v_lshl_add_u64 v[188:189], s[56:57], 0, v[138:139]
	s_add_i32 m0, s27, 0xe000
	s_nop 0
	global_load_lds_dwordx4 v[188:189], off
	ds_read_b128 v[176:179], v147
	ds_read_b128 v[180:183], v147 offset:1024
	ds_read_b128 v[184:187], v147 offset:2048
	ds_read_b128 v[200:203], v147 offset:3072
	ds_read_b128 v[204:207], v147 offset:4096
	ds_read_b128 v[208:211], v147 offset:5120
	ds_read_b128 v[212:215], v147 offset:6144
	ds_read_b128 v[216:219], v147 offset:7168
	s_waitcnt vmcnt(8)
	s_waitcnt lgkmcnt(0)
	s_setprio 1
	s_waitcnt lgkmcnt(0)
	v_mfma_f32_16x16x32_bf16 v[122:125], v[140:143], v[176:179], v[122:125]
	v_mfma_f32_16x16x32_bf16 v[126:129], v[152:155], v[176:179], v[126:129]
	v_mfma_f32_16x16x32_bf16 v[110:113], v[140:143], v[184:187], v[110:113]
	v_mfma_f32_16x16x32_bf16 v[106:109], v[152:155], v[184:187], v[106:109]
	v_mfma_f32_16x16x32_bf16 v[94:97], v[140:143], v[204:207], v[94:97]
	v_mfma_f32_16x16x32_bf16 v[90:93], v[152:155], v[204:207], v[90:93]
	v_mfma_f32_16x16x32_bf16 v[78:81], v[140:143], v[212:215], v[78:81]
	v_mfma_f32_16x16x32_bf16 v[74:77], v[152:155], v[212:215], v[74:77]
	v_mfma_f32_16x16x32_bf16 v[122:125], v[148:151], v[180:183], v[122:125]
	v_mfma_f32_16x16x32_bf16 v[126:129], v[156:159], v[180:183], v[126:129]
	v_mfma_f32_16x16x32_bf16 v[110:113], v[148:151], v[200:203], v[110:113]
	v_mfma_f32_16x16x32_bf16 v[106:109], v[156:159], v[200:203], v[106:109]
	v_mfma_f32_16x16x32_bf16 v[94:97], v[148:151], v[208:211], v[94:97]
	v_mfma_f32_16x16x32_bf16 v[90:93], v[156:159], v[208:211], v[90:93]
	v_mfma_f32_16x16x32_bf16 v[78:81], v[148:151], v[216:219], v[78:81]
	v_mfma_f32_16x16x32_bf16 v[74:77], v[156:159], v[216:219], v[74:77]
	s_setprio 0
	s_setprio 1
	v_mfma_f32_16x16x32_bf16 v[118:121], v[160:163], v[176:179], v[118:121]
	v_mfma_f32_16x16x32_bf16 v[114:117], v[168:171], v[176:179], v[114:117]
	v_mfma_f32_16x16x32_bf16 v[102:105], v[160:163], v[184:187], v[102:105]
	v_mfma_f32_16x16x32_bf16 v[98:101], v[168:171], v[184:187], v[98:101]
	v_mfma_f32_16x16x32_bf16 v[86:89], v[160:163], v[204:207], v[86:89]
	v_mfma_f32_16x16x32_bf16 v[82:85], v[168:171], v[204:207], v[82:85]
	v_mfma_f32_16x16x32_bf16 v[70:73], v[160:163], v[212:215], v[70:73]
	v_mfma_f32_16x16x32_bf16 v[66:69], v[168:171], v[212:215], v[66:69]
	v_mfma_f32_16x16x32_bf16 v[118:121], v[164:167], v[180:183], v[118:121]
	v_mfma_f32_16x16x32_bf16 v[114:117], v[172:175], v[180:183], v[114:117]
	v_mfma_f32_16x16x32_bf16 v[102:105], v[164:167], v[200:203], v[102:105]
	v_mfma_f32_16x16x32_bf16 v[98:101], v[172:175], v[200:203], v[98:101]
	v_mfma_f32_16x16x32_bf16 v[86:89], v[164:167], v[208:211], v[86:89]
	v_mfma_f32_16x16x32_bf16 v[82:85], v[172:175], v[208:211], v[82:85]
	v_mfma_f32_16x16x32_bf16 v[70:73], v[164:167], v[216:219], v[70:73]
	v_mfma_f32_16x16x32_bf16 v[66:69], v[172:175], v[216:219], v[66:69]
	s_setprio 0
	s_barrier
	s_add_i32 s78, s78, s5
	v_lshl_add_u64 v[188:189], s[80:81], 0, v[0:1]
	s_mov_b32 m0, s78
	ds_read_b128 v[176:179], v147 offset:16384
	ds_read_b128 v[180:183], v147 offset:17408
	ds_read_b128 v[184:187], v147 offset:18432
	ds_read_b128 v[200:203], v147 offset:19456
	ds_read_b128 v[204:207], v147 offset:20480
	ds_read_b128 v[208:211], v147 offset:21504
	ds_read_b128 v[212:215], v147 offset:22528
	ds_read_b128 v[216:219], v147 offset:23552
	global_load_lds_dwordx4 v[188:189], off
	s_add_i32 m0, s78, 0x2000
	v_lshl_add_u64 v[220:221], s[80:81], 0, v[130:131]
	s_add_u32 s80, s80, s6
	s_addc_u32 s81, s81, s7
	s_add_i32 s75, s75, s5
	global_load_lds_dwordx4 v[220:221], off
	v_lshl_add_u64 v[222:223], s[80:81], 0, v[0:1]
	s_mov_b32 m0, s75
	v_lshl_add_u64 v[224:225], s[80:81], 0, v[130:131]
	global_load_lds_dwordx4 v[222:223], off
	s_add_i32 m0, s75, 0x2000
	v_lshl_add_u64 v[226:227], s[58:59], 0, v[134:135]
	global_load_lds_dwordx4 v[224:225], off
	v_lshl_add_u64 v[228:229], s[58:59], 0, v[132:133]
	s_waitcnt vmcnt(6)
	s_waitcnt lgkmcnt(0)
	s_setprio 1
	s_waitcnt lgkmcnt(0)
	v_mfma_f32_16x16x32_bf16 v[62:65], v[140:143], v[176:179], v[62:65]
	v_mfma_f32_16x16x32_bf16 v[58:61], v[152:155], v[176:179], v[58:61]
	v_mfma_f32_16x16x32_bf16 v[46:49], v[140:143], v[184:187], v[46:49]
	v_mfma_f32_16x16x32_bf16 v[42:45], v[152:155], v[184:187], v[42:45]
	v_mfma_f32_16x16x32_bf16 v[30:33], v[140:143], v[204:207], v[30:33]
	v_mfma_f32_16x16x32_bf16 v[26:29], v[152:155], v[204:207], v[26:29]
	v_mfma_f32_16x16x32_bf16 v[14:17], v[140:143], v[212:215], v[14:17]
	v_mfma_f32_16x16x32_bf16 v[10:13], v[152:155], v[212:215], v[10:13]
	v_mfma_f32_16x16x32_bf16 v[62:65], v[148:151], v[180:183], v[62:65]
	v_mfma_f32_16x16x32_bf16 v[58:61], v[156:159], v[180:183], v[58:61]
	v_mfma_f32_16x16x32_bf16 v[46:49], v[148:151], v[200:203], v[46:49]
	v_mfma_f32_16x16x32_bf16 v[42:45], v[156:159], v[200:203], v[42:45]
	v_mfma_f32_16x16x32_bf16 v[30:33], v[148:151], v[208:211], v[30:33]
	v_mfma_f32_16x16x32_bf16 v[26:29], v[156:159], v[208:211], v[26:29]
	v_mfma_f32_16x16x32_bf16 v[14:17], v[148:151], v[216:219], v[14:17]
	v_mfma_f32_16x16x32_bf16 v[10:13], v[156:159], v[216:219], v[10:13]
	s_setprio 0
	s_setprio 1
	v_mfma_f32_16x16x32_bf16 v[54:57], v[160:163], v[176:179], v[54:57]
	v_mfma_f32_16x16x32_bf16 v[50:53], v[168:171], v[176:179], v[50:53]
	v_mfma_f32_16x16x32_bf16 v[38:41], v[160:163], v[184:187], v[38:41]
	v_mfma_f32_16x16x32_bf16 v[34:37], v[168:171], v[184:187], v[34:37]
	v_mfma_f32_16x16x32_bf16 v[22:25], v[160:163], v[204:207], v[22:25]
	v_mfma_f32_16x16x32_bf16 v[18:21], v[168:171], v[204:207], v[18:21]
	v_mfma_f32_16x16x32_bf16 v[6:9], v[160:163], v[212:215], v[6:9]
	v_mfma_f32_16x16x32_bf16 v[2:5], v[168:171], v[212:215], v[2:5]
	v_mfma_f32_16x16x32_bf16 v[54:57], v[164:167], v[180:183], v[54:57]
	v_mfma_f32_16x16x32_bf16 v[50:53], v[172:175], v[180:183], v[50:53]
	v_mfma_f32_16x16x32_bf16 v[38:41], v[164:167], v[200:203], v[38:41]
	v_mfma_f32_16x16x32_bf16 v[34:37], v[172:175], v[200:203], v[34:37]
	v_mfma_f32_16x16x32_bf16 v[22:25], v[164:167], v[208:211], v[22:25]
	v_mfma_f32_16x16x32_bf16 v[18:21], v[172:175], v[208:211], v[18:21]
	v_mfma_f32_16x16x32_bf16 v[6:9], v[164:167], v[216:219], v[6:9]
	v_mfma_f32_16x16x32_bf16 v[2:5], v[172:175], v[216:219], v[2:5]
	s_setprio 0
	s_barrier
	s_add_i32 s75, 0, 0x18000
	s_add_i32 s78, 0, 0x1c000
	v_add_u32_e32 v156, s75, v146
	v_add_u32_e32 v172, s78, v146
	ds_read_b128 v[140:143], v156
	ds_read_b128 v[148:151], v156 offset:1024
	ds_read_b128 v[152:155], v156 offset:2048
	ds_read_b128 v[156:159], v156 offset:3072
	ds_read_b128 v[160:163], v172
	ds_read_b128 v[164:167], v172 offset:1024
	ds_read_b128 v[168:171], v172 offset:2048
	ds_read_b128 v[172:175], v172 offset:3072
	s_add_u32 s58, s58, s2
	s_addc_u32 s59, s59, s3
	s_mov_b32 m0, s27
	v_lshl_add_u64 v[230:231], s[58:59], 0, v[134:135]
	s_nop 0
	global_load_lds_dwordx4 v[226:227], off
	s_mov_b32 m0, s30
	s_nop 0
	global_load_lds_dwordx4 v[228:229], off
	s_mov_b32 m0, s31
	s_nop 0
	global_load_lds_dwordx4 v[230:231], off
	v_lshl_add_u64 v[230:231], s[58:59], 0, v[132:133]
	s_mov_b32 m0, s53
	s_nop 0
	global_load_lds_dwordx4 v[230:231], off
	ds_read_b128 v[176:179], v147 offset:32768
	ds_read_b128 v[180:183], v147 offset:33792
	ds_read_b128 v[184:187], v147 offset:34816
	ds_read_b128 v[200:203], v147 offset:35840
	ds_read_b128 v[204:207], v147 offset:36864
	ds_read_b128 v[208:211], v147 offset:37888
	ds_read_b128 v[212:215], v147 offset:38912
	ds_read_b128 v[216:219], v147 offset:39936
	s_waitcnt vmcnt(8)
	s_waitcnt lgkmcnt(0)
	s_setprio 1
	s_waitcnt lgkmcnt(0)
	v_mfma_f32_16x16x32_bf16 v[122:125], v[140:143], v[176:179], v[122:125]
	v_mfma_f32_16x16x32_bf16 v[126:129], v[152:155], v[176:179], v[126:129]
	v_mfma_f32_16x16x32_bf16 v[110:113], v[140:143], v[184:187], v[110:113]
	v_mfma_f32_16x16x32_bf16 v[106:109], v[152:155], v[184:187], v[106:109]
	v_mfma_f32_16x16x32_bf16 v[94:97], v[140:143], v[204:207], v[94:97]
	v_mfma_f32_16x16x32_bf16 v[90:93], v[152:155], v[204:207], v[90:93]
	v_mfma_f32_16x16x32_bf16 v[78:81], v[140:143], v[212:215], v[78:81]
	v_mfma_f32_16x16x32_bf16 v[74:77], v[152:155], v[212:215], v[74:77]
	v_mfma_f32_16x16x32_bf16 v[122:125], v[148:151], v[180:183], v[122:125]
	v_mfma_f32_16x16x32_bf16 v[126:129], v[156:159], v[180:183], v[126:129]
	v_mfma_f32_16x16x32_bf16 v[110:113], v[148:151], v[200:203], v[110:113]
	v_mfma_f32_16x16x32_bf16 v[106:109], v[156:159], v[200:203], v[106:109]
	v_mfma_f32_16x16x32_bf16 v[94:97], v[148:151], v[208:211], v[94:97]
	v_mfma_f32_16x16x32_bf16 v[90:93], v[156:159], v[208:211], v[90:93]
	v_mfma_f32_16x16x32_bf16 v[78:81], v[148:151], v[216:219], v[78:81]
	v_mfma_f32_16x16x32_bf16 v[74:77], v[156:159], v[216:219], v[74:77]
	s_setprio 0
	s_setprio 1
	v_mfma_f32_16x16x32_bf16 v[118:121], v[160:163], v[176:179], v[118:121]
	v_mfma_f32_16x16x32_bf16 v[114:117], v[168:171], v[176:179], v[114:117]
	v_mfma_f32_16x16x32_bf16 v[102:105], v[160:163], v[184:187], v[102:105]
	v_mfma_f32_16x16x32_bf16 v[98:101], v[168:171], v[184:187], v[98:101]
	v_mfma_f32_16x16x32_bf16 v[86:89], v[160:163], v[204:207], v[86:89]
	v_mfma_f32_16x16x32_bf16 v[82:85], v[168:171], v[204:207], v[82:85]
	v_mfma_f32_16x16x32_bf16 v[70:73], v[160:163], v[212:215], v[70:73]
	v_mfma_f32_16x16x32_bf16 v[66:69], v[168:171], v[212:215], v[66:69]
	v_mfma_f32_16x16x32_bf16 v[118:121], v[164:167], v[180:183], v[118:121]
	v_mfma_f32_16x16x32_bf16 v[114:117], v[172:175], v[180:183], v[114:117]
	v_mfma_f32_16x16x32_bf16 v[102:105], v[164:167], v[200:203], v[102:105]
	v_mfma_f32_16x16x32_bf16 v[98:101], v[172:175], v[200:203], v[98:101]
	v_mfma_f32_16x16x32_bf16 v[86:89], v[164:167], v[208:211], v[86:89]
	v_mfma_f32_16x16x32_bf16 v[82:85], v[172:175], v[208:211], v[82:85]
	v_mfma_f32_16x16x32_bf16 v[70:73], v[164:167], v[216:219], v[70:73]
	v_mfma_f32_16x16x32_bf16 v[66:69], v[172:175], v[216:219], v[66:69]
	s_setprio 0
	s_barrier
	s_add_i32 s58, s75, s5
	v_lshl_add_u64 v[188:189], v[188:189], 0, s[24:25]
	s_mov_b32 m0, s58
	ds_read_b128 v[176:179], v147 offset:49152
	ds_read_b128 v[180:183], v147 offset:50176
	ds_read_b128 v[184:187], v147 offset:51200
	ds_read_b128 v[200:203], v147 offset:52224
	ds_read_b128 v[204:207], v147 offset:53248
	ds_read_b128 v[208:211], v147 offset:54272
	ds_read_b128 v[212:215], v147 offset:55296
	ds_read_b128 v[216:219], v147 offset:56320
	global_load_lds_dwordx4 v[188:189], off
	v_lshl_add_u64 v[188:189], v[220:221], 0, s[24:25]
	s_add_i32 m0, s58, 0x2000
	s_add_i32 s58, s78, s5
	global_load_lds_dwordx4 v[188:189], off
	v_lshl_add_u64 v[188:189], v[222:223], 0, s[24:25]
	s_mov_b32 m0, s58
	s_nop 0
	global_load_lds_dwordx4 v[188:189], off
	v_lshl_add_u64 v[188:189], v[224:225], 0, s[24:25]
	s_add_i32 m0, s58, 0x2000
	s_nop 0
	global_load_lds_dwordx4 v[188:189], off
	s_waitcnt vmcnt(6)
	s_waitcnt lgkmcnt(0)
	s_setprio 1
	s_waitcnt lgkmcnt(0)
	v_mfma_f32_16x16x32_bf16 v[62:65], v[140:143], v[176:179], v[62:65]
	v_mfma_f32_16x16x32_bf16 v[58:61], v[152:155], v[176:179], v[58:61]
	v_mfma_f32_16x16x32_bf16 v[46:49], v[140:143], v[184:187], v[46:49]
	v_mfma_f32_16x16x32_bf16 v[42:45], v[152:155], v[184:187], v[42:45]
	v_mfma_f32_16x16x32_bf16 v[30:33], v[140:143], v[204:207], v[30:33]
	v_mfma_f32_16x16x32_bf16 v[26:29], v[152:155], v[204:207], v[26:29]
	v_mfma_f32_16x16x32_bf16 v[14:17], v[140:143], v[212:215], v[14:17]
	v_mfma_f32_16x16x32_bf16 v[10:13], v[152:155], v[212:215], v[10:13]
	v_mfma_f32_16x16x32_bf16 v[62:65], v[148:151], v[180:183], v[62:65]
	v_mfma_f32_16x16x32_bf16 v[58:61], v[156:159], v[180:183], v[58:61]
	v_mfma_f32_16x16x32_bf16 v[46:49], v[148:151], v[200:203], v[46:49]
	v_mfma_f32_16x16x32_bf16 v[42:45], v[156:159], v[200:203], v[42:45]
	v_mfma_f32_16x16x32_bf16 v[30:33], v[148:151], v[208:211], v[30:33]
	v_mfma_f32_16x16x32_bf16 v[26:29], v[156:159], v[208:211], v[26:29]
	v_mfma_f32_16x16x32_bf16 v[14:17], v[148:151], v[216:219], v[14:17]
	v_mfma_f32_16x16x32_bf16 v[10:13], v[156:159], v[216:219], v[10:13]
	s_setprio 0
	s_setprio 1
	v_mfma_f32_16x16x32_bf16 v[54:57], v[160:163], v[176:179], v[54:57]
	v_mfma_f32_16x16x32_bf16 v[50:53], v[168:171], v[176:179], v[50:53]
	v_mfma_f32_16x16x32_bf16 v[38:41], v[160:163], v[184:187], v[38:41]
	v_mfma_f32_16x16x32_bf16 v[34:37], v[168:171], v[184:187], v[34:37]
	v_mfma_f32_16x16x32_bf16 v[22:25], v[160:163], v[204:207], v[22:25]
	v_mfma_f32_16x16x32_bf16 v[18:21], v[168:171], v[204:207], v[18:21]
	v_mfma_f32_16x16x32_bf16 v[6:9], v[160:163], v[212:215], v[6:9]
	v_mfma_f32_16x16x32_bf16 v[2:5], v[168:171], v[212:215], v[2:5]
	v_mfma_f32_16x16x32_bf16 v[54:57], v[164:167], v[180:183], v[54:57]
	v_mfma_f32_16x16x32_bf16 v[50:53], v[172:175], v[180:183], v[50:53]
	v_mfma_f32_16x16x32_bf16 v[38:41], v[164:167], v[200:203], v[38:41]
	v_mfma_f32_16x16x32_bf16 v[34:37], v[172:175], v[200:203], v[34:37]
	v_mfma_f32_16x16x32_bf16 v[22:25], v[164:167], v[208:211], v[22:25]
	v_mfma_f32_16x16x32_bf16 v[18:21], v[172:175], v[208:211], v[18:21]
	v_mfma_f32_16x16x32_bf16 v[6:9], v[164:167], v[216:219], v[6:9]
	v_mfma_f32_16x16x32_bf16 v[2:5], v[172:175], v[216:219], v[2:5]
	s_setprio 0
	s_barrier
	s_add_u32 s56, s56, 0x100
	s_addc_u32 s57, s57, 0
	s_add_u32 s51, s51, 0x100
	s_addc_u32 s55, s55, 0
	s_cmp_ge_i32 s74, s61
	s_mov_b32 s58, s74
	s_cbranch_scc0 .Lmy_q230

.LBB0_255:
	s_and_b64 vcc, exec, s[2:3]
	s_cbranch_vccz .LBB0_353
	v_readlane_b32 s2, v237, 13
	v_mov_b32_e32 v8, v190
	v_readlane_b32 s3, v237, 14
	s_movk_i32 s42, 0x1000
	v_readfirstlane_b32 s5, v8
	s_movk_i32 s38, 0x1000
	s_andn2_b64 vcc, exec, s[2:3]
	s_cbranch_vccnz .LBB0_353
	v_lshlrev_b32_e32 v0, 4, v8
	v_add_u32_e32 v2, 0x2000, v0
	s_waitcnt lgkmcnt(0)
	v_ashrrev_i32_e32 v3, 31, v2
	v_lshrrev_b32_e32 v3, 22, v3
	v_add_u32_e32 v3, v2, v3
	v_ashrrev_i32_e32 v3, 10, v3
	v_mul_i32_i24_e32 v4, 0x400, v3
	v_sub_u32_e32 v2, v2, v4
	v_lshrrev_b32_e32 v4, 4, v2
	v_bitop3_b32 v4, v4, v2, 32 bitop3:0x6c
	v_ashrrev_i32_e32 v2, 31, v4
	v_lshrrev_b32_e32 v2, 26, v2
	v_add_u32_e32 v5, v4, v2
	v_lshlrev_b32_e32 v6, 3, v3
	v_ashrrev_i32_e32 v2, 6, v5
	v_and_b32_e32 v6, -16, v6
	s_lshl_b32 s4, s97, 3
	v_readlane_b32 s30, v236, 12
	v_add_u32_e32 v6, v2, v6
	s_or_b32 s54, s4, s30
	v_and_b32_e32 v2, 3, v2
	s_mov_b32 s30, 0x7fffffe0
	v_lshrrev_b32_e32 v7, 2, v6
	v_lshlrev_b32_e32 v9, 1, v6
	v_and_or_b32 v2, v6, s30, v2
	v_and_b32_e32 v7, 4, v7
	v_and_b32_e32 v9, 24, v9
	v_or3_b32 v2, v2, v7, v9
	v_mul_lo_u32 v7, v2, s42
	v_lshlrev_b32_e32 v2, 5, v3
	v_and_b32_e32 v3, 0xc0, v5
	v_sub_u32_e32 v3, v4, v3
	v_ashrrev_i16_sdwa v3, v193, sext(v3) dst_sel:DWORD dst_unused:UNUSED_PAD src0_sel:DWORD src1_sel:BYTE_0
	v_and_b32_e32 v2, 32, v2
	v_bfe_i32 v3, v3, 0, 16
	v_add_u32_e32 v5, v2, v3
	v_mul_lo_u32 v4, v6, s38
	v_add_lshl_u32 v130, v7, v5, 1
	v_add_lshl_u32 v132, v5, v4, 1
	v_bfe_i32 v5, v8, 27, 1
	v_lshrrev_b32_e32 v5, 22, v5
	v_add_u32_e32 v5, v0, v5
	v_and_b32_e32 v5, 0xfffffc00, v5
	v_sub_u32_e32 v0, v0, v5
	v_lshrrev_b32_e32 v5, 4, v0
	v_ashrrev_i32_e32 v7, 31, v8
	v_bitop3_b32 v0, v5, v0, 32 bitop3:0x6c
	v_lshrrev_b32_e32 v7, 26, v7
	v_ashrrev_i32_e32 v5, 31, v0
	v_add_u32_e32 v7, v8, v7
	v_lshrrev_b32_e32 v5, 26, v5
	v_ashrrev_i32_e32 v7, 6, v7
	v_add_u32_e32 v6, v0, v5
	v_lshlrev_b32_e32 v9, 3, v7
	s_ashr_i32 s43, s42, 31
	v_ashrrev_i32_e32 v5, 6, v6
	v_and_b32_e32 v9, -16, v9
	v_readlane_b32 s44, v236, 24
	s_lshl_b64 s[34:35], s[42:43], 9
	v_add_u32_e32 v9, v5, v9
	v_and_b32_e32 v5, 3, v5
	v_readlane_b32 s45, v236, 25
	v_and_or_b32 v5, v9, s30, v5
	v_lshrrev_b32_e32 v10, 2, v9
	s_waitcnt vmcnt(0)
	v_lshlrev_b32_e32 v11, 1, v9
	s_mul_i32 s30, s34, s45
	s_mul_hi_u32 s31, s34, s44
	v_and_b32_e32 v10, 4, v10
	v_and_b32_e32 v11, 24, v11
	v_and_b32_e32 v6, 0xc0, v6
	s_add_i32 s40, s31, s30
	s_lshr_b64 s[30:31], s[42:43], 23
	s_ashr_i32 s29, s5, 6
	s_ashr_i32 s39, s38, 31
	v_or3_b32 v5, v5, v10, v11
	v_sub_u32_e32 v0, v0, v6
	s_ashr_i32 s55, s54, 31
	s_mul_i32 s30, s30, s44
	s_ashr_i32 s28, s5, 8
	s_lshl_b64 s[2:3], s[38:39], 8
	s_lshl_b64 s[6:7], s[42:43], 8
	s_lshl_b32 s27, s29, 10
	v_mul_lo_u32 v10, v5, s42
	v_lshlrev_b32_e32 v5, 5, v7
	v_ashrrev_i16_sdwa v0, v193, sext(v0) dst_sel:DWORD dst_unused:UNUSED_PAD src0_sel:DWORD src1_sel:BYTE_0
	v_mul_lo_u32 v7, v9, s38
	s_lshl_b64 s[38:39], s[54:55], 21
	s_add_i32 s40, s40, s30
	s_mul_i32 s30, s34, s44
	v_readlane_b32 s31, v235, 17
	v_and_b32_e32 v5, 32, v5
	v_bfe_i32 v6, v0, 0, 16
	s_add_u32 s58, s31, s30
	v_readlane_b32 s30, v235, 18
	v_add_u32_e32 v11, v5, v6
	s_addc_u32 s59, s30, s40
	s_add_i32 s30, s27, 0
	v_add_lshl_u32 v0, v10, v11, 1
	s_add_i32 m0, s30, 0x10000
	v_readlane_b32 s31, v236, 59
	global_load_lds_dwordx4 v0, s[58:59]
	s_add_i32 m0, s30, 0x12000
	s_add_u32 s40, s58, s6
	global_load_lds_dwordx4 v130, s[58:59]
	s_addc_u32 s41, s59, s7
	s_add_i32 m0, s30, 0x14000
	v_add_lshl_u32 v134, v11, v7, 1
	global_load_lds_dwordx4 v0, s[40:41]
	s_add_i32 m0, s30, 0x16000
	s_add_u32 s56, s31, s38
	v_readlane_b32 s31, v236, 56
	s_addc_u32 s57, s31, s39
	s_add_i32 s31, s30, 0x2000
	global_load_lds_dwordx4 v130, s[40:41]
	s_mov_b32 m0, s30
	s_add_u32 s38, s56, s2
	global_load_lds_dwordx4 v134, s[56:57]
	s_mov_b32 m0, s31
	s_addc_u32 s39, s57, s3
	s_add_i32 s53, s30, 0x4000
	global_load_lds_dwordx4 v132, s[56:57]
	s_mov_b32 m0, s53
	s_add_i32 s72, s30, 0x6000
	global_load_lds_dwordx4 v134, s[38:39]
	s_mov_b32 m0, s72
	s_cmp_eq_u32 s28, 1
	global_load_lds_dwordx4 v132, s[38:39]
	s_cselect_b64 s[38:39], -1, 0
	v_writelane_b32 v234, s38, 9
	s_cmp_lg_u32 s28, 1
	s_nop 0
	v_writelane_b32 v234, s39, 10
	s_cbranch_scc1 .LBB0_259
	s_nop 0

.LBB0_264:
	s_and_b32 s5, s5, 7
	s_or_b32 s5, s5, s4
	s_and_b64 s[46:47], s[48:49], exec
	s_cselect_b32 s46, s5, s29
	s_ashr_i32 s47, s46, 31
	s_lshl_b64 s[46:47], s[46:47], 21
	v_readlane_b32 s29, v236, 59
	s_add_u32 s46, s29, s46
	v_readlane_b32 s29, v236, 56
	v_mov_b32_e32 v125, 0
	s_addc_u32 s47, s29, s47
	s_andn2_b64 vcc, exec, s[42:43]
	v_mov_b32_e32 v124, v125
	v_mov_b32_e32 v123, v125
	v_mov_b32_e32 v122, v125
	v_mov_b32_e32 v129, v125
	v_mov_b32_e32 v128, v125
	v_mov_b32_e32 v127, v125
	v_mov_b32_e32 v126, v125
	v_mov_b32_e32 v113, v125
	v_mov_b32_e32 v112, v125
	v_mov_b32_e32 v111, v125
	v_mov_b32_e32 v110, v125
	v_mov_b32_e32 v109, v125
	v_mov_b32_e32 v108, v125
	v_mov_b32_e32 v107, v125
	v_mov_b32_e32 v106, v125
	v_mov_b32_e32 v97, v125
	v_mov_b32_e32 v96, v125
	v_mov_b32_e32 v95, v125
	v_mov_b32_e32 v94, v125
	v_mov_b32_e32 v93, v125
	v_mov_b32_e32 v92, v125
	v_mov_b32_e32 v91, v125
	v_mov_b32_e32 v90, v125
	v_mov_b32_e32 v81, v125
	v_mov_b32_e32 v80, v125
	v_mov_b32_e32 v79, v125
	v_mov_b32_e32 v78, v125
	v_mov_b32_e32 v77, v125
	v_mov_b32_e32 v76, v125
	v_mov_b32_e32 v75, v125
	v_mov_b32_e32 v74, v125
	v_mov_b32_e32 v121, v125
	v_mov_b32_e32 v120, v125
	v_mov_b32_e32 v119, v125
	v_mov_b32_e32 v118, v125
	v_mov_b32_e32 v117, v125
	v_mov_b32_e32 v116, v125
	v_mov_b32_e32 v115, v125
	v_mov_b32_e32 v114, v125
	v_mov_b32_e32 v105, v125
	v_mov_b32_e32 v104, v125
	v_mov_b32_e32 v103, v125
	v_mov_b32_e32 v102, v125
	v_mov_b32_e32 v101, v125
	v_mov_b32_e32 v100, v125
	v_mov_b32_e32 v99, v125
	v_mov_b32_e32 v98, v125
	v_mov_b32_e32 v89, v125
	v_mov_b32_e32 v88, v125
	v_mov_b32_e32 v87, v125
	v_mov_b32_e32 v86, v125
	v_mov_b32_e32 v85, v125
	v_mov_b32_e32 v84, v125
	v_mov_b32_e32 v83, v125
	v_mov_b32_e32 v82, v125
	v_mov_b32_e32 v73, v125
	v_mov_b32_e32 v72, v125
	v_mov_b32_e32 v71, v125
	v_mov_b32_e32 v70, v125
	v_mov_b32_e32 v69, v125
	v_mov_b32_e32 v68, v125
	v_mov_b32_e32 v67, v125
	v_mov_b32_e32 v66, v125
	v_mov_b32_e32 v65, v125
	v_mov_b32_e32 v64, v125
	v_mov_b32_e32 v63, v125
	v_mov_b32_e32 v62, v125
	v_mov_b32_e32 v61, v125
	v_mov_b32_e32 v60, v125
	v_mov_b32_e32 v59, v125
	v_mov_b32_e32 v58, v125
	v_mov_b32_e32 v49, v125
	v_mov_b32_e32 v48, v125
	v_mov_b32_e32 v47, v125
	v_mov_b32_e32 v46, v125
	v_mov_b32_e32 v45, v125
	v_mov_b32_e32 v44, v125
	v_mov_b32_e32 v43, v125
	v_mov_b32_e32 v42, v125
	v_mov_b32_e32 v33, v125
	v_mov_b32_e32 v32, v125
	v_mov_b32_e32 v31, v125
	v_mov_b32_e32 v30, v125
	v_mov_b32_e32 v29, v125
	v_mov_b32_e32 v28, v125
	v_mov_b32_e32 v27, v125
	v_mov_b32_e32 v26, v125
	v_mov_b32_e32 v17, v125
	v_mov_b32_e32 v16, v125
	v_mov_b32_e32 v15, v125
	v_mov_b32_e32 v14, v125
	v_mov_b32_e32 v13, v125
	v_mov_b32_e32 v12, v125
	v_mov_b32_e32 v11, v125
	v_mov_b32_e32 v10, v125
	v_mov_b32_e32 v57, v125
	v_mov_b32_e32 v56, v125
	v_mov_b32_e32 v55, v125
	v_mov_b32_e32 v54, v125
	v_mov_b32_e32 v53, v125
	v_mov_b32_e32 v52, v125
	v_mov_b32_e32 v51, v125
	v_mov_b32_e32 v50, v125
	v_mov_b32_e32 v41, v125
	v_mov_b32_e32 v40, v125
	v_mov_b32_e32 v39, v125
	v_mov_b32_e32 v38, v125
	v_mov_b32_e32 v37, v125
	v_mov_b32_e32 v36, v125
	v_mov_b32_e32 v35, v125
	v_mov_b32_e32 v34, v125
	v_mov_b32_e32 v25, v125
	v_mov_b32_e32 v24, v125
	v_mov_b32_e32 v23, v125
	v_mov_b32_e32 v22, v125
	v_mov_b32_e32 v21, v125
	v_mov_b32_e32 v20, v125
	v_mov_b32_e32 v19, v125
	v_mov_b32_e32 v18, v125
	v_mov_b32_e32 v9, v125
	v_mov_b32_e32 v8, v125
	v_mov_b32_e32 v7, v125
	v_mov_b32_e32 v6, v125
	v_mov_b32_e32 v5, v125
	v_mov_b32_e32 v4, v125
	v_mov_b32_e32 v3, v125
	v_mov_b32_e32 v2, v125
	s_cbranch_vccnz .LBB0_267
	s_and_b64 s[50:51], s[48:49], exec
	s_cselect_b32 s29, s47, s57
	s_cselect_b32 s50, s46, s56
	s_add_u32 s56, s56, 0x80
	s_addc_u32 s57, s57, 0
	s_add_u32 s51, s58, 0x100
	v_mov_b32_e32 v2, 0
	s_addc_u32 s55, s59, 0
	s_mov_b32 s58, 0
	v_mov_b32_e32 v3, v2
	v_mov_b32_e32 v4, v2
	v_mov_b32_e32 v5, v2
	v_mov_b32_e32 v6, v2
	v_mov_b32_e32 v7, v2
	v_mov_b32_e32 v8, v2
	v_mov_b32_e32 v9, v2
	v_mov_b32_e32 v18, v2
	v_mov_b32_e32 v19, v2
	v_mov_b32_e32 v20, v2
	v_mov_b32_e32 v21, v2
	v_mov_b32_e32 v22, v2
	v_mov_b32_e32 v23, v2
	v_mov_b32_e32 v24, v2
	v_mov_b32_e32 v25, v2
	v_mov_b32_e32 v34, v2
	v_mov_b32_e32 v35, v2
	v_mov_b32_e32 v36, v2
	v_mov_b32_e32 v37, v2
	v_mov_b32_e32 v38, v2
	v_mov_b32_e32 v39, v2
	v_mov_b32_e32 v40, v2
	v_mov_b32_e32 v41, v2
	v_mov_b32_e32 v50, v2
	v_mov_b32_e32 v51, v2
	v_mov_b32_e32 v52, v2
	v_mov_b32_e32 v53, v2
	v_mov_b32_e32 v54, v2
	v_mov_b32_e32 v55, v2
	v_mov_b32_e32 v56, v2
	v_mov_b32_e32 v57, v2
	v_mov_b32_e32 v10, v2
	v_mov_b32_e32 v11, v2
	v_mov_b32_e32 v12, v2
	v_mov_b32_e32 v13, v2
	v_mov_b32_e32 v14, v2
	v_mov_b32_e32 v15, v2
	v_mov_b32_e32 v16, v2
	v_mov_b32_e32 v17, v2
	v_mov_b32_e32 v26, v2
	v_mov_b32_e32 v27, v2
	v_mov_b32_e32 v28, v2
	v_mov_b32_e32 v29, v2
	v_mov_b32_e32 v30, v2
	v_mov_b32_e32 v31, v2
	v_mov_b32_e32 v32, v2
	v_mov_b32_e32 v33, v2
	v_mov_b32_e32 v42, v2
	v_mov_b32_e32 v43, v2
	v_mov_b32_e32 v44, v2
	v_mov_b32_e32 v45, v2
	v_mov_b32_e32 v46, v2
	v_mov_b32_e32 v47, v2
	v_mov_b32_e32 v48, v2
	v_mov_b32_e32 v49, v2
	v_mov_b32_e32 v58, v2
	v_mov_b32_e32 v59, v2
	v_mov_b32_e32 v60, v2
	v_mov_b32_e32 v61, v2
	v_mov_b32_e32 v62, v2
	v_mov_b32_e32 v63, v2
	v_mov_b32_e32 v64, v2
	v_mov_b32_e32 v65, v2
	v_mov_b32_e32 v66, v2
	v_mov_b32_e32 v67, v2
	v_mov_b32_e32 v68, v2
	v_mov_b32_e32 v69, v2
	v_mov_b32_e32 v70, v2
	v_mov_b32_e32 v71, v2
	v_mov_b32_e32 v72, v2
	v_mov_b32_e32 v73, v2
	v_mov_b32_e32 v82, v2
	v_mov_b32_e32 v83, v2
	v_mov_b32_e32 v84, v2
	v_mov_b32_e32 v85, v2
	v_mov_b32_e32 v86, v2
	v_mov_b32_e32 v87, v2
	v_mov_b32_e32 v88, v2
	v_mov_b32_e32 v89, v2
	v_mov_b32_e32 v98, v2
	v_mov_b32_e32 v99, v2
	v_mov_b32_e32 v100, v2
	v_mov_b32_e32 v101, v2
	v_mov_b32_e32 v102, v2
	v_mov_b32_e32 v103, v2
	v_mov_b32_e32 v104, v2
	v_mov_b32_e32 v105, v2
	v_mov_b32_e32 v114, v2
	v_mov_b32_e32 v115, v2
	v_mov_b32_e32 v116, v2
	v_mov_b32_e32 v117, v2
	v_mov_b32_e32 v118, v2
	v_mov_b32_e32 v119, v2
	v_mov_b32_e32 v120, v2
	v_mov_b32_e32 v121, v2
	v_mov_b32_e32 v74, v2
	v_mov_b32_e32 v75, v2
	v_mov_b32_e32 v76, v2
	v_mov_b32_e32 v77, v2
	v_mov_b32_e32 v78, v2
	v_mov_b32_e32 v79, v2
	v_mov_b32_e32 v80, v2
	v_mov_b32_e32 v81, v2
	v_mov_b32_e32 v90, v2
	v_mov_b32_e32 v91, v2
	v_mov_b32_e32 v92, v2
	v_mov_b32_e32 v93, v2
	v_mov_b32_e32 v94, v2
	v_mov_b32_e32 v95, v2
	v_mov_b32_e32 v96, v2
	v_mov_b32_e32 v97, v2
	v_mov_b32_e32 v106, v2
	v_mov_b32_e32 v107, v2
	v_mov_b32_e32 v108, v2
	v_mov_b32_e32 v109, v2
	v_mov_b32_e32 v110, v2
	v_mov_b32_e32 v111, v2
	v_mov_b32_e32 v112, v2
	v_mov_b32_e32 v113, v2
	v_mov_b32_e32 v126, v2
	v_mov_b32_e32 v127, v2
	v_mov_b32_e32 v128, v2
	v_mov_b32_e32 v129, v2
	v_mov_b32_e32 v122, v2
	v_mov_b32_e32 v123, v2
	v_mov_b32_e32 v124, v2
	v_mov_b32_e32 v125, v2
	s_bitcmp1_b32 s40, 0
	s_cbranch_scc0 .Lmy_q266
.LBB0_266:
	s_add_i32 s60, s58, 2
	s_add_u32 s61, s56, 0x80
	s_addc_u32 s59, s57, 0
	s_add_i32 s64, 0, 0x10000
	s_cmp_eq_u32 s39, s58
	s_cselect_b32 s59, s29, s59
	s_cselect_b32 s58, s50, s61
	s_cselect_b32 s63, s45, s55
	s_cselect_b32 s62, s44, s51
	s_add_i32 s61, 0, 0x14000
	v_add_u32_e32 v152, s64, v201
	v_add_u32_e32 v168, s61, v201
	ds_read_b128 v[140:143], v152
	ds_read_b128 v[144:147], v152 offset:1024
	ds_read_b128 v[148:151], v152 offset:2048
	ds_read_b128 v[152:155], v152 offset:3072
	ds_read_b128 v[156:159], v168
	ds_read_b128 v[160:163], v168 offset:1024
	ds_read_b128 v[164:167], v168 offset:2048
	ds_read_b128 v[168:171], v168 offset:3072
	v_lshl_add_u64 v[188:189], s[56:57], 0, v[134:135]
	s_mov_b32 m0, s83
	s_nop 0
	global_load_lds_dwordx4 v[188:189], off
	v_lshl_add_u64 v[188:189], s[56:57], 0, v[132:133]
	s_mov_b32 m0, s38
	s_nop 0
	global_load_lds_dwordx4 v[188:189], off
	v_lshl_add_u64 v[188:189], s[56:57], 0, v[136:137]
	s_add_i32 m0, s30, 0xc000
	s_nop 0
	global_load_lds_dwordx4 v[188:189], off
	v_lshl_add_u64 v[188:189], s[56:57], 0, v[138:139]
	s_add_i32 m0, s30, 0xe000
	s_nop 0
	global_load_lds_dwordx4 v[188:189], off
	ds_read_b128 v[172:175], v202
	ds_read_b128 v[176:179], v202 offset:1024
	ds_read_b128 v[180:183], v202 offset:2048
	ds_read_b128 v[184:187], v202 offset:3072
	ds_read_b128 v[204:207], v202 offset:4096
	ds_read_b128 v[208:211], v202 offset:5120
	ds_read_b128 v[212:215], v202 offset:6144
	ds_read_b128 v[216:219], v202 offset:7168
	s_waitcnt vmcnt(8)
	s_waitcnt lgkmcnt(0)
	s_barrier
	s_setprio 1
	s_waitcnt lgkmcnt(0)
	v_mfma_f32_16x16x32_bf16 v[122:125], v[140:143], v[172:175], v[122:125]
	v_mfma_f32_16x16x32_bf16 v[126:129], v[148:151], v[172:175], v[126:129]
	v_mfma_f32_16x16x32_bf16 v[110:113], v[140:143], v[180:183], v[110:113]
	v_mfma_f32_16x16x32_bf16 v[106:109], v[148:151], v[180:183], v[106:109]
	v_mfma_f32_16x16x32_bf16 v[94:97], v[140:143], v[204:207], v[94:97]
	v_mfma_f32_16x16x32_bf16 v[90:93], v[148:151], v[204:207], v[90:93]
	v_mfma_f32_16x16x32_bf16 v[78:81], v[140:143], v[212:215], v[78:81]
	v_mfma_f32_16x16x32_bf16 v[74:77], v[148:151], v[212:215], v[74:77]
	v_mfma_f32_16x16x32_bf16 v[122:125], v[144:147], v[176:179], v[122:125]
	v_mfma_f32_16x16x32_bf16 v[126:129], v[152:155], v[176:179], v[126:129]
	v_mfma_f32_16x16x32_bf16 v[110:113], v[144:147], v[184:187], v[110:113]
	v_mfma_f32_16x16x32_bf16 v[106:109], v[152:155], v[184:187], v[106:109]
	v_mfma_f32_16x16x32_bf16 v[94:97], v[144:147], v[208:211], v[94:97]
	v_mfma_f32_16x16x32_bf16 v[90:93], v[152:155], v[208:211], v[90:93]
	v_mfma_f32_16x16x32_bf16 v[78:81], v[144:147], v[216:219], v[78:81]
	v_mfma_f32_16x16x32_bf16 v[74:77], v[152:155], v[216:219], v[74:77]
	s_setprio 0
	s_setprio 1
	v_mfma_f32_16x16x32_bf16 v[118:121], v[156:159], v[172:175], v[118:121]
	v_mfma_f32_16x16x32_bf16 v[114:117], v[164:167], v[172:175], v[114:117]
	v_mfma_f32_16x16x32_bf16 v[102:105], v[156:159], v[180:183], v[102:105]
	v_mfma_f32_16x16x32_bf16 v[98:101], v[164:167], v[180:183], v[98:101]
	v_mfma_f32_16x16x32_bf16 v[86:89], v[156:159], v[204:207], v[86:89]
	v_mfma_f32_16x16x32_bf16 v[82:85], v[164:167], v[204:207], v[82:85]
	v_mfma_f32_16x16x32_bf16 v[70:73], v[156:159], v[212:215], v[70:73]
	v_mfma_f32_16x16x32_bf16 v[66:69], v[164:167], v[212:215], v[66:69]
	v_mfma_f32_16x16x32_bf16 v[118:121], v[160:163], v[176:179], v[118:121]
	v_mfma_f32_16x16x32_bf16 v[114:117], v[168:171], v[176:179], v[114:117]
	v_mfma_f32_16x16x32_bf16 v[102:105], v[160:163], v[184:187], v[102:105]
	v_mfma_f32_16x16x32_bf16 v[98:101], v[168:171], v[184:187], v[98:101]
	v_mfma_f32_16x16x32_bf16 v[86:89], v[160:163], v[208:211], v[86:89]
	v_mfma_f32_16x16x32_bf16 v[82:85], v[168:171], v[208:211], v[82:85]
	v_mfma_f32_16x16x32_bf16 v[70:73], v[160:163], v[216:219], v[70:73]
	v_mfma_f32_16x16x32_bf16 v[66:69], v[168:171], v[216:219], v[66:69]
	s_setprio 0
	s_add_i32 s64, s64, s27
	v_lshl_add_u64 v[188:189], s[62:63], 0, v[0:1]
	s_mov_b32 m0, s64
	ds_read_b128 v[172:175], v202 offset:16384
	ds_read_b128 v[176:179], v202 offset:17408
	ds_read_b128 v[180:183], v202 offset:18432
	ds_read_b128 v[184:187], v202 offset:19456
	ds_read_b128 v[204:207], v202 offset:20480
	ds_read_b128 v[208:211], v202 offset:21504
	ds_read_b128 v[212:215], v202 offset:22528
	ds_read_b128 v[216:219], v202 offset:23552
	global_load_lds_dwordx4 v[188:189], off
	s_add_i32 m0, s64, 0x2000
	v_lshl_add_u64 v[220:221], s[62:63], 0, v[130:131]
	s_add_u32 s62, s62, s6
	s_addc_u32 s63, s63, s7
	s_add_i32 s61, s61, s27
	global_load_lds_dwordx4 v[220:221], off
	v_lshl_add_u64 v[222:223], s[62:63], 0, v[0:1]
	s_mov_b32 m0, s61
	v_lshl_add_u64 v[224:225], s[62:63], 0, v[130:131]
	global_load_lds_dwordx4 v[222:223], off
	s_add_i32 m0, s61, 0x2000
	v_lshl_add_u64 v[226:227], s[58:59], 0, v[134:135]
	global_load_lds_dwordx4 v[224:225], off
	v_lshl_add_u64 v[228:229], s[58:59], 0, v[132:133]
	s_waitcnt vmcnt(6)
	s_waitcnt lgkmcnt(0)
	s_barrier
	s_setprio 1
	s_waitcnt lgkmcnt(0)
	v_mfma_f32_16x16x32_bf16 v[62:65], v[140:143], v[172:175], v[62:65]
	v_mfma_f32_16x16x32_bf16 v[58:61], v[148:151], v[172:175], v[58:61]
	v_mfma_f32_16x16x32_bf16 v[46:49], v[140:143], v[180:183], v[46:49]
	v_mfma_f32_16x16x32_bf16 v[42:45], v[148:151], v[180:183], v[42:45]
	v_mfma_f32_16x16x32_bf16 v[30:33], v[140:143], v[204:207], v[30:33]
	v_mfma_f32_16x16x32_bf16 v[26:29], v[148:151], v[204:207], v[26:29]
	v_mfma_f32_16x16x32_bf16 v[14:17], v[140:143], v[212:215], v[14:17]
	v_mfma_f32_16x16x32_bf16 v[10:13], v[148:151], v[212:215], v[10:13]
	v_mfma_f32_16x16x32_bf16 v[62:65], v[144:147], v[176:179], v[62:65]
	v_mfma_f32_16x16x32_bf16 v[58:61], v[152:155], v[176:179], v[58:61]
	v_mfma_f32_16x16x32_bf16 v[46:49], v[144:147], v[184:187], v[46:49]
	v_mfma_f32_16x16x32_bf16 v[42:45], v[152:155], v[184:187], v[42:45]
	v_mfma_f32_16x16x32_bf16 v[30:33], v[144:147], v[208:211], v[30:33]
	v_mfma_f32_16x16x32_bf16 v[26:29], v[152:155], v[208:211], v[26:29]
	v_mfma_f32_16x16x32_bf16 v[14:17], v[144:147], v[216:219], v[14:17]
	v_mfma_f32_16x16x32_bf16 v[10:13], v[152:155], v[216:219], v[10:13]
	s_setprio 0
	s_setprio 1
	v_mfma_f32_16x16x32_bf16 v[54:57], v[156:159], v[172:175], v[54:57]
	v_mfma_f32_16x16x32_bf16 v[50:53], v[164:167], v[172:175], v[50:53]
	v_mfma_f32_16x16x32_bf16 v[38:41], v[156:159], v[180:183], v[38:41]
	v_mfma_f32_16x16x32_bf16 v[34:37], v[164:167], v[180:183], v[34:37]
	v_mfma_f32_16x16x32_bf16 v[22:25], v[156:159], v[204:207], v[22:25]
	v_mfma_f32_16x16x32_bf16 v[18:21], v[164:167], v[204:207], v[18:21]
	v_mfma_f32_16x16x32_bf16 v[6:9], v[156:159], v[212:215], v[6:9]
	v_mfma_f32_16x16x32_bf16 v[2:5], v[164:167], v[212:215], v[2:5]
	v_mfma_f32_16x16x32_bf16 v[54:57], v[160:163], v[176:179], v[54:57]
	v_mfma_f32_16x16x32_bf16 v[50:53], v[168:171], v[176:179], v[50:53]
	v_mfma_f32_16x16x32_bf16 v[38:41], v[160:163], v[184:187], v[38:41]
	v_mfma_f32_16x16x32_bf16 v[34:37], v[168:171], v[184:187], v[34:37]
	v_mfma_f32_16x16x32_bf16 v[22:25], v[160:163], v[208:211], v[22:25]
	v_mfma_f32_16x16x32_bf16 v[18:21], v[168:171], v[208:211], v[18:21]
	v_mfma_f32_16x16x32_bf16 v[6:9], v[160:163], v[216:219], v[6:9]
	v_mfma_f32_16x16x32_bf16 v[2:5], v[168:171], v[216:219], v[2:5]
	s_setprio 0
	s_add_i32 s61, 0, 0x18000
	s_add_i32 s62, 0, 0x1c000
	v_add_u32_e32 v152, s61, v201
	v_add_u32_e32 v168, s62, v201
	ds_read_b128 v[140:143], v152
	ds_read_b128 v[144:147], v152 offset:1024
	ds_read_b128 v[148:151], v152 offset:2048
	ds_read_b128 v[152:155], v152 offset:3072
	ds_read_b128 v[156:159], v168
	ds_read_b128 v[160:163], v168 offset:1024
	ds_read_b128 v[164:167], v168 offset:2048
	ds_read_b128 v[168:171], v168 offset:3072
	s_add_u32 s58, s58, s2
	s_addc_u32 s59, s59, s3
	s_mov_b32 m0, s30
	v_lshl_add_u64 v[230:231], s[58:59], 0, v[134:135]
	s_nop 0
	global_load_lds_dwordx4 v[226:227], off
	s_mov_b32 m0, s31
	s_nop 0
	global_load_lds_dwordx4 v[228:229], off
	s_mov_b32 m0, s53
	s_nop 0
	global_load_lds_dwordx4 v[230:231], off
	v_lshl_add_u64 v[230:231], s[58:59], 0, v[132:133]
	s_mov_b32 m0, s72
	s_nop 0
	global_load_lds_dwordx4 v[230:231], off
	ds_read_b128 v[172:175], v202 offset:32768
	ds_read_b128 v[176:179], v202 offset:33792
	ds_read_b128 v[180:183], v202 offset:34816
	ds_read_b128 v[184:187], v202 offset:35840
	ds_read_b128 v[204:207], v202 offset:36864
	ds_read_b128 v[208:211], v202 offset:37888
	ds_read_b128 v[212:215], v202 offset:38912
	ds_read_b128 v[216:219], v202 offset:39936
	s_waitcnt vmcnt(8)
	s_waitcnt lgkmcnt(0)
	s_barrier
	s_setprio 1
	s_waitcnt lgkmcnt(0)
	v_mfma_f32_16x16x32_bf16 v[122:125], v[140:143], v[172:175], v[122:125]
	v_mfma_f32_16x16x32_bf16 v[126:129], v[148:151], v[172:175], v[126:129]
	v_mfma_f32_16x16x32_bf16 v[110:113], v[140:143], v[180:183], v[110:113]
	v_mfma_f32_16x16x32_bf16 v[106:109], v[148:151], v[180:183], v[106:109]
	v_mfma_f32_16x16x32_bf16 v[94:97], v[140:143], v[204:207], v[94:97]
	v_mfma_f32_16x16x32_bf16 v[90:93], v[148:151], v[204:207], v[90:93]
	v_mfma_f32_16x16x32_bf16 v[78:81], v[140:143], v[212:215], v[78:81]
	v_mfma_f32_16x16x32_bf16 v[74:77], v[148:151], v[212:215], v[74:77]
	v_mfma_f32_16x16x32_bf16 v[122:125], v[144:147], v[176:179], v[122:125]
	v_mfma_f32_16x16x32_bf16 v[126:129], v[152:155], v[176:179], v[126:129]
	v_mfma_f32_16x16x32_bf16 v[110:113], v[144:147], v[184:187], v[110:113]
	v_mfma_f32_16x16x32_bf16 v[106:109], v[152:155], v[184:187], v[106:109]
	v_mfma_f32_16x16x32_bf16 v[94:97], v[144:147], v[208:211], v[94:97]
	v_mfma_f32_16x16x32_bf16 v[90:93], v[152:155], v[208:211], v[90:93]
	v_mfma_f32_16x16x32_bf16 v[78:81], v[144:147], v[216:219], v[78:81]
	v_mfma_f32_16x16x32_bf16 v[74:77], v[152:155], v[216:219], v[74:77]
	s_setprio 0
	s_setprio 1
	v_mfma_f32_16x16x32_bf16 v[118:121], v[156:159], v[172:175], v[118:121]
	v_mfma_f32_16x16x32_bf16 v[114:117], v[164:167], v[172:175], v[114:117]
	v_mfma_f32_16x16x32_bf16 v[102:105], v[156:159], v[180:183], v[102:105]
	v_mfma_f32_16x16x32_bf16 v[98:101], v[164:167], v[180:183], v[98:101]
	v_mfma_f32_16x16x32_bf16 v[86:89], v[156:159], v[204:207], v[86:89]
	v_mfma_f32_16x16x32_bf16 v[82:85], v[164:167], v[204:207], v[82:85]
	v_mfma_f32_16x16x32_bf16 v[70:73], v[156:159], v[212:215], v[70:73]
	v_mfma_f32_16x16x32_bf16 v[66:69], v[164:167], v[212:215], v[66:69]
	v_mfma_f32_16x16x32_bf16 v[118:121], v[160:163], v[176:179], v[118:121]
	v_mfma_f32_16x16x32_bf16 v[114:117], v[168:171], v[176:179], v[114:117]
	v_mfma_f32_16x16x32_bf16 v[102:105], v[160:163], v[184:187], v[102:105]
	v_mfma_f32_16x16x32_bf16 v[98:101], v[168:171], v[184:187], v[98:101]
	v_mfma_f32_16x16x32_bf16 v[86:89], v[160:163], v[208:211], v[86:89]
	v_mfma_f32_16x16x32_bf16 v[82:85], v[168:171], v[208:211], v[82:85]
	v_mfma_f32_16x16x32_bf16 v[70:73], v[160:163], v[216:219], v[70:73]
	v_mfma_f32_16x16x32_bf16 v[66:69], v[168:171], v[216:219], v[66:69]
	s_setprio 0
	s_add_i32 s58, s61, s27
	v_lshl_add_u64 v[188:189], v[188:189], 0, s[24:25]
	s_mov_b32 m0, s58
	ds_read_b128 v[172:175], v202 offset:49152
	ds_read_b128 v[176:179], v202 offset:50176
	ds_read_b128 v[180:183], v202 offset:51200
	ds_read_b128 v[184:187], v202 offset:52224
	ds_read_b128 v[204:207], v202 offset:53248
	ds_read_b128 v[208:211], v202 offset:54272
	ds_read_b128 v[212:215], v202 offset:55296
	ds_read_b128 v[216:219], v202 offset:56320
	global_load_lds_dwordx4 v[188:189], off
	v_lshl_add_u64 v[188:189], v[220:221], 0, s[24:25]
	s_add_i32 m0, s58, 0x2000
	s_add_i32 s58, s62, s27
	global_load_lds_dwordx4 v[188:189], off
	v_lshl_add_u64 v[188:189], v[222:223], 0, s[24:25]
	s_mov_b32 m0, s58
	s_nop 0
	global_load_lds_dwordx4 v[188:189], off
	v_lshl_add_u64 v[188:189], v[224:225], 0, s[24:25]
	s_add_i32 m0, s58, 0x2000
	s_nop 0
	global_load_lds_dwordx4 v[188:189], off
	s_waitcnt vmcnt(6)
	s_waitcnt lgkmcnt(0)
	s_barrier
	s_setprio 1
	s_waitcnt lgkmcnt(0)
	v_mfma_f32_16x16x32_bf16 v[62:65], v[140:143], v[172:175], v[62:65]
	v_mfma_f32_16x16x32_bf16 v[58:61], v[148:151], v[172:175], v[58:61]
	v_mfma_f32_16x16x32_bf16 v[46:49], v[140:143], v[180:183], v[46:49]
	v_mfma_f32_16x16x32_bf16 v[42:45], v[148:151], v[180:183], v[42:45]
	v_mfma_f32_16x16x32_bf16 v[30:33], v[140:143], v[204:207], v[30:33]
	v_mfma_f32_16x16x32_bf16 v[26:29], v[148:151], v[204:207], v[26:29]
	v_mfma_f32_16x16x32_bf16 v[14:17], v[140:143], v[212:215], v[14:17]
	v_mfma_f32_16x16x32_bf16 v[10:13], v[148:151], v[212:215], v[10:13]
	v_mfma_f32_16x16x32_bf16 v[62:65], v[144:147], v[176:179], v[62:65]
	v_mfma_f32_16x16x32_bf16 v[58:61], v[152:155], v[176:179], v[58:61]
	v_mfma_f32_16x16x32_bf16 v[46:49], v[144:147], v[184:187], v[46:49]
	v_mfma_f32_16x16x32_bf16 v[42:45], v[152:155], v[184:187], v[42:45]
	v_mfma_f32_16x16x32_bf16 v[30:33], v[144:147], v[208:211], v[30:33]
	v_mfma_f32_16x16x32_bf16 v[26:29], v[152:155], v[208:211], v[26:29]
	v_mfma_f32_16x16x32_bf16 v[14:17], v[144:147], v[216:219], v[14:17]
	v_mfma_f32_16x16x32_bf16 v[10:13], v[152:155], v[216:219], v[10:13]
	s_setprio 0
	s_setprio 1
	v_mfma_f32_16x16x32_bf16 v[54:57], v[156:159], v[172:175], v[54:57]
	v_mfma_f32_16x16x32_bf16 v[50:53], v[164:167], v[172:175], v[50:53]
	v_mfma_f32_16x16x32_bf16 v[38:41], v[156:159], v[180:183], v[38:41]
	v_mfma_f32_16x16x32_bf16 v[34:37], v[164:167], v[180:183], v[34:37]
	v_mfma_f32_16x16x32_bf16 v[22:25], v[156:159], v[204:207], v[22:25]
	v_mfma_f32_16x16x32_bf16 v[18:21], v[164:167], v[204:207], v[18:21]
	v_mfma_f32_16x16x32_bf16 v[6:9], v[156:159], v[212:215], v[6:9]
	v_mfma_f32_16x16x32_bf16 v[2:5], v[164:167], v[212:215], v[2:5]
	v_mfma_f32_16x16x32_bf16 v[54:57], v[160:163], v[176:179], v[54:57]
	v_mfma_f32_16x16x32_bf16 v[50:53], v[168:171], v[176:179], v[50:53]
	v_mfma_f32_16x16x32_bf16 v[38:41], v[160:163], v[184:187], v[38:41]
	v_mfma_f32_16x16x32_bf16 v[34:37], v[168:171], v[184:187], v[34:37]
	v_mfma_f32_16x16x32_bf16 v[22:25], v[160:163], v[208:211], v[22:25]
	v_mfma_f32_16x16x32_bf16 v[18:21], v[168:171], v[208:211], v[18:21]
	v_mfma_f32_16x16x32_bf16 v[6:9], v[160:163], v[216:219], v[6:9]
	v_mfma_f32_16x16x32_bf16 v[2:5], v[168:171], v[216:219], v[2:5]
	s_setprio 0
	s_add_u32 s56, s56, 0x100
	s_addc_u32 s57, s57, 0
	s_add_u32 s51, s51, 0x100
	s_addc_u32 s55, s55, 0
	s_cmp_ge_i32 s60, s74
	s_mov_b32 s58, s60
	s_cbranch_scc0 .LBB0_266
	s_branch .Lmy_post266
.Lmy_q266:
	s_add_i32 s60, s58, 2
	s_add_u32 s61, s56, 0x80
	s_addc_u32 s59, s57, 0
	s_add_i32 s64, 0, 0x10000
	s_cmp_eq_u32 s39, s58
	s_cselect_b32 s59, s29, s59
	s_cselect_b32 s58, s50, s61
	s_cselect_b32 s63, s45, s55
	s_cselect_b32 s62, s44, s51
	s_add_i32 s61, 0, 0x14000
	v_add_u32_e32 v152, s64, v201
	v_add_u32_e32 v168, s61, v201
	ds_read_b128 v[140:143], v152
	ds_read_b128 v[144:147], v152 offset:1024
	ds_read_b128 v[148:151], v152 offset:2048
	ds_read_b128 v[152:155], v152 offset:3072
	ds_read_b128 v[156:159], v168
	ds_read_b128 v[160:163], v168 offset:1024
	ds_read_b128 v[164:167], v168 offset:2048
	ds_read_b128 v[168:171], v168 offset:3072
	v_lshl_add_u64 v[188:189], s[56:57], 0, v[134:135]
	s_mov_b32 m0, s83
	s_nop 0
	global_load_lds_dwordx4 v[188:189], off
	v_lshl_add_u64 v[188:189], s[56:57], 0, v[132:133]
	s_mov_b32 m0, s38
	s_nop 0
	global_load_lds_dwordx4 v[188:189], off
	v_lshl_add_u64 v[188:189], s[56:57], 0, v[136:137]
	s_add_i32 m0, s30, 0xc000
	s_nop 0
	global_load_lds_dwordx4 v[188:189], off
	v_lshl_add_u64 v[188:189], s[56:57], 0, v[138:139]
	s_add_i32 m0, s30, 0xe000
	s_nop 0
	global_load_lds_dwordx4 v[188:189], off
	ds_read_b128 v[172:175], v202
	ds_read_b128 v[176:179], v202 offset:1024
	ds_read_b128 v[180:183], v202 offset:2048
	ds_read_b128 v[184:187], v202 offset:3072
	ds_read_b128 v[204:207], v202 offset:4096
	ds_read_b128 v[208:211], v202 offset:5120
	ds_read_b128 v[212:215], v202 offset:6144
	ds_read_b128 v[216:219], v202 offset:7168
	s_waitcnt vmcnt(8)
	s_waitcnt lgkmcnt(0)
	s_setprio 1
	s_waitcnt lgkmcnt(0)
	v_mfma_f32_16x16x32_bf16 v[122:125], v[140:143], v[172:175], v[122:125]
	v_mfma_f32_16x16x32_bf16 v[126:129], v[148:151], v[172:175], v[126:129]
	v_mfma_f32_16x16x32_bf16 v[110:113], v[140:143], v[180:183], v[110:113]
	v_mfma_f32_16x16x32_bf16 v[106:109], v[148:151], v[180:183], v[106:109]
	v_mfma_f32_16x16x32_bf16 v[94:97], v[140:143], v[204:207], v[94:97]
	v_mfma_f32_16x16x32_bf16 v[90:93], v[148:151], v[204:207], v[90:93]
	v_mfma_f32_16x16x32_bf16 v[78:81], v[140:143], v[212:215], v[78:81]
	v_mfma_f32_16x16x32_bf16 v[74:77], v[148:151], v[212:215], v[74:77]
	v_mfma_f32_16x16x32_bf16 v[122:125], v[144:147], v[176:179], v[122:125]
	v_mfma_f32_16x16x32_bf16 v[126:129], v[152:155], v[176:179], v[126:129]
	v_mfma_f32_16x16x32_bf16 v[110:113], v[144:147], v[184:187], v[110:113]
	v_mfma_f32_16x16x32_bf16 v[106:109], v[152:155], v[184:187], v[106:109]
	v_mfma_f32_16x16x32_bf16 v[94:97], v[144:147], v[208:211], v[94:97]
	v_mfma_f32_16x16x32_bf16 v[90:93], v[152:155], v[208:211], v[90:93]
	v_mfma_f32_16x16x32_bf16 v[78:81], v[144:147], v[216:219], v[78:81]
	v_mfma_f32_16x16x32_bf16 v[74:77], v[152:155], v[216:219], v[74:77]
	s_setprio 0
	s_setprio 1
	v_mfma_f32_16x16x32_bf16 v[118:121], v[156:159], v[172:175], v[118:121]
	v_mfma_f32_16x16x32_bf16 v[114:117], v[164:167], v[172:175], v[114:117]
	v_mfma_f32_16x16x32_bf16 v[102:105], v[156:159], v[180:183], v[102:105]
	v_mfma_f32_16x16x32_bf16 v[98:101], v[164:167], v[180:183], v[98:101]
	v_mfma_f32_16x16x32_bf16 v[86:89], v[156:159], v[204:207], v[86:89]
	v_mfma_f32_16x16x32_bf16 v[82:85], v[164:167], v[204:207], v[82:85]
	v_mfma_f32_16x16x32_bf16 v[70:73], v[156:159], v[212:215], v[70:73]
	v_mfma_f32_16x16x32_bf16 v[66:69], v[164:167], v[212:215], v[66:69]
	v_mfma_f32_16x16x32_bf16 v[118:121], v[160:163], v[176:179], v[118:121]
	v_mfma_f32_16x16x32_bf16 v[114:117], v[168:171], v[176:179], v[114:117]
	v_mfma_f32_16x16x32_bf16 v[102:105], v[160:163], v[184:187], v[102:105]
	v_mfma_f32_16x16x32_bf16 v[98:101], v[168:171], v[184:187], v[98:101]
	v_mfma_f32_16x16x32_bf16 v[86:89], v[160:163], v[208:211], v[86:89]
	v_mfma_f32_16x16x32_bf16 v[82:85], v[168:171], v[208:211], v[82:85]
	v_mfma_f32_16x16x32_bf16 v[70:73], v[160:163], v[216:219], v[70:73]
	v_mfma_f32_16x16x32_bf16 v[66:69], v[168:171], v[216:219], v[66:69]
	s_setprio 0
	s_barrier
	s_add_i32 s64, s64, s27
	v_lshl_add_u64 v[188:189], s[62:63], 0, v[0:1]
	s_mov_b32 m0, s64
	ds_read_b128 v[172:175], v202 offset:16384
	ds_read_b128 v[176:179], v202 offset:17408
	ds_read_b128 v[180:183], v202 offset:18432
	ds_read_b128 v[184:187], v202 offset:19456
	ds_read_b128 v[204:207], v202 offset:20480
	ds_read_b128 v[208:211], v202 offset:21504
	ds_read_b128 v[212:215], v202 offset:22528
	ds_read_b128 v[216:219], v202 offset:23552
	global_load_lds_dwordx4 v[188:189], off
	s_add_i32 m0, s64, 0x2000
	v_lshl_add_u64 v[220:221], s[62:63], 0, v[130:131]
	s_add_u32 s62, s62, s6
	s_addc_u32 s63, s63, s7
	s_add_i32 s61, s61, s27
	global_load_lds_dwordx4 v[220:221], off
	v_lshl_add_u64 v[222:223], s[62:63], 0, v[0:1]
	s_mov_b32 m0, s61
	v_lshl_add_u64 v[224:225], s[62:63], 0, v[130:131]
	global_load_lds_dwordx4 v[222:223], off
	s_add_i32 m0, s61, 0x2000
	v_lshl_add_u64 v[226:227], s[58:59], 0, v[134:135]
	global_load_lds_dwordx4 v[224:225], off
	v_lshl_add_u64 v[228:229], s[58:59], 0, v[132:133]
	s_waitcnt vmcnt(6)
	s_waitcnt lgkmcnt(0)
	s_setprio 1
	s_waitcnt lgkmcnt(0)
	v_mfma_f32_16x16x32_bf16 v[62:65], v[140:143], v[172:175], v[62:65]
	v_mfma_f32_16x16x32_bf16 v[58:61], v[148:151], v[172:175], v[58:61]
	v_mfma_f32_16x16x32_bf16 v[46:49], v[140:143], v[180:183], v[46:49]
	v_mfma_f32_16x16x32_bf16 v[42:45], v[148:151], v[180:183], v[42:45]
	v_mfma_f32_16x16x32_bf16 v[30:33], v[140:143], v[204:207], v[30:33]
	v_mfma_f32_16x16x32_bf16 v[26:29], v[148:151], v[204:207], v[26:29]
	v_mfma_f32_16x16x32_bf16 v[14:17], v[140:143], v[212:215], v[14:17]
	v_mfma_f32_16x16x32_bf16 v[10:13], v[148:151], v[212:215], v[10:13]
	v_mfma_f32_16x16x32_bf16 v[62:65], v[144:147], v[176:179], v[62:65]
	v_mfma_f32_16x16x32_bf16 v[58:61], v[152:155], v[176:179], v[58:61]
	v_mfma_f32_16x16x32_bf16 v[46:49], v[144:147], v[184:187], v[46:49]
	v_mfma_f32_16x16x32_bf16 v[42:45], v[152:155], v[184:187], v[42:45]
	v_mfma_f32_16x16x32_bf16 v[30:33], v[144:147], v[208:211], v[30:33]
	v_mfma_f32_16x16x32_bf16 v[26:29], v[152:155], v[208:211], v[26:29]
	v_mfma_f32_16x16x32_bf16 v[14:17], v[144:147], v[216:219], v[14:17]
	v_mfma_f32_16x16x32_bf16 v[10:13], v[152:155], v[216:219], v[10:13]
	s_setprio 0
	s_setprio 1
	v_mfma_f32_16x16x32_bf16 v[54:57], v[156:159], v[172:175], v[54:57]
	v_mfma_f32_16x16x32_bf16 v[50:53], v[164:167], v[172:175], v[50:53]
	v_mfma_f32_16x16x32_bf16 v[38:41], v[156:159], v[180:183], v[38:41]
	v_mfma_f32_16x16x32_bf16 v[34:37], v[164:167], v[180:183], v[34:37]
	v_mfma_f32_16x16x32_bf16 v[22:25], v[156:159], v[204:207], v[22:25]
	v_mfma_f32_16x16x32_bf16 v[18:21], v[164:167], v[204:207], v[18:21]
	v_mfma_f32_16x16x32_bf16 v[6:9], v[156:159], v[212:215], v[6:9]
	v_mfma_f32_16x16x32_bf16 v[2:5], v[164:167], v[212:215], v[2:5]
	v_mfma_f32_16x16x32_bf16 v[54:57], v[160:163], v[176:179], v[54:57]
	v_mfma_f32_16x16x32_bf16 v[50:53], v[168:171], v[176:179], v[50:53]
	v_mfma_f32_16x16x32_bf16 v[38:41], v[160:163], v[184:187], v[38:41]
	v_mfma_f32_16x16x32_bf16 v[34:37], v[168:171], v[184:187], v[34:37]
	v_mfma_f32_16x16x32_bf16 v[22:25], v[160:163], v[208:211], v[22:25]
	v_mfma_f32_16x16x32_bf16 v[18:21], v[168:171], v[208:211], v[18:21]
	v_mfma_f32_16x16x32_bf16 v[6:9], v[160:163], v[216:219], v[6:9]
	v_mfma_f32_16x16x32_bf16 v[2:5], v[168:171], v[216:219], v[2:5]
	s_setprio 0
	s_barrier
	s_add_i32 s61, 0, 0x18000
	s_add_i32 s62, 0, 0x1c000
	v_add_u32_e32 v152, s61, v201
	v_add_u32_e32 v168, s62, v201
	ds_read_b128 v[140:143], v152
	ds_read_b128 v[144:147], v152 offset:1024
	ds_read_b128 v[148:151], v152 offset:2048
	ds_read_b128 v[152:155], v152 offset:3072
	ds_read_b128 v[156:159], v168
	ds_read_b128 v[160:163], v168 offset:1024
	ds_read_b128 v[164:167], v168 offset:2048
	ds_read_b128 v[168:171], v168 offset:3072
	s_add_u32 s58, s58, s2
	s_addc_u32 s59, s59, s3
	s_mov_b32 m0, s30
	v_lshl_add_u64 v[230:231], s[58:59], 0, v[134:135]
	s_nop 0
	global_load_lds_dwordx4 v[226:227], off
	s_mov_b32 m0, s31
	s_nop 0
	global_load_lds_dwordx4 v[228:229], off
	s_mov_b32 m0, s53
	s_nop 0
	global_load_lds_dwordx4 v[230:231], off
	v_lshl_add_u64 v[230:231], s[58:59], 0, v[132:133]
	s_mov_b32 m0, s72
	s_nop 0
	global_load_lds_dwordx4 v[230:231], off
	ds_read_b128 v[172:175], v202 offset:32768
	ds_read_b128 v[176:179], v202 offset:33792
	ds_read_b128 v[180:183], v202 offset:34816
	ds_read_b128 v[184:187], v202 offset:35840
	ds_read_b128 v[204:207], v202 offset:36864
	ds_read_b128 v[208:211], v202 offset:37888
	ds_read_b128 v[212:215], v202 offset:38912
	ds_read_b128 v[216:219], v202 offset:39936
	s_waitcnt vmcnt(8)
	s_waitcnt lgkmcnt(0)
	s_setprio 1
	s_waitcnt lgkmcnt(0)
	v_mfma_f32_16x16x32_bf16 v[122:125], v[140:143], v[172:175], v[122:125]
	v_mfma_f32_16x16x32_bf16 v[126:129], v[148:151], v[172:175], v[126:129]
	v_mfma_f32_16x16x32_bf16 v[110:113], v[140:143], v[180:183], v[110:113]
	v_mfma_f32_16x16x32_bf16 v[106:109], v[148:151], v[180:183], v[106:109]
	v_mfma_f32_16x16x32_bf16 v[94:97], v[140:143], v[204:207], v[94:97]
	v_mfma_f32_16x16x32_bf16 v[90:93], v[148:151], v[204:207], v[90:93]
	v_mfma_f32_16x16x32_bf16 v[78:81], v[140:143], v[212:215], v[78:81]
	v_mfma_f32_16x16x32_bf16 v[74:77], v[148:151], v[212:215], v[74:77]
	v_mfma_f32_16x16x32_bf16 v[122:125], v[144:147], v[176:179], v[122:125]
	v_mfma_f32_16x16x32_bf16 v[126:129], v[152:155], v[176:179], v[126:129]
	v_mfma_f32_16x16x32_bf16 v[110:113], v[144:147], v[184:187], v[110:113]
	v_mfma_f32_16x16x32_bf16 v[106:109], v[152:155], v[184:187], v[106:109]
	v_mfma_f32_16x16x32_bf16 v[94:97], v[144:147], v[208:211], v[94:97]
	v_mfma_f32_16x16x32_bf16 v[90:93], v[152:155], v[208:211], v[90:93]
	v_mfma_f32_16x16x32_bf16 v[78:81], v[144:147], v[216:219], v[78:81]
	v_mfma_f32_16x16x32_bf16 v[74:77], v[152:155], v[216:219], v[74:77]
	s_setprio 0
	s_setprio 1
	v_mfma_f32_16x16x32_bf16 v[118:121], v[156:159], v[172:175], v[118:121]
	v_mfma_f32_16x16x32_bf16 v[114:117], v[164:167], v[172:175], v[114:117]
	v_mfma_f32_16x16x32_bf16 v[102:105], v[156:159], v[180:183], v[102:105]
	v_mfma_f32_16x16x32_bf16 v[98:101], v[164:167], v[180:183], v[98:101]
	v_mfma_f32_16x16x32_bf16 v[86:89], v[156:159], v[204:207], v[86:89]
	v_mfma_f32_16x16x32_bf16 v[82:85], v[164:167], v[204:207], v[82:85]
	v_mfma_f32_16x16x32_bf16 v[70:73], v[156:159], v[212:215], v[70:73]
	v_mfma_f32_16x16x32_bf16 v[66:69], v[164:167], v[212:215], v[66:69]
	v_mfma_f32_16x16x32_bf16 v[118:121], v[160:163], v[176:179], v[118:121]
	v_mfma_f32_16x16x32_bf16 v[114:117], v[168:171], v[176:179], v[114:117]
	v_mfma_f32_16x16x32_bf16 v[102:105], v[160:163], v[184:187], v[102:105]
	v_mfma_f32_16x16x32_bf16 v[98:101], v[168:171], v[184:187], v[98:101]
	v_mfma_f32_16x16x32_bf16 v[86:89], v[160:163], v[208:211], v[86:89]
	v_mfma_f32_16x16x32_bf16 v[82:85], v[168:171], v[208:211], v[82:85]
	v_mfma_f32_16x16x32_bf16 v[70:73], v[160:163], v[216:219], v[70:73]
	v_mfma_f32_16x16x32_bf16 v[66:69], v[168:171], v[216:219], v[66:69]
	s_setprio 0
	s_barrier
	s_add_i32 s58, s61, s27
	v_lshl_add_u64 v[188:189], v[188:189], 0, s[24:25]
	s_mov_b32 m0, s58
	ds_read_b128 v[172:175], v202 offset:49152
	ds_read_b128 v[176:179], v202 offset:50176
	ds_read_b128 v[180:183], v202 offset:51200
	ds_read_b128 v[184:187], v202 offset:52224
	ds_read_b128 v[204:207], v202 offset:53248
	ds_read_b128 v[208:211], v202 offset:54272
	ds_read_b128 v[212:215], v202 offset:55296
	ds_read_b128 v[216:219], v202 offset:56320
	global_load_lds_dwordx4 v[188:189], off
	v_lshl_add_u64 v[188:189], v[220:221], 0, s[24:25]
	s_add_i32 m0, s58, 0x2000
	s_add_i32 s58, s62, s27
	global_load_lds_dwordx4 v[188:189], off
	v_lshl_add_u64 v[188:189], v[222:223], 0, s[24:25]
	s_mov_b32 m0, s58
	s_nop 0
	global_load_lds_dwordx4 v[188:189], off
	v_lshl_add_u64 v[188:189], v[224:225], 0, s[24:25]
	s_add_i32 m0, s58, 0x2000
	s_nop 0
	global_load_lds_dwordx4 v[188:189], off
	s_waitcnt vmcnt(6)
	s_waitcnt lgkmcnt(0)
	s_setprio 1
	s_waitcnt lgkmcnt(0)
	v_mfma_f32_16x16x32_bf16 v[62:65], v[140:143], v[172:175], v[62:65]
	v_mfma_f32_16x16x32_bf16 v[58:61], v[148:151], v[172:175], v[58:61]
	v_mfma_f32_16x16x32_bf16 v[46:49], v[140:143], v[180:183], v[46:49]
	v_mfma_f32_16x16x32_bf16 v[42:45], v[148:151], v[180:183], v[42:45]
	v_mfma_f32_16x16x32_bf16 v[30:33], v[140:143], v[204:207], v[30:33]
	v_mfma_f32_16x16x32_bf16 v[26:29], v[148:151], v[204:207], v[26:29]
	v_mfma_f32_16x16x32_bf16 v[14:17], v[140:143], v[212:215], v[14:17]
	v_mfma_f32_16x16x32_bf16 v[10:13], v[148:151], v[212:215], v[10:13]
	v_mfma_f32_16x16x32_bf16 v[62:65], v[144:147], v[176:179], v[62:65]
	v_mfma_f32_16x16x32_bf16 v[58:61], v[152:155], v[176:179], v[58:61]
	v_mfma_f32_16x16x32_bf16 v[46:49], v[144:147], v[184:187], v[46:49]
	v_mfma_f32_16x16x32_bf16 v[42:45], v[152:155], v[184:187], v[42:45]
	v_mfma_f32_16x16x32_bf16 v[30:33], v[144:147], v[208:211], v[30:33]
	v_mfma_f32_16x16x32_bf16 v[26:29], v[152:155], v[208:211], v[26:29]
	v_mfma_f32_16x16x32_bf16 v[14:17], v[144:147], v[216:219], v[14:17]
	v_mfma_f32_16x16x32_bf16 v[10:13], v[152:155], v[216:219], v[10:13]
	s_setprio 0
	s_setprio 1
	v_mfma_f32_16x16x32_bf16 v[54:57], v[156:159], v[172:175], v[54:57]
	v_mfma_f32_16x16x32_bf16 v[50:53], v[164:167], v[172:175], v[50:53]
	v_mfma_f32_16x16x32_bf16 v[38:41], v[156:159], v[180:183], v[38:41]
	v_mfma_f32_16x16x32_bf16 v[34:37], v[164:167], v[180:183], v[34:37]
	v_mfma_f32_16x16x32_bf16 v[22:25], v[156:159], v[204:207], v[22:25]
	v_mfma_f32_16x16x32_bf16 v[18:21], v[164:167], v[204:207], v[18:21]
	v_mfma_f32_16x16x32_bf16 v[6:9], v[156:159], v[212:215], v[6:9]
	v_mfma_f32_16x16x32_bf16 v[2:5], v[164:167], v[212:215], v[2:5]
	v_mfma_f32_16x16x32_bf16 v[54:57], v[160:163], v[176:179], v[54:57]
	v_mfma_f32_16x16x32_bf16 v[50:53], v[168:171], v[176:179], v[50:53]
	v_mfma_f32_16x16x32_bf16 v[38:41], v[160:163], v[184:187], v[38:41]
	v_mfma_f32_16x16x32_bf16 v[34:37], v[168:171], v[184:187], v[34:37]
	v_mfma_f32_16x16x32_bf16 v[22:25], v[160:163], v[208:211], v[22:25]
	v_mfma_f32_16x16x32_bf16 v[18:21], v[168:171], v[208:211], v[18:21]
	v_mfma_f32_16x16x32_bf16 v[6:9], v[160:163], v[216:219], v[6:9]
	v_mfma_f32_16x16x32_bf16 v[2:5], v[168:171], v[216:219], v[2:5]
	s_setprio 0
	s_barrier
	s_add_u32 s56, s56, 0x100
	s_addc_u32 s57, s57, 0
	s_add_u32 s51, s51, 0x100
	s_addc_u32 s55, s55, 0
	s_cmp_ge_i32 s60, s74
	s_mov_b32 s58, s60
	s_cbranch_scc0 .Lmy_q266
.Lmy_post266:
.LBB0_267:
	s_and_b64 vcc, exec, s[40:41]
	s_cbranch_vccz .LBB0_269
	s_nop 0

.LBB0_350:
	v_lshl_add_u64 v[6:7], v[146:147], 2, s[68:69]
	s_waitcnt lgkmcnt(0)
	global_load_dwordx4 v[10:13], v[6:7], off offset:16
	global_load_dwordx4 v[14:17], v[6:7], off
	global_load_dwordx4 v[2:5], v[6:7], off offset:528
	s_nop 0
	global_load_dwordx4 v[6:9], v[6:7], off offset:512
	s_nop 0
	global_load_dwordx4 v[204:207], v[176:177], off offset:48
	global_load_dwordx4 v[208:211], v[176:177], off offset:32
	global_load_dwordx4 v[212:215], v[176:177], off offset:16
	global_load_dwordx4 v[216:219], v[176:177], off
	s_mov_b32 s28, 0x800000
	s_mov_b32 s96, 0x800000
	s_mov_b64 s[50:51], -1
	s_waitcnt vmcnt(0)
	v_add_f32_e32 v208, v208, v209
	v_mov_b32_e32 v176, v213
	v_mov_b32_e32 v146, v217
	v_mov_b32_e32 v147, v218
	v_mov_b32_e32 v217, v219
	v_mov_b32_e32 v177, v214
	v_mov_b32_e32 v213, v215
	v_pk_add_f32 v[146:147], v[146:147], v[216:217]
	v_pk_add_f32 v[176:177], v[176:177], v[212:213]
	v_add_f32_e32 v146, v146, v147
	v_pk_add_f32 v[176:177], v[176:177], v[176:177] op_sel:[0,1] op_sel_hi:[1,0]
	v_add_f32_e32 v146, 0, v146
	v_add_f32_e32 v210, v210, v211
	v_mov_b32_e32 v147, v204
	v_mov_b32_e32 v177, v205
	v_mov_b32_e32 v209, v206
	v_mov_b32_e32 v211, v207
	v_pk_add_f32 v[146:147], v[146:147], v[176:177]
	v_pk_add_f32 v[176:177], v[208:209], v[210:211]
	s_nop 0
	v_pk_add_f32 v[146:147], v[146:147], v[176:177]
	s_nop 0
	v_add_f32_e32 v146, v146, v147
	v_fmamk_f32 v146, v146, 0x3a800000, v191
	v_cmp_gt_f32_e32 vcc, s28, v146
	v_mul_f32_e32 v147, 0x4b800000, v146
	s_nop 0
	v_cndmask_b32_e32 v146, v146, v147, vcc
	v_rsq_f32_e32 v146, v146
	s_nop 0
	v_mul_f32_e32 v147, 0x45800000, v146
	v_cndmask_b32_e32 v146, v146, v147, vcc
	v_pk_mul_f32 v[176:177], v[144:145], v[146:147] op_sel_hi:[1,0]
	v_pk_mul_f32 v[142:143], v[142:143], v[146:147] op_sel_hi:[1,0]
	v_pk_mul_f32 v[122:123], v[122:123], v[146:147] op_sel_hi:[1,0]
	v_pk_mul_f32 v[144:145], v[16:17], v[142:143]
	v_pk_mul_f32 v[142:143], v[14:15], v[176:177]
	global_store_dwordx4 v[140:141], v[142:145], off
	v_pk_mul_f32 v[120:121], v[120:121], v[146:147] op_sel_hi:[1,0]
	v_pk_mul_f32 v[116:117], v[116:117], v[146:147] op_sel_hi:[1,0]
	v_pk_mul_f32 v[142:143], v[124:125], v[146:147] op_sel_hi:[1,0]
	v_pk_mul_f32 v[124:125], v[12:13], v[122:123]
	v_pk_mul_f32 v[122:123], v[10:11], v[142:143]
	global_store_dwordx4 v[140:141], v[122:125], off offset:16
	s_nop 1
	v_pk_mul_f32 v[124:125], v[126:127], v[146:147] op_sel_hi:[1,0]
	v_pk_mul_f32 v[122:123], v[8:9], v[120:121]
	v_pk_mul_f32 v[120:121], v[6:7], v[124:125]
	global_store_dwordx4 v[140:141], v[120:123], off offset:512
	s_nop 1
	v_pk_mul_f32 v[120:121], v[118:119], v[146:147] op_sel_hi:[1,0]
	v_pk_mul_f32 v[118:119], v[4:5], v[116:117]
	v_pk_mul_f32 v[116:117], v[2:3], v[120:121]
	global_store_dwordx4 v[140:141], v[116:119], off offset:528
	global_load_dwordx4 v[116:119], v[174:175], off offset:48
	s_nop 0
	global_load_dwordx4 v[120:123], v[174:175], off offset:32
	global_load_dwordx4 v[124:127], v[174:175], off offset:16
	global_load_dwordx4 v[140:143], v[174:175], off
	s_waitcnt vmcnt(2)
	v_add_f32_e32 v120, v120, v121
	v_add_f32_e32 v122, v122, v123
	s_waitcnt vmcnt(0)
	v_mov_b32_e32 v144, v141
	v_mov_b32_e32 v145, v142
	v_mov_b32_e32 v141, v143
	v_mov_b32_e32 v142, v125
	v_mov_b32_e32 v143, v126
	v_mov_b32_e32 v125, v127
	v_pk_add_f32 v[140:141], v[144:145], v[140:141]
	v_pk_add_f32 v[124:125], v[142:143], v[124:125]
	v_add_f32_e32 v140, v140, v141
	v_pk_add_f32 v[124:125], v[124:125], v[124:125] op_sel:[0,1] op_sel_hi:[1,0]
	v_add_f32_e32 v140, 0, v140
	v_mov_b32_e32 v141, v116
	v_mov_b32_e32 v125, v117
	v_mov_b32_e32 v121, v118
	v_mov_b32_e32 v123, v119
	v_pk_add_f32 v[116:117], v[140:141], v[124:125]
	v_pk_add_f32 v[118:119], v[120:121], v[122:123]
	s_nop 0
	v_pk_add_f32 v[116:117], v[116:117], v[118:119]
	s_nop 0
	v_add_f32_e32 v116, v116, v117
	v_fmamk_f32 v116, v116, 0x3a800000, v191
	v_cmp_gt_f32_e32 vcc, s28, v116
	v_mul_f32_e32 v117, 0x4b800000, v116
	s_nop 0
	v_cndmask_b32_e32 v116, v116, v117, vcc
	v_rsq_f32_e32 v116, v116
	s_nop 0
	v_mul_f32_e32 v117, 0x45800000, v116
	v_cndmask_b32_e32 v116, v116, v117, vcc
	v_pk_mul_f32 v[106:107], v[106:107], v[116:117] op_sel_hi:[1,0]
	v_pk_mul_f32 v[108:109], v[108:109], v[116:117] op_sel_hi:[1,0]
	v_pk_mul_f32 v[106:107], v[10:11], v[106:107]
	v_pk_mul_f32 v[108:109], v[12:13], v[108:109]
	global_store_dwordx4 v[114:115], v[106:109], off offset:16
	v_pk_mul_f32 v[104:105], v[104:105], v[116:117] op_sel_hi:[1,0]
	v_pk_mul_f32 v[110:111], v[110:111], v[116:117] op_sel_hi:[1,0]
	v_pk_mul_f32 v[108:109], v[128:129], v[116:117] op_sel_hi:[1,0]
	v_pk_mul_f32 v[106:107], v[8:9], v[104:105]
	v_pk_mul_f32 v[104:105], v[6:7], v[108:109]
	v_pk_mul_f32 v[112:113], v[112:113], v[116:117] op_sel_hi:[1,0]
	global_store_dwordx4 v[114:115], v[104:107], off offset:512
	v_pk_mul_f32 v[100:101], v[100:101], v[116:117] op_sel_hi:[1,0]
	v_pk_mul_f32 v[112:113], v[16:17], v[112:113]
	v_pk_mul_f32 v[104:105], v[102:103], v[116:117] op_sel_hi:[1,0]
	v_pk_mul_f32 v[110:111], v[14:15], v[110:111]
	v_pk_mul_f32 v[102:103], v[4:5], v[100:101]
	v_pk_mul_f32 v[100:101], v[2:3], v[104:105]
	global_store_dwordx4 v[114:115], v[110:113], off
	global_store_dwordx4 v[114:115], v[100:103], off offset:528
	global_load_dwordx4 v[100:103], v[178:179], off offset:48
	global_load_dwordx4 v[104:107], v[178:179], off offset:32
	global_load_dwordx4 v[108:111], v[178:179], off offset:16
	global_load_dwordx4 v[112:115], v[178:179], off
	s_waitcnt vmcnt(2)
	v_add_f32_e32 v104, v104, v105
	v_add_f32_e32 v106, v106, v107
	s_waitcnt vmcnt(0)
	v_mov_b32_e32 v116, v113
	v_mov_b32_e32 v117, v114
	v_mov_b32_e32 v113, v115
	v_mov_b32_e32 v114, v109
	v_mov_b32_e32 v115, v110
	v_mov_b32_e32 v109, v111
	v_pk_add_f32 v[112:113], v[116:117], v[112:113]
	v_pk_add_f32 v[108:109], v[114:115], v[108:109]
	v_add_f32_e32 v112, v112, v113
	v_pk_add_f32 v[108:109], v[108:109], v[108:109] op_sel:[0,1] op_sel_hi:[1,0]
	v_add_f32_e32 v112, 0, v112
	v_mov_b32_e32 v113, v100
	v_mov_b32_e32 v109, v101
	v_mov_b32_e32 v105, v102
	v_mov_b32_e32 v107, v103
	v_pk_add_f32 v[100:101], v[112:113], v[108:109]
	v_pk_add_f32 v[102:103], v[104:105], v[106:107]
	s_nop 0
	v_pk_add_f32 v[100:101], v[100:101], v[102:103]
	s_nop 0
	v_add_f32_e32 v100, v100, v101
	v_fmamk_f32 v100, v100, 0x3a800000, v191
	v_cmp_gt_f32_e32 vcc, s28, v100
	v_mul_f32_e32 v101, 0x4b800000, v100
	s_nop 0
	v_cndmask_b32_e32 v100, v100, v101, vcc
	v_rsq_f32_e32 v100, v100
	s_nop 0
	v_mul_f32_e32 v101, 0x45800000, v100
	v_cndmask_b32_e32 v100, v100, v101, vcc
	v_pk_mul_f32 v[90:91], v[90:91], v[100:101] op_sel_hi:[1,0]
	v_pk_mul_f32 v[92:93], v[92:93], v[100:101] op_sel_hi:[1,0]
	v_pk_mul_f32 v[90:91], v[10:11], v[90:91]
	v_pk_mul_f32 v[92:93], v[12:13], v[92:93]
	global_store_dwordx4 v[98:99], v[90:93], off offset:16
	v_pk_mul_f32 v[88:89], v[88:89], v[100:101] op_sel_hi:[1,0]
	v_pk_mul_f32 v[94:95], v[94:95], v[100:101] op_sel_hi:[1,0]
	v_pk_mul_f32 v[92:93], v[148:149], v[100:101] op_sel_hi:[1,0]
	v_pk_mul_f32 v[90:91], v[8:9], v[88:89]
	v_pk_mul_f32 v[88:89], v[6:7], v[92:93]
	v_pk_mul_f32 v[96:97], v[96:97], v[100:101] op_sel_hi:[1,0]
	global_store_dwordx4 v[98:99], v[88:91], off offset:512
	v_pk_mul_f32 v[84:85], v[84:85], v[100:101] op_sel_hi:[1,0]
	v_pk_mul_f32 v[96:97], v[16:17], v[96:97]
	v_pk_mul_f32 v[88:89], v[86:87], v[100:101] op_sel_hi:[1,0]
	v_pk_mul_f32 v[94:95], v[14:15], v[94:95]
	v_pk_mul_f32 v[86:87], v[4:5], v[84:85]
	v_pk_mul_f32 v[84:85], v[2:3], v[88:89]
	global_store_dwordx4 v[98:99], v[94:97], off
	global_store_dwordx4 v[98:99], v[84:87], off offset:528
	global_load_dwordx4 v[84:87], v[180:181], off offset:48
	s_nop 0
	global_load_dwordx4 v[88:91], v[180:181], off offset:32
	global_load_dwordx4 v[92:95], v[180:181], off offset:16
	global_load_dwordx4 v[96:99], v[180:181], off
	s_waitcnt vmcnt(2)
	v_add_f32_e32 v88, v88, v89
	v_add_f32_e32 v90, v90, v91
	s_waitcnt vmcnt(0)
	v_mov_b32_e32 v100, v97
	v_mov_b32_e32 v101, v98
	v_mov_b32_e32 v97, v99
	v_mov_b32_e32 v98, v93
	v_mov_b32_e32 v99, v94
	v_mov_b32_e32 v93, v95
	v_pk_add_f32 v[96:97], v[100:101], v[96:97]
	v_pk_add_f32 v[92:93], v[98:99], v[92:93]
	v_add_f32_e32 v96, v96, v97
	v_pk_add_f32 v[92:93], v[92:93], v[92:93] op_sel:[0,1] op_sel_hi:[1,0]
	v_add_f32_e32 v96, 0, v96
	v_mov_b32_e32 v97, v84
	v_mov_b32_e32 v93, v85
	v_mov_b32_e32 v89, v86
	v_mov_b32_e32 v91, v87
	v_pk_add_f32 v[84:85], v[96:97], v[92:93]
	v_pk_add_f32 v[86:87], v[88:89], v[90:91]
	s_nop 0
	v_pk_add_f32 v[84:85], v[84:85], v[86:87]
	s_nop 0
	v_add_f32_e32 v84, v84, v85
	v_fmamk_f32 v84, v84, 0x3a800000, v191
	v_cmp_gt_f32_e32 vcc, s28, v84
	v_mul_f32_e32 v85, 0x4b800000, v84
	s_nop 0
	v_cndmask_b32_e32 v84, v84, v85, vcc
	v_rsq_f32_e32 v84, v84
	s_nop 0
	v_mul_f32_e32 v85, 0x45800000, v84
	v_cndmask_b32_e32 v84, v84, v85, vcc
	v_pk_mul_f32 v[74:75], v[74:75], v[84:85] op_sel_hi:[1,0]
	v_pk_mul_f32 v[76:77], v[76:77], v[84:85] op_sel_hi:[1,0]
	v_pk_mul_f32 v[74:75], v[10:11], v[74:75]
	v_pk_mul_f32 v[76:77], v[12:13], v[76:77]
	global_store_dwordx4 v[82:83], v[74:77], off offset:16
	v_pk_mul_f32 v[72:73], v[72:73], v[84:85] op_sel_hi:[1,0]
	v_pk_mul_f32 v[78:79], v[78:79], v[84:85] op_sel_hi:[1,0]
	v_pk_mul_f32 v[76:77], v[150:151], v[84:85] op_sel_hi:[1,0]
	v_pk_mul_f32 v[74:75], v[8:9], v[72:73]
	v_pk_mul_f32 v[72:73], v[6:7], v[76:77]
	v_pk_mul_f32 v[80:81], v[80:81], v[84:85] op_sel_hi:[1,0]
	global_store_dwordx4 v[82:83], v[72:75], off offset:512
	v_pk_mul_f32 v[68:69], v[68:69], v[84:85] op_sel_hi:[1,0]
	v_pk_mul_f32 v[80:81], v[16:17], v[80:81]
	v_pk_mul_f32 v[72:73], v[70:71], v[84:85] op_sel_hi:[1,0]
	v_pk_mul_f32 v[78:79], v[14:15], v[78:79]
	v_pk_mul_f32 v[70:71], v[4:5], v[68:69]
	v_pk_mul_f32 v[68:69], v[2:3], v[72:73]
	global_store_dwordx4 v[82:83], v[78:81], off
	global_store_dwordx4 v[82:83], v[68:71], off offset:528
	global_load_dwordx4 v[68:71], v[182:183], off offset:48
	global_load_dwordx4 v[72:75], v[182:183], off offset:32
	global_load_dwordx4 v[76:79], v[182:183], off offset:16
	global_load_dwordx4 v[80:83], v[182:183], off
	s_waitcnt vmcnt(2)
	v_add_f32_e32 v72, v72, v73
	v_add_f32_e32 v74, v74, v75
	s_waitcnt vmcnt(0)
	v_mov_b32_e32 v84, v81
	v_mov_b32_e32 v85, v82
	v_mov_b32_e32 v81, v83
	v_mov_b32_e32 v82, v77
	v_mov_b32_e32 v83, v78
	v_mov_b32_e32 v77, v79
	v_pk_add_f32 v[80:81], v[84:85], v[80:81]
	v_pk_add_f32 v[76:77], v[82:83], v[76:77]
	v_add_f32_e32 v80, v80, v81
	v_pk_add_f32 v[76:77], v[76:77], v[76:77] op_sel:[0,1] op_sel_hi:[1,0]
	v_add_f32_e32 v80, 0, v80
	v_mov_b32_e32 v81, v68
	v_mov_b32_e32 v77, v69
	v_mov_b32_e32 v73, v70
	v_mov_b32_e32 v75, v71
	v_pk_add_f32 v[68:69], v[80:81], v[76:77]
	v_pk_add_f32 v[70:71], v[72:73], v[74:75]
	s_nop 0
	v_pk_add_f32 v[68:69], v[68:69], v[70:71]
	s_nop 0
	v_add_f32_e32 v68, v68, v69
	v_fmamk_f32 v68, v68, 0x3a800000, v191
	v_cmp_gt_f32_e32 vcc, s28, v68
	v_mul_f32_e32 v69, 0x4b800000, v68
	s_nop 0
	v_cndmask_b32_e32 v68, v68, v69, vcc
	v_rsq_f32_e32 v68, v68
	s_nop 0
	v_mul_f32_e32 v69, 0x45800000, v68
	v_cndmask_b32_e32 v68, v68, v69, vcc
	v_pk_mul_f32 v[58:59], v[58:59], v[68:69] op_sel_hi:[1,0]
	v_pk_mul_f32 v[60:61], v[60:61], v[68:69] op_sel_hi:[1,0]
	v_pk_mul_f32 v[58:59], v[10:11], v[58:59]
	v_pk_mul_f32 v[60:61], v[12:13], v[60:61]
	global_store_dwordx4 v[66:67], v[58:61], off offset:16
	v_pk_mul_f32 v[56:57], v[56:57], v[68:69] op_sel_hi:[1,0]
	v_pk_mul_f32 v[62:63], v[62:63], v[68:69] op_sel_hi:[1,0]
	v_pk_mul_f32 v[60:61], v[152:153], v[68:69] op_sel_hi:[1,0]
	v_pk_mul_f32 v[58:59], v[8:9], v[56:57]
	v_pk_mul_f32 v[56:57], v[6:7], v[60:61]
	v_pk_mul_f32 v[64:65], v[64:65], v[68:69] op_sel_hi:[1,0]
	global_store_dwordx4 v[66:67], v[56:59], off offset:512
	v_pk_mul_f32 v[52:53], v[52:53], v[68:69] op_sel_hi:[1,0]
	v_pk_mul_f32 v[64:65], v[16:17], v[64:65]
	v_pk_mul_f32 v[56:57], v[54:55], v[68:69] op_sel_hi:[1,0]
	v_pk_mul_f32 v[62:63], v[14:15], v[62:63]
	v_pk_mul_f32 v[54:55], v[4:5], v[52:53]
	v_pk_mul_f32 v[52:53], v[2:3], v[56:57]
	global_store_dwordx4 v[66:67], v[62:65], off
	global_store_dwordx4 v[66:67], v[52:55], off offset:528
	global_load_dwordx4 v[52:55], v[184:185], off offset:48
	s_nop 0
	global_load_dwordx4 v[56:59], v[184:185], off offset:32
	global_load_dwordx4 v[60:63], v[184:185], off offset:16
	global_load_dwordx4 v[64:67], v[184:185], off
	s_waitcnt vmcnt(2)
	v_add_f32_e32 v56, v56, v57
	v_add_f32_e32 v58, v58, v59
	s_waitcnt vmcnt(0)
	v_mov_b32_e32 v68, v65
	v_mov_b32_e32 v69, v66
	v_mov_b32_e32 v65, v67
	v_mov_b32_e32 v66, v61
	v_mov_b32_e32 v67, v62
	v_mov_b32_e32 v61, v63
	v_pk_add_f32 v[64:65], v[68:69], v[64:65]
	v_pk_add_f32 v[60:61], v[66:67], v[60:61]
	v_add_f32_e32 v64, v64, v65
	v_pk_add_f32 v[60:61], v[60:61], v[60:61] op_sel:[0,1] op_sel_hi:[1,0]
	v_add_f32_e32 v64, 0, v64
	v_mov_b32_e32 v65, v52
	v_mov_b32_e32 v61, v53
	v_mov_b32_e32 v57, v54
	v_mov_b32_e32 v59, v55
	v_pk_add_f32 v[52:53], v[64:65], v[60:61]
	v_pk_add_f32 v[54:55], v[56:57], v[58:59]
	s_nop 0
	v_pk_add_f32 v[52:53], v[52:53], v[54:55]
	s_nop 0
	v_add_f32_e32 v52, v52, v53
	v_fmamk_f32 v52, v52, 0x3a800000, v191
	v_cmp_gt_f32_e32 vcc, s28, v52
	v_mul_f32_e32 v53, 0x4b800000, v52
	s_nop 0
	v_cndmask_b32_e32 v52, v52, v53, vcc
	v_rsq_f32_e32 v52, v52
	s_nop 0
	v_mul_f32_e32 v53, 0x45800000, v52
	v_cndmask_b32_e32 v52, v52, v53, vcc
	v_pk_mul_f32 v[42:43], v[42:43], v[52:53] op_sel_hi:[1,0]
	v_pk_mul_f32 v[44:45], v[44:45], v[52:53] op_sel_hi:[1,0]
	v_pk_mul_f32 v[42:43], v[10:11], v[42:43]
	v_pk_mul_f32 v[44:45], v[12:13], v[44:45]
	global_store_dwordx4 v[50:51], v[42:45], off offset:16
	v_pk_mul_f32 v[46:47], v[46:47], v[52:53] op_sel_hi:[1,0]
	v_pk_mul_f32 v[48:49], v[48:49], v[52:53] op_sel_hi:[1,0]
	v_pk_mul_f32 v[42:43], v[158:159], v[52:53] op_sel_hi:[1,0]
	v_pk_mul_f32 v[44:45], v[154:155], v[52:53] op_sel_hi:[1,0]
	v_pk_mul_f32 v[42:43], v[6:7], v[42:43]
	v_pk_mul_f32 v[44:45], v[8:9], v[44:45]
	global_store_dwordx4 v[50:51], v[42:45], off offset:512
	v_pk_mul_f32 v[38:39], v[38:39], v[52:53] op_sel_hi:[1,0]
	v_pk_mul_f32 v[48:49], v[16:17], v[48:49]
	v_pk_mul_f32 v[42:43], v[40:41], v[52:53] op_sel_hi:[1,0]
	v_pk_mul_f32 v[46:47], v[14:15], v[46:47]
	v_pk_mul_f32 v[40:41], v[4:5], v[38:39]
	v_pk_mul_f32 v[38:39], v[2:3], v[42:43]
	global_store_dwordx4 v[50:51], v[46:49], off
	global_store_dwordx4 v[50:51], v[38:41], off offset:528
	global_load_dwordx4 v[38:41], v[186:187], off offset:48
	global_load_dwordx4 v[42:45], v[186:187], off offset:32
	global_load_dwordx4 v[46:49], v[186:187], off offset:16
	global_load_dwordx4 v[50:53], v[186:187], off
	s_waitcnt vmcnt(2)
	v_add_f32_e32 v42, v42, v43
	v_add_f32_e32 v44, v44, v45
	s_waitcnt vmcnt(0)
	v_mov_b32_e32 v54, v51
	v_mov_b32_e32 v55, v52
	v_mov_b32_e32 v51, v53
	v_mov_b32_e32 v52, v47
	v_mov_b32_e32 v53, v48
	v_mov_b32_e32 v47, v49
	v_pk_add_f32 v[50:51], v[54:55], v[50:51]
	v_pk_add_f32 v[46:47], v[52:53], v[46:47]
	v_add_f32_e32 v50, v50, v51
	v_pk_add_f32 v[46:47], v[46:47], v[46:47] op_sel:[0,1] op_sel_hi:[1,0]
	v_add_f32_e32 v50, 0, v50
	v_mov_b32_e32 v51, v38
	v_mov_b32_e32 v47, v39
	v_mov_b32_e32 v43, v40
	v_mov_b32_e32 v45, v41
	v_pk_add_f32 v[38:39], v[50:51], v[46:47]
	v_pk_add_f32 v[40:41], v[42:43], v[44:45]
	s_nop 0
	v_pk_add_f32 v[38:39], v[38:39], v[40:41]
	s_nop 0
	v_add_f32_e32 v38, v38, v39
	v_fmamk_f32 v38, v38, 0x3a800000, v191
	v_cmp_gt_f32_e32 vcc, s28, v38
	v_mul_f32_e32 v39, 0x4b800000, v38
	s_nop 0
	v_cndmask_b32_e32 v38, v38, v39, vcc
	v_rsq_f32_e32 v38, v38
	s_nop 0
	v_mul_f32_e32 v39, 0x45800000, v38
	v_cndmask_b32_e32 v38, v38, v39, vcc
	v_pk_mul_f32 v[26:27], v[26:27], v[38:39] op_sel_hi:[1,0]
	v_pk_mul_f32 v[28:29], v[28:29], v[38:39] op_sel_hi:[1,0]
	v_pk_mul_f32 v[26:27], v[10:11], v[26:27]
	v_pk_mul_f32 v[28:29], v[12:13], v[28:29]
	global_store_dwordx4 v[34:35], v[26:29], off offset:16
	v_pk_mul_f32 v[30:31], v[30:31], v[38:39] op_sel_hi:[1,0]
	v_pk_mul_f32 v[32:33], v[32:33], v[38:39] op_sel_hi:[1,0]
	v_pk_mul_f32 v[26:27], v[166:167], v[38:39] op_sel_hi:[1,0]
	v_pk_mul_f32 v[28:29], v[162:163], v[38:39] op_sel_hi:[1,0]
	v_pk_mul_f32 v[26:27], v[6:7], v[26:27]
	v_pk_mul_f32 v[28:29], v[8:9], v[28:29]
	global_store_dwordx4 v[34:35], v[26:29], off offset:512
	v_pk_mul_f32 v[32:33], v[16:17], v[32:33]
	v_pk_mul_f32 v[30:31], v[14:15], v[30:31]
	v_pk_mul_f32 v[26:27], v[160:161], v[38:39] op_sel_hi:[1,0]
	v_pk_mul_f32 v[28:29], v[156:157], v[38:39] op_sel_hi:[1,0]
	v_pk_mul_f32 v[26:27], v[2:3], v[26:27]
	v_pk_mul_f32 v[28:29], v[4:5], v[28:29]
	global_store_dwordx4 v[34:35], v[30:33], off
	global_store_dwordx4 v[34:35], v[26:29], off offset:528
	global_load_dwordx4 v[26:29], v[188:189], off offset:48
	s_nop 0
	global_load_dwordx4 v[30:33], v[188:189], off offset:32
	global_load_dwordx4 v[38:41], v[188:189], off offset:16
	global_load_dwordx4 v[42:45], v[188:189], off
	s_waitcnt vmcnt(2)
	v_add_f32_e32 v30, v30, v31
	v_add_f32_e32 v32, v32, v33
	s_waitcnt vmcnt(0)
	v_mov_b32_e32 v34, v43
	v_mov_b32_e32 v35, v44
	v_mov_b32_e32 v43, v45
	v_pk_add_f32 v[34:35], v[34:35], v[42:43]
	v_mov_b32_e32 v42, v39
	v_mov_b32_e32 v43, v40
	v_mov_b32_e32 v39, v41
	v_pk_add_f32 v[38:39], v[42:43], v[38:39]
	v_add_f32_e32 v34, v34, v35
	v_pk_add_f32 v[38:39], v[38:39], v[38:39] op_sel:[0,1] op_sel_hi:[1,0]
	v_add_f32_e32 v34, 0, v34
	v_mov_b32_e32 v35, v26
	v_mov_b32_e32 v39, v27
	v_mov_b32_e32 v31, v28
	v_mov_b32_e32 v33, v29
	v_pk_add_f32 v[26:27], v[34:35], v[38:39]
	v_pk_add_f32 v[28:29], v[30:31], v[32:33]
	s_nop 0
	v_pk_add_f32 v[26:27], v[26:27], v[28:29]
	s_nop 0
	v_add_f32_e32 v26, v26, v27
	v_fmamk_f32 v26, v26, 0x3a800000, v191
	v_cmp_gt_f32_e32 vcc, s28, v26
	v_mul_f32_e32 v27, 0x4b800000, v26
	s_nop 0
	v_cndmask_b32_e32 v26, v26, v27, vcc
	v_rsq_f32_e32 v26, v26
	s_nop 0
	v_mul_f32_e32 v27, 0x45800000, v26
	v_cndmask_b32_e32 v26, v26, v27, vcc
	v_pk_mul_f32 v[28:29], v[36:37], v[26:27] op_sel_hi:[1,0]
	v_pk_mul_f32 v[24:25], v[24:25], v[26:27] op_sel_hi:[1,0]
	v_pk_mul_f32 v[14:15], v[14:15], v[28:29]
	v_pk_mul_f32 v[16:17], v[16:17], v[24:25]
	global_store_dwordx4 v[18:19], v[14:17], off
	s_andn2_b64 vcc, exec, s[48:49]
	s_nop 0
	v_pk_mul_f32 v[14:15], v[22:23], v[26:27] op_sel_hi:[1,0]
	v_pk_mul_f32 v[16:17], v[20:21], v[26:27] op_sel_hi:[1,0]
	v_pk_mul_f32 v[10:11], v[10:11], v[14:15]
	v_pk_mul_f32 v[12:13], v[12:13], v[16:17]
	global_store_dwordx4 v[18:19], v[10:13], off offset:16
	s_nop 1
	v_pk_mul_f32 v[10:11], v[172:173], v[26:27] op_sel_hi:[1,0]
	v_pk_mul_f32 v[12:13], v[170:171], v[26:27] op_sel_hi:[1,0]
	v_pk_mul_f32 v[6:7], v[6:7], v[10:11]
	v_pk_mul_f32 v[8:9], v[8:9], v[12:13]
	global_store_dwordx4 v[18:19], v[6:9], off offset:512
	s_nop 1
	v_pk_mul_f32 v[6:7], v[168:169], v[26:27] op_sel_hi:[1,0]
	v_pk_mul_f32 v[8:9], v[164:165], v[26:27] op_sel_hi:[1,0]
	v_pk_mul_f32 v[2:3], v[2:3], v[6:7]
	v_pk_mul_f32 v[4:5], v[4:5], v[8:9]
	global_store_dwordx4 v[18:19], v[2:5], off offset:528
	s_cbranch_vccnz .LBB0_261
	v_readlane_b32 s28, v234, 9
	v_readlane_b32 s29, v234, 10
	s_andn2_b64 vcc, exec, s[28:29]
	s_cbranch_vccnz .LBB0_260
	s_nop 0
	s_branch .LBB0_260

.LBB0_458:
	s_ashr_i32 s3, s3, 8
	s_cmp_eq_u32 s3, 1
	s_cselect_b64 s[60:61], -1, 0
	s_cmp_lg_u32 s3, 1
	s_cbranch_scc1 .LBB0_460
	s_nop 0

.LBB0_465:
	v_readlane_b32 s28, v237, 62
	v_readlane_b32 s29, v237, 63
	s_and_b64 s[34:35], s[6:7], s[28:29]
	s_and_b64 s[28:29], s[34:35], exec
	s_cselect_b32 s28, s58, s58
	s_ashr_i32 s29, s28, 31
	s_lshl_b64 s[28:29], s[28:29], 19
	s_add_u32 s66, s22, s28
	s_addc_u32 s67, s23, s29
	s_and_b64 s[28:29], s[34:35], exec
	v_mov_b32_e32 v129, 0
	s_cselect_b32 s81, s2, s43
	s_cselect_b32 s80, s30, s42
	s_andn2_b64 vcc, exec, s[62:63]
	v_mov_b32_e32 v128, v129
	v_mov_b32_e32 v127, v129
	v_mov_b32_e32 v126, v129
	v_mov_b32_e32 v125, v129
	v_mov_b32_e32 v124, v129
	v_mov_b32_e32 v123, v129
	v_mov_b32_e32 v122, v129
	v_mov_b32_e32 v113, v129
	v_mov_b32_e32 v112, v129
	v_mov_b32_e32 v111, v129
	v_mov_b32_e32 v110, v129
	v_mov_b32_e32 v109, v129
	v_mov_b32_e32 v108, v129
	v_mov_b32_e32 v107, v129
	v_mov_b32_e32 v106, v129
	v_mov_b32_e32 v97, v129
	v_mov_b32_e32 v96, v129
	v_mov_b32_e32 v95, v129
	v_mov_b32_e32 v94, v129
	v_mov_b32_e32 v93, v129
	v_mov_b32_e32 v92, v129
	v_mov_b32_e32 v91, v129
	v_mov_b32_e32 v90, v129
	v_mov_b32_e32 v81, v129
	v_mov_b32_e32 v80, v129
	v_mov_b32_e32 v79, v129
	v_mov_b32_e32 v78, v129
	v_mov_b32_e32 v77, v129
	v_mov_b32_e32 v76, v129
	v_mov_b32_e32 v75, v129
	v_mov_b32_e32 v74, v129
	v_mov_b32_e32 v121, v129
	v_mov_b32_e32 v120, v129
	v_mov_b32_e32 v119, v129
	v_mov_b32_e32 v118, v129
	v_mov_b32_e32 v117, v129
	v_mov_b32_e32 v116, v129
	v_mov_b32_e32 v115, v129
	v_mov_b32_e32 v114, v129
	v_mov_b32_e32 v105, v129
	v_mov_b32_e32 v104, v129
	v_mov_b32_e32 v103, v129
	v_mov_b32_e32 v102, v129
	v_mov_b32_e32 v101, v129
	v_mov_b32_e32 v100, v129
	v_mov_b32_e32 v99, v129
	v_mov_b32_e32 v98, v129
	v_mov_b32_e32 v89, v129
	v_mov_b32_e32 v88, v129
	v_mov_b32_e32 v87, v129
	v_mov_b32_e32 v86, v129
	v_mov_b32_e32 v85, v129
	v_mov_b32_e32 v84, v129
	v_mov_b32_e32 v83, v129
	v_mov_b32_e32 v82, v129
	v_mov_b32_e32 v73, v129
	v_mov_b32_e32 v72, v129
	v_mov_b32_e32 v71, v129
	v_mov_b32_e32 v70, v129
	v_mov_b32_e32 v69, v129
	v_mov_b32_e32 v68, v129
	v_mov_b32_e32 v67, v129
	v_mov_b32_e32 v66, v129
	v_mov_b32_e32 v65, v129
	v_mov_b32_e32 v64, v129
	v_mov_b32_e32 v63, v129
	v_mov_b32_e32 v62, v129
	v_mov_b32_e32 v61, v129
	v_mov_b32_e32 v60, v129
	v_mov_b32_e32 v59, v129
	v_mov_b32_e32 v58, v129
	v_mov_b32_e32 v49, v129
	v_mov_b32_e32 v48, v129
	v_mov_b32_e32 v47, v129
	v_mov_b32_e32 v46, v129
	v_mov_b32_e32 v45, v129
	v_mov_b32_e32 v44, v129
	v_mov_b32_e32 v43, v129
	v_mov_b32_e32 v42, v129
	v_mov_b32_e32 v33, v129
	v_mov_b32_e32 v32, v129
	v_mov_b32_e32 v31, v129
	v_mov_b32_e32 v30, v129
	v_mov_b32_e32 v29, v129
	v_mov_b32_e32 v28, v129
	v_mov_b32_e32 v27, v129
	v_mov_b32_e32 v26, v129
	v_mov_b32_e32 v17, v129
	v_mov_b32_e32 v16, v129
	v_mov_b32_e32 v15, v129
	v_mov_b32_e32 v14, v129
	v_mov_b32_e32 v13, v129
	v_mov_b32_e32 v12, v129
	v_mov_b32_e32 v11, v129
	v_mov_b32_e32 v10, v129
	v_mov_b32_e32 v57, v129
	v_mov_b32_e32 v56, v129
	v_mov_b32_e32 v55, v129
	v_mov_b32_e32 v54, v129
	v_mov_b32_e32 v53, v129
	v_mov_b32_e32 v52, v129
	v_mov_b32_e32 v51, v129
	v_mov_b32_e32 v50, v129
	v_mov_b32_e32 v41, v129
	v_mov_b32_e32 v40, v129
	v_mov_b32_e32 v39, v129
	v_mov_b32_e32 v38, v129
	v_mov_b32_e32 v37, v129
	v_mov_b32_e32 v36, v129
	v_mov_b32_e32 v35, v129
	v_mov_b32_e32 v34, v129
	v_mov_b32_e32 v25, v129
	v_mov_b32_e32 v24, v129
	v_mov_b32_e32 v23, v129
	v_mov_b32_e32 v22, v129
	v_mov_b32_e32 v21, v129
	v_mov_b32_e32 v20, v129
	v_mov_b32_e32 v19, v129
	v_mov_b32_e32 v18, v129
	v_mov_b32_e32 v9, v129
	v_mov_b32_e32 v8, v129
	v_mov_b32_e32 v7, v129
	v_mov_b32_e32 v6, v129
	v_mov_b32_e32 v5, v129
	v_mov_b32_e32 v4, v129
	v_mov_b32_e32 v3, v129
	v_mov_b32_e32 v2, v129
	s_cbranch_vccnz .LBB0_468
	s_and_b64 s[28:29], s[34:35], exec
	s_cselect_b32 s28, s67, s41
	s_cselect_b32 s29, s66, s40
	s_add_u32 s40, s40, 0x80
	s_addc_u32 s41, s41, 0
	s_add_u32 s44, s42, 0x100
	v_mov_b32_e32 v2, 0
	s_addc_u32 s45, s43, 0
	s_mov_b32 s42, 0
	v_mov_b32_e32 v3, v2
	v_mov_b32_e32 v4, v2
	v_mov_b32_e32 v5, v2
	v_mov_b32_e32 v6, v2
	v_mov_b32_e32 v7, v2
	v_mov_b32_e32 v8, v2
	v_mov_b32_e32 v9, v2
	v_mov_b32_e32 v18, v2
	v_mov_b32_e32 v19, v2
	v_mov_b32_e32 v20, v2
	v_mov_b32_e32 v21, v2
	v_mov_b32_e32 v22, v2
	v_mov_b32_e32 v23, v2
	v_mov_b32_e32 v24, v2
	v_mov_b32_e32 v25, v2
	v_mov_b32_e32 v34, v2
	v_mov_b32_e32 v35, v2
	v_mov_b32_e32 v36, v2
	v_mov_b32_e32 v37, v2
	v_mov_b32_e32 v38, v2
	v_mov_b32_e32 v39, v2
	v_mov_b32_e32 v40, v2
	v_mov_b32_e32 v41, v2
	v_mov_b32_e32 v50, v2
	v_mov_b32_e32 v51, v2
	v_mov_b32_e32 v52, v2
	v_mov_b32_e32 v53, v2
	v_mov_b32_e32 v54, v2
	v_mov_b32_e32 v55, v2
	v_mov_b32_e32 v56, v2
	v_mov_b32_e32 v57, v2
	v_mov_b32_e32 v10, v2
	v_mov_b32_e32 v11, v2
	v_mov_b32_e32 v12, v2
	v_mov_b32_e32 v13, v2
	v_mov_b32_e32 v14, v2
	v_mov_b32_e32 v15, v2
	v_mov_b32_e32 v16, v2
	v_mov_b32_e32 v17, v2
	v_mov_b32_e32 v26, v2
	v_mov_b32_e32 v27, v2
	v_mov_b32_e32 v28, v2
	v_mov_b32_e32 v29, v2
	v_mov_b32_e32 v30, v2
	v_mov_b32_e32 v31, v2
	v_mov_b32_e32 v32, v2
	v_mov_b32_e32 v33, v2
	v_mov_b32_e32 v42, v2
	v_mov_b32_e32 v43, v2
	v_mov_b32_e32 v44, v2
	v_mov_b32_e32 v45, v2
	v_mov_b32_e32 v46, v2
	v_mov_b32_e32 v47, v2
	v_mov_b32_e32 v48, v2
	v_mov_b32_e32 v49, v2
	v_mov_b32_e32 v58, v2
	v_mov_b32_e32 v59, v2
	v_mov_b32_e32 v60, v2
	v_mov_b32_e32 v61, v2
	v_mov_b32_e32 v62, v2
	v_mov_b32_e32 v63, v2
	v_mov_b32_e32 v64, v2
	v_mov_b32_e32 v65, v2
	v_mov_b32_e32 v66, v2
	v_mov_b32_e32 v67, v2
	v_mov_b32_e32 v68, v2
	v_mov_b32_e32 v69, v2
	v_mov_b32_e32 v70, v2
	v_mov_b32_e32 v71, v2
	v_mov_b32_e32 v72, v2
	v_mov_b32_e32 v73, v2
	v_mov_b32_e32 v82, v2
	v_mov_b32_e32 v83, v2
	v_mov_b32_e32 v84, v2
	v_mov_b32_e32 v85, v2
	v_mov_b32_e32 v86, v2
	v_mov_b32_e32 v87, v2
	v_mov_b32_e32 v88, v2
	v_mov_b32_e32 v89, v2
	v_mov_b32_e32 v98, v2
	v_mov_b32_e32 v99, v2
	v_mov_b32_e32 v100, v2
	v_mov_b32_e32 v101, v2
	v_mov_b32_e32 v102, v2
	v_mov_b32_e32 v103, v2
	v_mov_b32_e32 v104, v2
	v_mov_b32_e32 v105, v2
	v_mov_b32_e32 v114, v2
	v_mov_b32_e32 v115, v2
	v_mov_b32_e32 v116, v2
	v_mov_b32_e32 v117, v2
	v_mov_b32_e32 v118, v2
	v_mov_b32_e32 v119, v2
	v_mov_b32_e32 v120, v2
	v_mov_b32_e32 v121, v2
	v_mov_b32_e32 v74, v2
	v_mov_b32_e32 v75, v2
	v_mov_b32_e32 v76, v2
	v_mov_b32_e32 v77, v2
	v_mov_b32_e32 v78, v2
	v_mov_b32_e32 v79, v2
	v_mov_b32_e32 v80, v2
	v_mov_b32_e32 v81, v2
	v_mov_b32_e32 v90, v2
	v_mov_b32_e32 v91, v2
	v_mov_b32_e32 v92, v2
	v_mov_b32_e32 v93, v2
	v_mov_b32_e32 v94, v2
	v_mov_b32_e32 v95, v2
	v_mov_b32_e32 v96, v2
	v_mov_b32_e32 v97, v2
	v_mov_b32_e32 v106, v2
	v_mov_b32_e32 v107, v2
	v_mov_b32_e32 v108, v2
	v_mov_b32_e32 v109, v2
	v_mov_b32_e32 v110, v2
	v_mov_b32_e32 v111, v2
	v_mov_b32_e32 v112, v2
	v_mov_b32_e32 v113, v2
	v_mov_b32_e32 v122, v2
	v_mov_b32_e32 v123, v2
	v_mov_b32_e32 v124, v2
	v_mov_b32_e32 v125, v2
	v_mov_b32_e32 v126, v2
	v_mov_b32_e32 v127, v2
	v_mov_b32_e32 v128, v2
	v_mov_b32_e32 v129, v2
	s_bitcmp1_b32 s38, 0
	s_cbranch_scc0 .Lmy_q467
.LBB0_467:
	s_add_i32 s46, s42, 2
	s_add_u32 s47, s40, 0x80
	s_addc_u32 s43, s41, 0
	s_add_i32 s50, 0, 0x10000
	s_cmp_eq_u32 s75, s42
	s_cselect_b32 s43, s28, s43
	s_cselect_b32 s42, s29, s47
	v_add_u32_e32 v0, s50, v180
	s_cselect_b32 s49, s81, s45
	s_cselect_b32 s48, s80, s44
	s_add_i32 s47, 0, 0x14000
	ds_read_b128 v[130:133], v0
	ds_read_b128 v[134:137], v0 offset:1024
	ds_read_b128 v[138:141], v0 offset:2048
	ds_read_b128 v[142:145], v0 offset:3072
	v_add_u32_e32 v0, s47, v180
	ds_read_b128 v[158:161], v0
	ds_read_b128 v[162:165], v0 offset:1024
	ds_read_b128 v[166:169], v0 offset:2048
	ds_read_b128 v[170:173], v0 offset:3072
	v_lshl_add_u64 v[220:221], s[40:41], 0, v[152:153]
	s_mov_b32 m0, s27
	s_nop 0
	global_load_lds_dwordx4 v[220:221], off
	v_lshl_add_u64 v[220:221], s[40:41], 0, v[148:149]
	s_mov_b32 m0, s72
	s_nop 0
	global_load_lds_dwordx4 v[220:221], off
	v_lshl_add_u64 v[220:221], s[40:41], 0, v[154:155]
	s_add_i32 m0, s53, 0xc000
	s_nop 0
	global_load_lds_dwordx4 v[220:221], off
	v_lshl_add_u64 v[220:221], s[40:41], 0, v[156:157]
	s_add_i32 m0, s53, 0xe000
	s_nop 0
	global_load_lds_dwordx4 v[220:221], off
	ds_read_b128 v[174:177], v181
	ds_read_b128 v[182:185], v181 offset:1024
	ds_read_b128 v[186:189], v181 offset:2048
	ds_read_b128 v[200:203], v181 offset:3072
	ds_read_b128 v[204:207], v181 offset:4096
	ds_read_b128 v[208:211], v181 offset:5120
	ds_read_b128 v[212:215], v181 offset:6144
	ds_read_b128 v[216:219], v181 offset:7168
	s_waitcnt vmcnt(8)
	s_waitcnt lgkmcnt(0)
	s_barrier
	s_setprio 1
	s_waitcnt lgkmcnt(0)
	v_mfma_f32_16x16x32_bf16 v[126:129], v[130:133], v[174:177], v[126:129]
	v_mfma_f32_16x16x32_bf16 v[122:125], v[138:141], v[174:177], v[122:125]
	v_mfma_f32_16x16x32_bf16 v[110:113], v[130:133], v[186:189], v[110:113]
	v_mfma_f32_16x16x32_bf16 v[106:109], v[138:141], v[186:189], v[106:109]
	v_mfma_f32_16x16x32_bf16 v[94:97], v[130:133], v[204:207], v[94:97]
	v_mfma_f32_16x16x32_bf16 v[90:93], v[138:141], v[204:207], v[90:93]
	v_mfma_f32_16x16x32_bf16 v[78:81], v[130:133], v[212:215], v[78:81]
	v_mfma_f32_16x16x32_bf16 v[74:77], v[138:141], v[212:215], v[74:77]
	v_mfma_f32_16x16x32_bf16 v[126:129], v[134:137], v[182:185], v[126:129]
	v_mfma_f32_16x16x32_bf16 v[122:125], v[142:145], v[182:185], v[122:125]
	v_mfma_f32_16x16x32_bf16 v[110:113], v[134:137], v[200:203], v[110:113]
	v_mfma_f32_16x16x32_bf16 v[106:109], v[142:145], v[200:203], v[106:109]
	v_mfma_f32_16x16x32_bf16 v[94:97], v[134:137], v[208:211], v[94:97]
	v_mfma_f32_16x16x32_bf16 v[90:93], v[142:145], v[208:211], v[90:93]
	v_mfma_f32_16x16x32_bf16 v[78:81], v[134:137], v[216:219], v[78:81]
	v_mfma_f32_16x16x32_bf16 v[74:77], v[142:145], v[216:219], v[74:77]
	s_setprio 0
	s_setprio 1
	v_mfma_f32_16x16x32_bf16 v[118:121], v[158:161], v[174:177], v[118:121]
	v_mfma_f32_16x16x32_bf16 v[114:117], v[166:169], v[174:177], v[114:117]
	v_mfma_f32_16x16x32_bf16 v[102:105], v[158:161], v[186:189], v[102:105]
	v_mfma_f32_16x16x32_bf16 v[98:101], v[166:169], v[186:189], v[98:101]
	v_mfma_f32_16x16x32_bf16 v[86:89], v[158:161], v[204:207], v[86:89]
	v_mfma_f32_16x16x32_bf16 v[82:85], v[166:169], v[204:207], v[82:85]
	v_mfma_f32_16x16x32_bf16 v[70:73], v[158:161], v[212:215], v[70:73]
	v_mfma_f32_16x16x32_bf16 v[66:69], v[166:169], v[212:215], v[66:69]
	v_mfma_f32_16x16x32_bf16 v[118:121], v[162:165], v[182:185], v[118:121]
	v_mfma_f32_16x16x32_bf16 v[114:117], v[170:173], v[182:185], v[114:117]
	v_mfma_f32_16x16x32_bf16 v[102:105], v[162:165], v[200:203], v[102:105]
	v_mfma_f32_16x16x32_bf16 v[98:101], v[170:173], v[200:203], v[98:101]
	v_mfma_f32_16x16x32_bf16 v[86:89], v[162:165], v[208:211], v[86:89]
	v_mfma_f32_16x16x32_bf16 v[82:85], v[170:173], v[208:211], v[82:85]
	v_mfma_f32_16x16x32_bf16 v[70:73], v[162:165], v[216:219], v[70:73]
	v_mfma_f32_16x16x32_bf16 v[66:69], v[170:173], v[216:219], v[66:69]
	s_setprio 0
	s_add_i32 s50, s50, s31
	v_lshl_add_u64 v[220:221], s[48:49], 0, v[150:151]
	s_mov_b32 m0, s50
	ds_read_b128 v[174:177], v181 offset:16384
	ds_read_b128 v[182:185], v181 offset:17408
	ds_read_b128 v[186:189], v181 offset:18432
	ds_read_b128 v[200:203], v181 offset:19456
	ds_read_b128 v[204:207], v181 offset:20480
	ds_read_b128 v[208:211], v181 offset:21504
	ds_read_b128 v[212:215], v181 offset:22528
	ds_read_b128 v[216:219], v181 offset:23552
	global_load_lds_dwordx4 v[220:221], off
	s_add_i32 m0, s50, 0x2000
	v_lshl_add_u64 v[222:223], s[48:49], 0, v[146:147]
	s_add_u32 s48, s48, s56
	s_addc_u32 s49, s49, s57
	s_add_i32 s47, s47, s31
	global_load_lds_dwordx4 v[222:223], off
	v_lshl_add_u64 v[224:225], s[48:49], 0, v[150:151]
	s_mov_b32 m0, s47
	v_lshl_add_u64 v[226:227], s[48:49], 0, v[146:147]
	global_load_lds_dwordx4 v[224:225], off
	s_add_i32 m0, s47, 0x2000
	v_lshl_add_u64 v[228:229], s[42:43], 0, v[152:153]
	global_load_lds_dwordx4 v[226:227], off
	v_lshl_add_u64 v[230:231], s[42:43], 0, v[148:149]
	s_waitcnt vmcnt(6)
	s_waitcnt lgkmcnt(0)
	s_barrier
	s_setprio 1
	s_waitcnt lgkmcnt(0)
	v_mfma_f32_16x16x32_bf16 v[62:65], v[130:133], v[174:177], v[62:65]
	v_mfma_f32_16x16x32_bf16 v[58:61], v[138:141], v[174:177], v[58:61]
	v_mfma_f32_16x16x32_bf16 v[46:49], v[130:133], v[186:189], v[46:49]
	v_mfma_f32_16x16x32_bf16 v[42:45], v[138:141], v[186:189], v[42:45]
	v_mfma_f32_16x16x32_bf16 v[30:33], v[130:133], v[204:207], v[30:33]
	v_mfma_f32_16x16x32_bf16 v[26:29], v[138:141], v[204:207], v[26:29]
	v_mfma_f32_16x16x32_bf16 v[14:17], v[130:133], v[212:215], v[14:17]
	v_mfma_f32_16x16x32_bf16 v[10:13], v[138:141], v[212:215], v[10:13]
	v_mfma_f32_16x16x32_bf16 v[62:65], v[134:137], v[182:185], v[62:65]
	v_mfma_f32_16x16x32_bf16 v[58:61], v[142:145], v[182:185], v[58:61]
	v_mfma_f32_16x16x32_bf16 v[46:49], v[134:137], v[200:203], v[46:49]
	v_mfma_f32_16x16x32_bf16 v[42:45], v[142:145], v[200:203], v[42:45]
	v_mfma_f32_16x16x32_bf16 v[30:33], v[134:137], v[208:211], v[30:33]
	v_mfma_f32_16x16x32_bf16 v[26:29], v[142:145], v[208:211], v[26:29]
	v_mfma_f32_16x16x32_bf16 v[14:17], v[134:137], v[216:219], v[14:17]
	v_mfma_f32_16x16x32_bf16 v[10:13], v[142:145], v[216:219], v[10:13]
	s_setprio 0
	s_setprio 1
	v_mfma_f32_16x16x32_bf16 v[54:57], v[158:161], v[174:177], v[54:57]
	v_mfma_f32_16x16x32_bf16 v[50:53], v[166:169], v[174:177], v[50:53]
	v_mfma_f32_16x16x32_bf16 v[38:41], v[158:161], v[186:189], v[38:41]
	v_mfma_f32_16x16x32_bf16 v[34:37], v[166:169], v[186:189], v[34:37]
	v_mfma_f32_16x16x32_bf16 v[22:25], v[158:161], v[204:207], v[22:25]
	v_mfma_f32_16x16x32_bf16 v[18:21], v[166:169], v[204:207], v[18:21]
	v_mfma_f32_16x16x32_bf16 v[6:9], v[158:161], v[212:215], v[6:9]
	v_mfma_f32_16x16x32_bf16 v[2:5], v[166:169], v[212:215], v[2:5]
	v_mfma_f32_16x16x32_bf16 v[54:57], v[162:165], v[182:185], v[54:57]
	v_mfma_f32_16x16x32_bf16 v[50:53], v[170:173], v[182:185], v[50:53]
	v_mfma_f32_16x16x32_bf16 v[38:41], v[162:165], v[200:203], v[38:41]
	v_mfma_f32_16x16x32_bf16 v[34:37], v[170:173], v[200:203], v[34:37]
	v_mfma_f32_16x16x32_bf16 v[22:25], v[162:165], v[208:211], v[22:25]
	v_mfma_f32_16x16x32_bf16 v[18:21], v[170:173], v[208:211], v[18:21]
	v_mfma_f32_16x16x32_bf16 v[6:9], v[162:165], v[216:219], v[6:9]
	v_mfma_f32_16x16x32_bf16 v[2:5], v[170:173], v[216:219], v[2:5]
	s_setprio 0
	s_add_i32 s47, 0, 0x18000
	v_add_u32_e32 v0, s47, v180
	s_add_i32 s48, 0, 0x1c000
	ds_read_b128 v[130:133], v0
	ds_read_b128 v[134:137], v0 offset:1024
	ds_read_b128 v[138:141], v0 offset:2048
	ds_read_b128 v[142:145], v0 offset:3072
	v_add_u32_e32 v0, s48, v180
	ds_read_b128 v[158:161], v0
	ds_read_b128 v[162:165], v0 offset:1024
	ds_read_b128 v[166:169], v0 offset:2048
	ds_read_b128 v[170:173], v0 offset:3072
	s_add_u32 s42, s42, s54
	s_addc_u32 s43, s43, s55
	s_mov_b32 m0, s53
	v_lshl_add_u64 v[232:233], s[42:43], 0, v[152:153]
	s_nop 0
	global_load_lds_dwordx4 v[228:229], off
	s_mov_b32 m0, s4
	s_nop 0
	global_load_lds_dwordx4 v[230:231], off
	s_mov_b32 m0, s82
	s_nop 0
	global_load_lds_dwordx4 v[232:233], off
	v_lshl_add_u64 v[232:233], s[42:43], 0, v[148:149]
	s_mov_b32 m0, s83
	s_nop 0
	global_load_lds_dwordx4 v[232:233], off
	ds_read_b128 v[174:177], v181 offset:32768
	ds_read_b128 v[182:185], v181 offset:33792
	ds_read_b128 v[186:189], v181 offset:34816
	ds_read_b128 v[200:203], v181 offset:35840
	ds_read_b128 v[204:207], v181 offset:36864
	ds_read_b128 v[208:211], v181 offset:37888
	ds_read_b128 v[212:215], v181 offset:38912
	ds_read_b128 v[216:219], v181 offset:39936
	s_waitcnt vmcnt(8)
	s_waitcnt lgkmcnt(0)
	s_barrier
	s_setprio 1
	s_waitcnt lgkmcnt(0)
	v_mfma_f32_16x16x32_bf16 v[126:129], v[130:133], v[174:177], v[126:129]
	v_mfma_f32_16x16x32_bf16 v[122:125], v[138:141], v[174:177], v[122:125]
	v_mfma_f32_16x16x32_bf16 v[110:113], v[130:133], v[186:189], v[110:113]
	v_mfma_f32_16x16x32_bf16 v[106:109], v[138:141], v[186:189], v[106:109]
	v_mfma_f32_16x16x32_bf16 v[94:97], v[130:133], v[204:207], v[94:97]
	v_mfma_f32_16x16x32_bf16 v[90:93], v[138:141], v[204:207], v[90:93]
	v_mfma_f32_16x16x32_bf16 v[78:81], v[130:133], v[212:215], v[78:81]
	v_mfma_f32_16x16x32_bf16 v[74:77], v[138:141], v[212:215], v[74:77]
	v_mfma_f32_16x16x32_bf16 v[126:129], v[134:137], v[182:185], v[126:129]
	v_mfma_f32_16x16x32_bf16 v[122:125], v[142:145], v[182:185], v[122:125]
	v_mfma_f32_16x16x32_bf16 v[110:113], v[134:137], v[200:203], v[110:113]
	v_mfma_f32_16x16x32_bf16 v[106:109], v[142:145], v[200:203], v[106:109]
	v_mfma_f32_16x16x32_bf16 v[94:97], v[134:137], v[208:211], v[94:97]
	v_mfma_f32_16x16x32_bf16 v[90:93], v[142:145], v[208:211], v[90:93]
	v_mfma_f32_16x16x32_bf16 v[78:81], v[134:137], v[216:219], v[78:81]
	v_mfma_f32_16x16x32_bf16 v[74:77], v[142:145], v[216:219], v[74:77]
	s_setprio 0
	s_setprio 1
	v_mfma_f32_16x16x32_bf16 v[118:121], v[158:161], v[174:177], v[118:121]
	v_mfma_f32_16x16x32_bf16 v[114:117], v[166:169], v[174:177], v[114:117]
	v_mfma_f32_16x16x32_bf16 v[102:105], v[158:161], v[186:189], v[102:105]
	v_mfma_f32_16x16x32_bf16 v[98:101], v[166:169], v[186:189], v[98:101]
	v_mfma_f32_16x16x32_bf16 v[86:89], v[158:161], v[204:207], v[86:89]
	v_mfma_f32_16x16x32_bf16 v[82:85], v[166:169], v[204:207], v[82:85]
	v_mfma_f32_16x16x32_bf16 v[70:73], v[158:161], v[212:215], v[70:73]
	v_mfma_f32_16x16x32_bf16 v[66:69], v[166:169], v[212:215], v[66:69]
	v_mfma_f32_16x16x32_bf16 v[118:121], v[162:165], v[182:185], v[118:121]
	v_mfma_f32_16x16x32_bf16 v[114:117], v[170:173], v[182:185], v[114:117]
	v_mfma_f32_16x16x32_bf16 v[102:105], v[162:165], v[200:203], v[102:105]
	v_mfma_f32_16x16x32_bf16 v[98:101], v[170:173], v[200:203], v[98:101]
	v_mfma_f32_16x16x32_bf16 v[86:89], v[162:165], v[208:211], v[86:89]
	v_mfma_f32_16x16x32_bf16 v[82:85], v[170:173], v[208:211], v[82:85]
	v_mfma_f32_16x16x32_bf16 v[70:73], v[162:165], v[216:219], v[70:73]
	v_mfma_f32_16x16x32_bf16 v[66:69], v[170:173], v[216:219], v[66:69]
	s_setprio 0
	s_add_i32 s42, s47, s31
	v_lshl_add_u64 v[220:221], v[220:221], 0, s[24:25]
	s_mov_b32 m0, s42
	ds_read_b128 v[174:177], v181 offset:49152
	ds_read_b128 v[182:185], v181 offset:50176
	ds_read_b128 v[186:189], v181 offset:51200
	ds_read_b128 v[200:203], v181 offset:52224
	ds_read_b128 v[204:207], v181 offset:53248
	ds_read_b128 v[208:211], v181 offset:54272
	ds_read_b128 v[212:215], v181 offset:55296
	ds_read_b128 v[216:219], v181 offset:56320
	global_load_lds_dwordx4 v[220:221], off
	v_lshl_add_u64 v[220:221], v[222:223], 0, s[24:25]
	s_add_i32 m0, s42, 0x2000
	s_add_i32 s42, s48, s31
	global_load_lds_dwordx4 v[220:221], off
	v_lshl_add_u64 v[220:221], v[224:225], 0, s[24:25]
	s_mov_b32 m0, s42
	s_nop 0
	global_load_lds_dwordx4 v[220:221], off
	v_lshl_add_u64 v[220:221], v[226:227], 0, s[24:25]
	s_add_i32 m0, s42, 0x2000
	s_nop 0
	global_load_lds_dwordx4 v[220:221], off
	s_waitcnt vmcnt(6)
	s_waitcnt lgkmcnt(0)
	s_barrier
	s_setprio 1
	s_waitcnt lgkmcnt(0)
	v_mfma_f32_16x16x32_bf16 v[62:65], v[130:133], v[174:177], v[62:65]
	v_mfma_f32_16x16x32_bf16 v[58:61], v[138:141], v[174:177], v[58:61]
	v_mfma_f32_16x16x32_bf16 v[46:49], v[130:133], v[186:189], v[46:49]
	v_mfma_f32_16x16x32_bf16 v[42:45], v[138:141], v[186:189], v[42:45]
	v_mfma_f32_16x16x32_bf16 v[30:33], v[130:133], v[204:207], v[30:33]
	v_mfma_f32_16x16x32_bf16 v[26:29], v[138:141], v[204:207], v[26:29]
	v_mfma_f32_16x16x32_bf16 v[14:17], v[130:133], v[212:215], v[14:17]
	v_mfma_f32_16x16x32_bf16 v[10:13], v[138:141], v[212:215], v[10:13]
	v_mfma_f32_16x16x32_bf16 v[62:65], v[134:137], v[182:185], v[62:65]
	v_mfma_f32_16x16x32_bf16 v[58:61], v[142:145], v[182:185], v[58:61]
	v_mfma_f32_16x16x32_bf16 v[46:49], v[134:137], v[200:203], v[46:49]
	v_mfma_f32_16x16x32_bf16 v[42:45], v[142:145], v[200:203], v[42:45]
	v_mfma_f32_16x16x32_bf16 v[30:33], v[134:137], v[208:211], v[30:33]
	v_mfma_f32_16x16x32_bf16 v[26:29], v[142:145], v[208:211], v[26:29]
	v_mfma_f32_16x16x32_bf16 v[14:17], v[134:137], v[216:219], v[14:17]
	v_mfma_f32_16x16x32_bf16 v[10:13], v[142:145], v[216:219], v[10:13]
	s_setprio 0
	s_setprio 1
	v_mfma_f32_16x16x32_bf16 v[54:57], v[158:161], v[174:177], v[54:57]
	v_mfma_f32_16x16x32_bf16 v[50:53], v[166:169], v[174:177], v[50:53]
	v_mfma_f32_16x16x32_bf16 v[38:41], v[158:161], v[186:189], v[38:41]
	v_mfma_f32_16x16x32_bf16 v[34:37], v[166:169], v[186:189], v[34:37]
	v_mfma_f32_16x16x32_bf16 v[22:25], v[158:161], v[204:207], v[22:25]
	v_mfma_f32_16x16x32_bf16 v[18:21], v[166:169], v[204:207], v[18:21]
	v_mfma_f32_16x16x32_bf16 v[6:9], v[158:161], v[212:215], v[6:9]
	v_mfma_f32_16x16x32_bf16 v[2:5], v[166:169], v[212:215], v[2:5]
	v_mfma_f32_16x16x32_bf16 v[54:57], v[162:165], v[182:185], v[54:57]
	v_mfma_f32_16x16x32_bf16 v[50:53], v[170:173], v[182:185], v[50:53]
	v_mfma_f32_16x16x32_bf16 v[38:41], v[162:165], v[200:203], v[38:41]
	v_mfma_f32_16x16x32_bf16 v[34:37], v[170:173], v[200:203], v[34:37]
	v_mfma_f32_16x16x32_bf16 v[22:25], v[162:165], v[208:211], v[22:25]
	v_mfma_f32_16x16x32_bf16 v[18:21], v[170:173], v[208:211], v[18:21]
	v_mfma_f32_16x16x32_bf16 v[6:9], v[162:165], v[216:219], v[6:9]
	v_mfma_f32_16x16x32_bf16 v[2:5], v[170:173], v[216:219], v[2:5]
	s_setprio 0
	s_add_u32 s40, s40, 0x100
	s_addc_u32 s41, s41, 0
	s_add_u32 s44, s44, 0x100
	s_addc_u32 s45, s45, 0
	s_cmp_ge_i32 s46, s74
	s_mov_b32 s42, s46
	s_cbranch_scc0 .LBB0_467
	s_branch .Lmy_post467
.Lmy_q467:
	s_add_i32 s46, s42, 2
	s_add_u32 s47, s40, 0x80
	s_addc_u32 s43, s41, 0
	s_add_i32 s50, 0, 0x10000
	s_cmp_eq_u32 s75, s42
	s_cselect_b32 s43, s28, s43
	s_cselect_b32 s42, s29, s47
	v_add_u32_e32 v0, s50, v180
	s_cselect_b32 s49, s81, s45
	s_cselect_b32 s48, s80, s44
	s_add_i32 s47, 0, 0x14000
	ds_read_b128 v[130:133], v0
	ds_read_b128 v[134:137], v0 offset:1024
	ds_read_b128 v[138:141], v0 offset:2048
	ds_read_b128 v[142:145], v0 offset:3072
	v_add_u32_e32 v0, s47, v180
	ds_read_b128 v[158:161], v0
	ds_read_b128 v[162:165], v0 offset:1024
	ds_read_b128 v[166:169], v0 offset:2048
	ds_read_b128 v[170:173], v0 offset:3072
	v_lshl_add_u64 v[220:221], s[40:41], 0, v[152:153]
	s_mov_b32 m0, s27
	s_nop 0
	global_load_lds_dwordx4 v[220:221], off
	v_lshl_add_u64 v[220:221], s[40:41], 0, v[148:149]
	s_mov_b32 m0, s72
	s_nop 0
	global_load_lds_dwordx4 v[220:221], off
	v_lshl_add_u64 v[220:221], s[40:41], 0, v[154:155]
	s_add_i32 m0, s53, 0xc000
	s_nop 0
	global_load_lds_dwordx4 v[220:221], off
	v_lshl_add_u64 v[220:221], s[40:41], 0, v[156:157]
	s_add_i32 m0, s53, 0xe000
	s_nop 0
	global_load_lds_dwordx4 v[220:221], off
	ds_read_b128 v[174:177], v181
	ds_read_b128 v[182:185], v181 offset:1024
	ds_read_b128 v[186:189], v181 offset:2048
	ds_read_b128 v[200:203], v181 offset:3072
	ds_read_b128 v[204:207], v181 offset:4096
	ds_read_b128 v[208:211], v181 offset:5120
	ds_read_b128 v[212:215], v181 offset:6144
	ds_read_b128 v[216:219], v181 offset:7168
	s_waitcnt vmcnt(8)
	s_waitcnt lgkmcnt(0)
	s_setprio 1
	s_waitcnt lgkmcnt(0)
	v_mfma_f32_16x16x32_bf16 v[126:129], v[130:133], v[174:177], v[126:129]
	v_mfma_f32_16x16x32_bf16 v[122:125], v[138:141], v[174:177], v[122:125]
	v_mfma_f32_16x16x32_bf16 v[110:113], v[130:133], v[186:189], v[110:113]
	v_mfma_f32_16x16x32_bf16 v[106:109], v[138:141], v[186:189], v[106:109]
	v_mfma_f32_16x16x32_bf16 v[94:97], v[130:133], v[204:207], v[94:97]
	v_mfma_f32_16x16x32_bf16 v[90:93], v[138:141], v[204:207], v[90:93]
	v_mfma_f32_16x16x32_bf16 v[78:81], v[130:133], v[212:215], v[78:81]
	v_mfma_f32_16x16x32_bf16 v[74:77], v[138:141], v[212:215], v[74:77]
	v_mfma_f32_16x16x32_bf16 v[126:129], v[134:137], v[182:185], v[126:129]
	v_mfma_f32_16x16x32_bf16 v[122:125], v[142:145], v[182:185], v[122:125]
	v_mfma_f32_16x16x32_bf16 v[110:113], v[134:137], v[200:203], v[110:113]
	v_mfma_f32_16x16x32_bf16 v[106:109], v[142:145], v[200:203], v[106:109]
	v_mfma_f32_16x16x32_bf16 v[94:97], v[134:137], v[208:211], v[94:97]
	v_mfma_f32_16x16x32_bf16 v[90:93], v[142:145], v[208:211], v[90:93]
	v_mfma_f32_16x16x32_bf16 v[78:81], v[134:137], v[216:219], v[78:81]
	v_mfma_f32_16x16x32_bf16 v[74:77], v[142:145], v[216:219], v[74:77]
	s_setprio 0
	s_setprio 1
	v_mfma_f32_16x16x32_bf16 v[118:121], v[158:161], v[174:177], v[118:121]
	v_mfma_f32_16x16x32_bf16 v[114:117], v[166:169], v[174:177], v[114:117]
	v_mfma_f32_16x16x32_bf16 v[102:105], v[158:161], v[186:189], v[102:105]
	v_mfma_f32_16x16x32_bf16 v[98:101], v[166:169], v[186:189], v[98:101]
	v_mfma_f32_16x16x32_bf16 v[86:89], v[158:161], v[204:207], v[86:89]
	v_mfma_f32_16x16x32_bf16 v[82:85], v[166:169], v[204:207], v[82:85]
	v_mfma_f32_16x16x32_bf16 v[70:73], v[158:161], v[212:215], v[70:73]
	v_mfma_f32_16x16x32_bf16 v[66:69], v[166:169], v[212:215], v[66:69]
	v_mfma_f32_16x16x32_bf16 v[118:121], v[162:165], v[182:185], v[118:121]
	v_mfma_f32_16x16x32_bf16 v[114:117], v[170:173], v[182:185], v[114:117]
	v_mfma_f32_16x16x32_bf16 v[102:105], v[162:165], v[200:203], v[102:105]
	v_mfma_f32_16x16x32_bf16 v[98:101], v[170:173], v[200:203], v[98:101]
	v_mfma_f32_16x16x32_bf16 v[86:89], v[162:165], v[208:211], v[86:89]
	v_mfma_f32_16x16x32_bf16 v[82:85], v[170:173], v[208:211], v[82:85]
	v_mfma_f32_16x16x32_bf16 v[70:73], v[162:165], v[216:219], v[70:73]
	v_mfma_f32_16x16x32_bf16 v[66:69], v[170:173], v[216:219], v[66:69]
	s_setprio 0
	s_barrier
	s_add_i32 s50, s50, s31
	v_lshl_add_u64 v[220:221], s[48:49], 0, v[150:151]
	s_mov_b32 m0, s50
	ds_read_b128 v[174:177], v181 offset:16384
	ds_read_b128 v[182:185], v181 offset:17408
	ds_read_b128 v[186:189], v181 offset:18432
	ds_read_b128 v[200:203], v181 offset:19456
	ds_read_b128 v[204:207], v181 offset:20480
	ds_read_b128 v[208:211], v181 offset:21504
	ds_read_b128 v[212:215], v181 offset:22528
	ds_read_b128 v[216:219], v181 offset:23552
	global_load_lds_dwordx4 v[220:221], off
	s_add_i32 m0, s50, 0x2000
	v_lshl_add_u64 v[222:223], s[48:49], 0, v[146:147]
	s_add_u32 s48, s48, s56
	s_addc_u32 s49, s49, s57
	s_add_i32 s47, s47, s31
	global_load_lds_dwordx4 v[222:223], off
	v_lshl_add_u64 v[224:225], s[48:49], 0, v[150:151]
	s_mov_b32 m0, s47
	v_lshl_add_u64 v[226:227], s[48:49], 0, v[146:147]
	global_load_lds_dwordx4 v[224:225], off
	s_add_i32 m0, s47, 0x2000
	v_lshl_add_u64 v[228:229], s[42:43], 0, v[152:153]
	global_load_lds_dwordx4 v[226:227], off
	v_lshl_add_u64 v[230:231], s[42:43], 0, v[148:149]
	s_waitcnt vmcnt(6)
	s_waitcnt lgkmcnt(0)
	s_setprio 1
	s_waitcnt lgkmcnt(0)
	v_mfma_f32_16x16x32_bf16 v[62:65], v[130:133], v[174:177], v[62:65]
	v_mfma_f32_16x16x32_bf16 v[58:61], v[138:141], v[174:177], v[58:61]
	v_mfma_f32_16x16x32_bf16 v[46:49], v[130:133], v[186:189], v[46:49]
	v_mfma_f32_16x16x32_bf16 v[42:45], v[138:141], v[186:189], v[42:45]
	v_mfma_f32_16x16x32_bf16 v[30:33], v[130:133], v[204:207], v[30:33]
	v_mfma_f32_16x16x32_bf16 v[26:29], v[138:141], v[204:207], v[26:29]
	v_mfma_f32_16x16x32_bf16 v[14:17], v[130:133], v[212:215], v[14:17]
	v_mfma_f32_16x16x32_bf16 v[10:13], v[138:141], v[212:215], v[10:13]
	v_mfma_f32_16x16x32_bf16 v[62:65], v[134:137], v[182:185], v[62:65]
	v_mfma_f32_16x16x32_bf16 v[58:61], v[142:145], v[182:185], v[58:61]
	v_mfma_f32_16x16x32_bf16 v[46:49], v[134:137], v[200:203], v[46:49]
	v_mfma_f32_16x16x32_bf16 v[42:45], v[142:145], v[200:203], v[42:45]
	v_mfma_f32_16x16x32_bf16 v[30:33], v[134:137], v[208:211], v[30:33]
	v_mfma_f32_16x16x32_bf16 v[26:29], v[142:145], v[208:211], v[26:29]
	v_mfma_f32_16x16x32_bf16 v[14:17], v[134:137], v[216:219], v[14:17]
	v_mfma_f32_16x16x32_bf16 v[10:13], v[142:145], v[216:219], v[10:13]
	s_setprio 0
	s_setprio 1
	v_mfma_f32_16x16x32_bf16 v[54:57], v[158:161], v[174:177], v[54:57]
	v_mfma_f32_16x16x32_bf16 v[50:53], v[166:169], v[174:177], v[50:53]
	v_mfma_f32_16x16x32_bf16 v[38:41], v[158:161], v[186:189], v[38:41]
	v_mfma_f32_16x16x32_bf16 v[34:37], v[166:169], v[186:189], v[34:37]
	v_mfma_f32_16x16x32_bf16 v[22:25], v[158:161], v[204:207], v[22:25]
	v_mfma_f32_16x16x32_bf16 v[18:21], v[166:169], v[204:207], v[18:21]
	v_mfma_f32_16x16x32_bf16 v[6:9], v[158:161], v[212:215], v[6:9]
	v_mfma_f32_16x16x32_bf16 v[2:5], v[166:169], v[212:215], v[2:5]
	v_mfma_f32_16x16x32_bf16 v[54:57], v[162:165], v[182:185], v[54:57]
	v_mfma_f32_16x16x32_bf16 v[50:53], v[170:173], v[182:185], v[50:53]
	v_mfma_f32_16x16x32_bf16 v[38:41], v[162:165], v[200:203], v[38:41]
	v_mfma_f32_16x16x32_bf16 v[34:37], v[170:173], v[200:203], v[34:37]
	v_mfma_f32_16x16x32_bf16 v[22:25], v[162:165], v[208:211], v[22:25]
	v_mfma_f32_16x16x32_bf16 v[18:21], v[170:173], v[208:211], v[18:21]
	v_mfma_f32_16x16x32_bf16 v[6:9], v[162:165], v[216:219], v[6:9]
	v_mfma_f32_16x16x32_bf16 v[2:5], v[170:173], v[216:219], v[2:5]
	s_setprio 0
	s_barrier
	s_add_i32 s47, 0, 0x18000
	v_add_u32_e32 v0, s47, v180
	s_add_i32 s48, 0, 0x1c000
	ds_read_b128 v[130:133], v0
	ds_read_b128 v[134:137], v0 offset:1024
	ds_read_b128 v[138:141], v0 offset:2048
	ds_read_b128 v[142:145], v0 offset:3072
	v_add_u32_e32 v0, s48, v180
	ds_read_b128 v[158:161], v0
	ds_read_b128 v[162:165], v0 offset:1024
	ds_read_b128 v[166:169], v0 offset:2048
	ds_read_b128 v[170:173], v0 offset:3072
	s_add_u32 s42, s42, s54
	s_addc_u32 s43, s43, s55
	s_mov_b32 m0, s53
	v_lshl_add_u64 v[232:233], s[42:43], 0, v[152:153]
	s_nop 0
	global_load_lds_dwordx4 v[228:229], off
	s_mov_b32 m0, s4
	s_nop 0
	global_load_lds_dwordx4 v[230:231], off
	s_mov_b32 m0, s82
	s_nop 0
	global_load_lds_dwordx4 v[232:233], off
	v_lshl_add_u64 v[232:233], s[42:43], 0, v[148:149]
	s_mov_b32 m0, s83
	s_nop 0
	global_load_lds_dwordx4 v[232:233], off
	ds_read_b128 v[174:177], v181 offset:32768
	ds_read_b128 v[182:185], v181 offset:33792
	ds_read_b128 v[186:189], v181 offset:34816
	ds_read_b128 v[200:203], v181 offset:35840
	ds_read_b128 v[204:207], v181 offset:36864
	ds_read_b128 v[208:211], v181 offset:37888
	ds_read_b128 v[212:215], v181 offset:38912
	ds_read_b128 v[216:219], v181 offset:39936
	s_waitcnt vmcnt(8)
	s_waitcnt lgkmcnt(0)
	s_setprio 1
	s_waitcnt lgkmcnt(0)
	v_mfma_f32_16x16x32_bf16 v[126:129], v[130:133], v[174:177], v[126:129]
	v_mfma_f32_16x16x32_bf16 v[122:125], v[138:141], v[174:177], v[122:125]
	v_mfma_f32_16x16x32_bf16 v[110:113], v[130:133], v[186:189], v[110:113]
	v_mfma_f32_16x16x32_bf16 v[106:109], v[138:141], v[186:189], v[106:109]
	v_mfma_f32_16x16x32_bf16 v[94:97], v[130:133], v[204:207], v[94:97]
	v_mfma_f32_16x16x32_bf16 v[90:93], v[138:141], v[204:207], v[90:93]
	v_mfma_f32_16x16x32_bf16 v[78:81], v[130:133], v[212:215], v[78:81]
	v_mfma_f32_16x16x32_bf16 v[74:77], v[138:141], v[212:215], v[74:77]
	v_mfma_f32_16x16x32_bf16 v[126:129], v[134:137], v[182:185], v[126:129]
	v_mfma_f32_16x16x32_bf16 v[122:125], v[142:145], v[182:185], v[122:125]
	v_mfma_f32_16x16x32_bf16 v[110:113], v[134:137], v[200:203], v[110:113]
	v_mfma_f32_16x16x32_bf16 v[106:109], v[142:145], v[200:203], v[106:109]
	v_mfma_f32_16x16x32_bf16 v[94:97], v[134:137], v[208:211], v[94:97]
	v_mfma_f32_16x16x32_bf16 v[90:93], v[142:145], v[208:211], v[90:93]
	v_mfma_f32_16x16x32_bf16 v[78:81], v[134:137], v[216:219], v[78:81]
	v_mfma_f32_16x16x32_bf16 v[74:77], v[142:145], v[216:219], v[74:77]
	s_setprio 0
	s_setprio 1
	v_mfma_f32_16x16x32_bf16 v[118:121], v[158:161], v[174:177], v[118:121]
	v_mfma_f32_16x16x32_bf16 v[114:117], v[166:169], v[174:177], v[114:117]
	v_mfma_f32_16x16x32_bf16 v[102:105], v[158:161], v[186:189], v[102:105]
	v_mfma_f32_16x16x32_bf16 v[98:101], v[166:169], v[186:189], v[98:101]
	v_mfma_f32_16x16x32_bf16 v[86:89], v[158:161], v[204:207], v[86:89]
	v_mfma_f32_16x16x32_bf16 v[82:85], v[166:169], v[204:207], v[82:85]
	v_mfma_f32_16x16x32_bf16 v[70:73], v[158:161], v[212:215], v[70:73]
	v_mfma_f32_16x16x32_bf16 v[66:69], v[166:169], v[212:215], v[66:69]
	v_mfma_f32_16x16x32_bf16 v[118:121], v[162:165], v[182:185], v[118:121]
	v_mfma_f32_16x16x32_bf16 v[114:117], v[170:173], v[182:185], v[114:117]
	v_mfma_f32_16x16x32_bf16 v[102:105], v[162:165], v[200:203], v[102:105]
	v_mfma_f32_16x16x32_bf16 v[98:101], v[170:173], v[200:203], v[98:101]
	v_mfma_f32_16x16x32_bf16 v[86:89], v[162:165], v[208:211], v[86:89]
	v_mfma_f32_16x16x32_bf16 v[82:85], v[170:173], v[208:211], v[82:85]
	v_mfma_f32_16x16x32_bf16 v[70:73], v[162:165], v[216:219], v[70:73]
	v_mfma_f32_16x16x32_bf16 v[66:69], v[170:173], v[216:219], v[66:69]
	s_setprio 0
	s_barrier
	s_add_i32 s42, s47, s31
	v_lshl_add_u64 v[220:221], v[220:221], 0, s[24:25]
	s_mov_b32 m0, s42
	ds_read_b128 v[174:177], v181 offset:49152
	ds_read_b128 v[182:185], v181 offset:50176
	ds_read_b128 v[186:189], v181 offset:51200
	ds_read_b128 v[200:203], v181 offset:52224
	ds_read_b128 v[204:207], v181 offset:53248
	ds_read_b128 v[208:211], v181 offset:54272
	ds_read_b128 v[212:215], v181 offset:55296
	ds_read_b128 v[216:219], v181 offset:56320
	global_load_lds_dwordx4 v[220:221], off
	v_lshl_add_u64 v[220:221], v[222:223], 0, s[24:25]
	s_add_i32 m0, s42, 0x2000
	s_add_i32 s42, s48, s31
	global_load_lds_dwordx4 v[220:221], off
	v_lshl_add_u64 v[220:221], v[224:225], 0, s[24:25]
	s_mov_b32 m0, s42
	s_nop 0
	global_load_lds_dwordx4 v[220:221], off
	v_lshl_add_u64 v[220:221], v[226:227], 0, s[24:25]
	s_add_i32 m0, s42, 0x2000
	s_nop 0
	global_load_lds_dwordx4 v[220:221], off
	s_waitcnt vmcnt(6)
	s_waitcnt lgkmcnt(0)
	s_setprio 1
	s_waitcnt lgkmcnt(0)
	v_mfma_f32_16x16x32_bf16 v[62:65], v[130:133], v[174:177], v[62:65]
	v_mfma_f32_16x16x32_bf16 v[58:61], v[138:141], v[174:177], v[58:61]
	v_mfma_f32_16x16x32_bf16 v[46:49], v[130:133], v[186:189], v[46:49]
	v_mfma_f32_16x16x32_bf16 v[42:45], v[138:141], v[186:189], v[42:45]
	v_mfma_f32_16x16x32_bf16 v[30:33], v[130:133], v[204:207], v[30:33]
	v_mfma_f32_16x16x32_bf16 v[26:29], v[138:141], v[204:207], v[26:29]
	v_mfma_f32_16x16x32_bf16 v[14:17], v[130:133], v[212:215], v[14:17]
	v_mfma_f32_16x16x32_bf16 v[10:13], v[138:141], v[212:215], v[10:13]
	v_mfma_f32_16x16x32_bf16 v[62:65], v[134:137], v[182:185], v[62:65]
	v_mfma_f32_16x16x32_bf16 v[58:61], v[142:145], v[182:185], v[58:61]
	v_mfma_f32_16x16x32_bf16 v[46:49], v[134:137], v[200:203], v[46:49]
	v_mfma_f32_16x16x32_bf16 v[42:45], v[142:145], v[200:203], v[42:45]
	v_mfma_f32_16x16x32_bf16 v[30:33], v[134:137], v[208:211], v[30:33]
	v_mfma_f32_16x16x32_bf16 v[26:29], v[142:145], v[208:211], v[26:29]
	v_mfma_f32_16x16x32_bf16 v[14:17], v[134:137], v[216:219], v[14:17]
	v_mfma_f32_16x16x32_bf16 v[10:13], v[142:145], v[216:219], v[10:13]
	s_setprio 0
	s_setprio 1
	v_mfma_f32_16x16x32_bf16 v[54:57], v[158:161], v[174:177], v[54:57]
	v_mfma_f32_16x16x32_bf16 v[50:53], v[166:169], v[174:177], v[50:53]
	v_mfma_f32_16x16x32_bf16 v[38:41], v[158:161], v[186:189], v[38:41]
	v_mfma_f32_16x16x32_bf16 v[34:37], v[166:169], v[186:189], v[34:37]
	v_mfma_f32_16x16x32_bf16 v[22:25], v[158:161], v[204:207], v[22:25]
	v_mfma_f32_16x16x32_bf16 v[18:21], v[166:169], v[204:207], v[18:21]
	v_mfma_f32_16x16x32_bf16 v[6:9], v[158:161], v[212:215], v[6:9]
	v_mfma_f32_16x16x32_bf16 v[2:5], v[166:169], v[212:215], v[2:5]
	v_mfma_f32_16x16x32_bf16 v[54:57], v[162:165], v[182:185], v[54:57]
	v_mfma_f32_16x16x32_bf16 v[50:53], v[170:173], v[182:185], v[50:53]
	v_mfma_f32_16x16x32_bf16 v[38:41], v[162:165], v[200:203], v[38:41]
	v_mfma_f32_16x16x32_bf16 v[34:37], v[170:173], v[200:203], v[34:37]
	v_mfma_f32_16x16x32_bf16 v[22:25], v[162:165], v[208:211], v[22:25]
	v_mfma_f32_16x16x32_bf16 v[18:21], v[170:173], v[208:211], v[18:21]
	v_mfma_f32_16x16x32_bf16 v[6:9], v[162:165], v[216:219], v[6:9]
	v_mfma_f32_16x16x32_bf16 v[2:5], v[170:173], v[216:219], v[2:5]
	s_setprio 0
	s_barrier
	s_add_u32 s40, s40, 0x100
	s_addc_u32 s41, s41, 0
	s_add_u32 s44, s44, 0x100
	s_addc_u32 s45, s45, 0
	s_cmp_ge_i32 s46, s74
	s_mov_b32 s42, s46
	s_cbranch_scc0 .Lmy_q467
.Lmy_post467:
.LBB0_468:
	s_and_b64 vcc, exec, s[38:39]
	s_cbranch_vccz .LBB0_470
	s_nop 0

.LBB0_631:
	s_andn2_b64 vcc, exec, s[34:35]
	s_mov_b64 s[28:29], -1
	s_cbranch_vccnz .LBB0_464
	s_andn2_b64 vcc, exec, s[60:61]
	s_cbranch_vccnz .LBB0_463
	s_nop 0
	s_branch .LBB0_463
